# P2a solve rounds specialised per 16-column block (skip structural-zero row groups and rounds), backward waves take blocks in reverse order
# speedup vs baseline: 1.0084x; 1.0003x over previous
; #define LAS __attribute__((address_space(3)))
; __device__ __forceinline__ void gdn_prep_phase(LAS unsigned char* lds, const GdnPrepArgs& A, int bid, int G, const unsigned char* zero_page) {
;     ...
;     if (!(pflg & 16)) {
;         const int dir = w >> 2, li = (w & 3) * 64 + lane, j = li >> 2, q = li & 3;
;         const LAS float* LP = (const LAS float*)(lds + (dir ? L_LPB : L_LPF)) + q * 16;
;         float t[16];
; #pragma unroll
;         for (int a = 0; a < 16; ++a) t[a] = 0.f;
;         f32x4 lq[3][4];
;     ...
;         SOLVE_LD(0); SOLVE_LD(1);
; #pragma unroll
;         for (int i = 0; i < 64; ++i) {
;             if (i + 2 < 48) SOLVE_LD(i + 2);
;             else if (i + 1 >= 48 && i + 1 < 64) SOLVE_LD(i + 1);
;             float p0 = 0.f, p1 = 0.f;
; #pragma unroll
;             for (int a4 = 0; a4 < (i + 15) / 16; ++a4) { const f32x4 lv = lq[i % 3][a4];
;                 p0 = __builtin_fmaf(lv.x, t[4 * a4], p0); p1 = __builtin_fmaf(lv.y, t[4 * a4 + 1], p1); p0 = __builtin_fmaf(lv.z, t[4 * a4 + 2], p0); p1 = __builtin_fmaf(lv.w, t[4 * a4 + 3], p1); }
;             float p = quad_sum(p0 + p1);
;             const float ti = (i == j ? 1.f : 0.f) - p;
;             if (q == (i & 3)) t[i >> 2] = ti;
;             if ((i & 7) == 3 && !(pflg & 64)) {
;                 constexpr int kk = 0; const int k8 = i >> 3, b = w + 8 * (k8 & 1); v4u f; int off; (void)kk;
;                 if (k8 < 2)      { f = frag16_rm(lds + L_KN, QS_, b >> 2, b & 3, lane); off = B_KA + b * 1024; }
;                 else if (k8 < 4) { f = frag16_rm(lds + L_QN, QS_, b >> 2, b & 3, lane); off = B_QA + b * 1024; }
;                 else if (k8 < 6) { f = frag16_tr(lds + L_KN, QS_, b >> 1, b & 1, lane); off = B_KT + b * 1024; }
;                 else             { f = frag16_rm(lds + (k8 == 6 ? L_AF : L_AB), AS_, w >> 1, w & 1, lane); off = (k8 == 6 ? B_AF : B_AB) + w * 1024; }
;                 *(v4u*)(blob + off + lane * 16) = f; }
;             __builtin_amdgcn_sched_barrier(0);
;         }
;     ...
;         const LAS float* sc = (const LAS float*)(lds + L_SC);
;         if (dir == 0) { const float bj = sc[128 + j];
; #pragma unroll
;             for (int a = 0; a < 16; ++a) *(LAS unsigned short*)(lds + L_TBF + (4 * a + q) * AS_ + j * 2) = (unsigned short)(pkbf(t[a] * bj, 0.f) & 0xffffu);
;         } else { const int jo = 63 - j; const float bj = sc[192 + jo];
; #pragma unroll
.LBB0_197:
	s_and_b64 vcc, exec, s[2:3]
	s_cbranch_vccnz .LBB0_362
	s_lshl_b32 s67, s34, 4
	v_writelane_b32 v254, s42, 55
	s_lshl_b32 s3, s34, 3
	s_ashr_i32 s2, s67, 31
	v_writelane_b32 v254, s43, 56
	s_cmp_lt_i32 s34, 51
	v_writelane_b32 v254, s2, 57
	s_cselect_b64 s[4:5], -1, 0
	s_ashr_i32 s2, s38, 7
	s_bfe_u32 s6, s38, 0x10006
	v_writelane_b32 v254, s4, 59
	s_cmpk_gt_u32 s38, 0xff
	s_mov_b32 s7, 0x11000
	v_writelane_b32 v254, s5, 60
	s_cselect_b64 s[4:5], -1, 0
	s_cmpk_lt_u32 s38, 0x100
	s_mov_b32 s39, 0x15800
	s_cselect_b32 s7, s7, 0xcc00
	s_cselect_b32 s39, s39, 0x19800
	s_lshl_b32 s40, s2, 5
	v_and_b32_e32 v4, 31, v7
	s_add_i32 s7, s7, 0
	s_and_b32 s40, s40, 32
	v_or_b32_e32 v3, s40, v4
	v_mov_b32_e32 v6, s7
	s_movk_i32 s42, 0x110
	s_lshl_b32 s7, s6, 5
	v_lshrrev_b32_e32 v5, 5, v18
	v_mad_u32_u24 v11, v3, s42, v6
	v_or_b32_e32 v3, s7, v4
	v_lshlrev_b32_e32 v12, 4, v5
	v_lshl_or_b32 v15, v5, 2, s40
	v_lshlrev_b32_e32 v5, 1, v3
	s_add_i32 s40, 0, 0x1d800
	s_add_i32 s41, 0, 0x11000
	v_add_u32_e32 v8, s40, v5
	s_add_i32 s40, 0, 0x1fc00
	v_mov_b32_e32 v6, s41
	v_add_u32_e32 v9, s40, v5
	v_lshlrev_b32_e32 v5, 6, v7
	v_mad_u32_u24 v14, v3, s42, v6
	v_and_b32_e32 v5, 0xc0, v5
	s_add_i32 s40, 0, 0x15800
	v_bitop3_b32 v6, s7, 60, v4 bitop3:0xc8
	v_bitop3_b32 v4, s7, 63, v4 bitop3:0x36
	v_add3_u32 v13, s40, v5, v6
	v_lshlrev_b32_e32 v5, 4, v4
	v_lshrrev_b32_e32 v4, 2, v4
	v_and_b32_e32 v57, 15, v7
	v_and_or_b32 v16, v5, 48, v4
	v_lshl_or_b32 v4, s2, 4, v57
	s_movk_i32 s2, 0x90
	v_mul_lo_u32 v4, v4, s2
	s_lshl_b32 s2, s6, 6
	v_lshrrev_b32_e32 v6, 1, v7
	s_lshr_b32 s100, s38, 8
	s_and_b32 s38, s38, 0xc0
	s_mul_i32 s100, s100, 0xc0
	s_xor_b32 s100, s38, s100
	s_lshr_b32 s101, s100, 6
	s_nop 0
	v_and_b32_e32 v58, 24, v6
	s_add_i32 s2, s2, 0
	v_add3_u32 v33, s2, v4, v58
	v_lshrrev_b32_e32 v4, 2, v7
	s_add_i32 s6, s38, 0
	v_lshlrev_b32_e32 v2, 1, v18
	v_or_b32_e32 v17, s100, v18
	v_and_b32_e32 v59, 12, v4
	v_add_u32_e32 v62, s6, v58
	s_movk_i32 s6, 0x3fc
	v_readlane_b32 s42, v252, 62
	v_lshrrev_b32_e32 v32, 2, v17
	v_or_b32_e32 v4, s7, v59
	v_and_b32_e32 v60, 30, v2
	v_bitop3_b32 v2, v17, s6, v169 bitop3:0x6c
	v_mul_u32_u24_e32 v4, 0x110, v4
	v_add_u32_e32 v64, s42, v2
	v_lshlrev_b32_e32 v2, 1, v32
	v_add3_u32 v61, s41, v4, v60
	v_xor_b32_e32 v4, 0x7e, v2
	v_readlane_b32 s6, v252, 63
	s_or_b32 s52, s3, 7
	s_mulk_i32 s52, 0x300
	v_add_u32_e32 v34, s6, v4
	v_readlane_b32 s6, v254, 0
	s_or_b32 s53, s3, 1
	s_add_i32 s3, s52, 0xfffffd00
	v_add_u32_e32 v35, s6, v2
	v_cmp_gt_u32_e64 s[6:7], 2, v18
	v_and_b32_e32 v5, 3, v7
	s_add_i32 s39, s39, 0
	v_writelane_b32 v254, s6, 61
	v_and_b32_e32 v27, 64, v1
	v_lshl_add_u32 v56, v5, 6, s39
	v_writelane_b32 v254, s7, 62
	v_cmp_eq_u32_e64 s[6:7], 0, v18
	s_add_i32 s41, s41, s38
	v_bitop3_b32 v4, s38, v169, v18 bitop3:0xc8
	v_writelane_b32 v254, s6, 63
	v_xor_b32_e32 v21, 16, v1
	v_add_u32_e32 v27, 64, v27
	v_writelane_b32 v255, s7, 0
	v_writelane_b32 v255, s3, 1
	s_add_i32 s3, s52, 0xfffffa00
	v_writelane_b32 v255, s3, 3
	s_add_i32 s3, s52, 0xfffff700
	v_writelane_b32 v255, s3, 5
	s_add_i32 s3, s52, 0xfffff400
	v_writelane_b32 v255, s3, 7
	s_add_i32 s3, s52, 0xfffff100
	v_writelane_b32 v255, s3, 9
	s_add_i32 s3, s52, 0xffffee00
	v_writelane_b32 v255, s3, 11
	v_cmp_ge_u32_e64 s[38:39], v15, v3
	v_cmp_lt_i32_e32 vcc, v21, v27
	s_add_i32 s3, 0, 0x19800
	v_writelane_b32 v255, s38, 13
	v_cndmask_b32_e32 v21, v1, v21, vcc
	v_lshlrev_b32_e32 v69, 2, v21
	v_writelane_b32 v255, s39, 14
	v_cmp_gt_u32_e64 s[38:39], v15, v3
	v_xor_b32_e32 v21, 32, v1
	v_cmp_lt_i32_e32 vcc, v21, v27
	v_writelane_b32 v255, s38, 15
	v_lshlrev_b32_e32 v27, 6, v15
	v_add_u32_e32 v63, s41, v58
	v_writelane_b32 v255, s39, 16
	s_movk_i32 s38, 0xfc0
	v_bitop3_b32 v27, v16, s38, v27 bitop3:0x36
	v_lshl_add_u32 v73, v27, 2, s3
	v_or_b32_e32 v27, 1, v15
	v_lshl_add_u32 v74, v27, 2, s42
	v_cmp_lt_u32_e64 s[40:41], v27, v3
	v_lshlrev_b32_e32 v38, 8, v27
	v_lshlrev_b32_e32 v27, 6, v27
	v_cndmask_b32_e32 v21, v1, v21, vcc
	v_bitop3_b32 v27, v16, s38, v27 bitop3:0x36
	v_cmp_gt_u32_e32 vcc, 4, v17
	v_writelane_b32 v255, s40, 17
	v_lshl_add_u32 v75, v27, 2, s3
	v_or_b32_e32 v27, 2, v15
	v_cndmask_b32_e64 v104, 0, 1.0, vcc
	v_cmp_eq_u32_e32 vcc, 1, v32
	v_writelane_b32 v255, s41, 18
	v_cmp_lt_u32_e64 s[40:41], v27, v3
	v_cndmask_b32_e64 v105, 0, 1.0, vcc
	v_cmp_eq_u32_e32 vcc, 2, v32
	v_writelane_b32 v255, s40, 19
	v_lshl_add_u32 v76, v27, 2, s42
	v_cndmask_b32_e64 v106, 0, 1.0, vcc
	v_cmp_eq_u32_e32 vcc, 3, v32
	v_writelane_b32 v255, s41, 20
	v_cmp_gt_u32_e64 s[40:41], v27, v3
	v_lshlrev_b32_e32 v39, 8, v27
	v_lshlrev_b32_e32 v27, 6, v27
	v_cndmask_b32_e64 v107, 0, 1.0, vcc
	v_cmp_eq_u32_e32 vcc, 4, v32
	v_bitop3_b32 v27, v16, s38, v27 bitop3:0x36
	v_writelane_b32 v255, s40, 21
	v_cndmask_b32_e64 v109, 0, 1.0, vcc
	v_cmp_eq_u32_e32 vcc, 5, v32
	v_lshl_add_u32 v77, v27, 2, s3
	v_or_b32_e32 v27, 3, v15
	v_cndmask_b32_e64 v110, 0, 1.0, vcc
	v_cmp_eq_u32_e32 vcc, 6, v32
	v_writelane_b32 v255, s41, 22
	v_cmp_lt_u32_e64 s[40:41], v27, v3
	v_cndmask_b32_e64 v111, 0, 1.0, vcc
	v_cmp_eq_u32_e32 vcc, 7, v32
	v_writelane_b32 v255, s40, 23
	v_lshl_add_u32 v78, v27, 2, s42
	v_cndmask_b32_e64 v112, 0, 1.0, vcc
	v_cmp_eq_u32_e32 vcc, 8, v32
	v_writelane_b32 v255, s41, 24
	v_cmp_gt_u32_e64 s[40:41], v27, v3
	v_lshlrev_b32_e32 v40, 8, v27
	v_lshlrev_b32_e32 v27, 6, v27
	v_cndmask_b32_e64 v113, 0, 1.0, vcc
	v_cmp_eq_u32_e32 vcc, 9, v32
	v_bitop3_b32 v27, v16, s38, v27 bitop3:0x36
	v_writelane_b32 v255, s40, 25
	v_cndmask_b32_e64 v114, 0, 1.0, vcc
	v_cmp_eq_u32_e32 vcc, 10, v32
	v_lshl_add_u32 v79, v27, 2, s3
	v_or_b32_e32 v27, 8, v15
	v_cndmask_b32_e64 v115, 0, 1.0, vcc
; #define LAS __attribute__((address_space(3)))
; __device__ __forceinline__ void gdn_prep_phase(LAS unsigned char* lds, const GdnPrepArgs& A, int bid, int G, const unsigned char* zero_page) {
;     ...
;     if (!(pflg & 16)) {
;         const int dir = w >> 2, li = (w & 3) * 64 + lane, j = li >> 2, q = li & 3;
;         const LAS float* LP = (const LAS float*)(lds + (dir ? L_LPB : L_LPF)) + q * 16;
;         float t[16];
; #pragma unroll
;         for (int a = 0; a < 16; ++a) t[a] = 0.f;
;         f32x4 lq[3][4];
;     ...
;         SOLVE_LD(0); SOLVE_LD(1);
; #pragma unroll
;         for (int i = 0; i < 64; ++i) {
;             if (i + 2 < 48) SOLVE_LD(i + 2);
;             else if (i + 1 >= 48 && i + 1 < 64) SOLVE_LD(i + 1);
;             float p0 = 0.f, p1 = 0.f;
; #pragma unroll
;             for (int a4 = 0; a4 < (i + 15) / 16; ++a4) { const f32x4 lv = lq[i % 3][a4];
;                 p0 = __builtin_fmaf(lv.x, t[4 * a4], p0); p1 = __builtin_fmaf(lv.y, t[4 * a4 + 1], p1); p0 = __builtin_fmaf(lv.z, t[4 * a4 + 2], p0); p1 = __builtin_fmaf(lv.w, t[4 * a4 + 3], p1); }
;             float p = quad_sum(p0 + p1);
;             const float ti = (i == j ? 1.f : 0.f) - p;
;             if (q == (i & 3)) t[i >> 2] = ti;
;             if ((i & 7) == 3 && !(pflg & 64)) {
;                 constexpr int kk = 0; const int k8 = i >> 3, b = w + 8 * (k8 & 1); v4u f; int off; (void)kk;
;                 if (k8 < 2)      { f = frag16_rm(lds + L_KN, QS_, b >> 2, b & 3, lane); off = B_KA + b * 1024; }
;                 else if (k8 < 4) { f = frag16_rm(lds + L_QN, QS_, b >> 2, b & 3, lane); off = B_QA + b * 1024; }
;                 else if (k8 < 6) { f = frag16_tr(lds + L_KN, QS_, b >> 1, b & 1, lane); off = B_KT + b * 1024; }
;                 else             { f = frag16_rm(lds + (k8 == 6 ? L_AF : L_AB), AS_, w >> 1, w & 1, lane); off = (k8 == 6 ? B_AF : B_AB) + w * 1024; }
;                 *(v4u*)(blob + off + lane * 16) = f; }
;             __builtin_amdgcn_sched_barrier(0);
;         }
;     ...
;         const LAS float* sc = (const LAS float*)(lds + L_SC);
;         if (dir == 0) { const float bj = sc[128 + j];
; #pragma unroll
;             for (int a = 0; a < 16; ++a) *(LAS unsigned short*)(lds + L_TBF + (4 * a + q) * AS_ + j * 2) = (unsigned short)(pkbf(t[a] * bj, 0.f) & 0xffffu);
;         } else { const int jo = 63 - j; const float bj = sc[192 + jo];
; #pragma unroll
	v_cmp_eq_u32_e32 vcc, 11, v32
	v_writelane_b32 v255, s41, 26
	v_cmp_lt_u32_e64 s[40:41], v27, v3
	v_cndmask_b32_e64 v116, 0, 1.0, vcc
	v_cmp_eq_u32_e32 vcc, 12, v32
	v_writelane_b32 v255, s40, 27
	v_lshl_add_u32 v80, v27, 2, s42
	v_cndmask_b32_e64 v118, 0, 1.0, vcc
	v_cmp_eq_u32_e32 vcc, 13, v32
	v_writelane_b32 v255, s41, 28
	v_cmp_gt_u32_e64 s[40:41], v27, v3
	v_lshlrev_b32_e32 v41, 8, v27
	v_lshlrev_b32_e32 v27, 6, v27
	v_cndmask_b32_e64 v119, 0, 1.0, vcc
	v_cmp_eq_u32_e32 vcc, 14, v32
	v_bitop3_b32 v27, v16, s38, v27 bitop3:0x36
	v_writelane_b32 v255, s40, 29
	v_cndmask_b32_e64 v120, 0, 1.0, vcc
	v_cmp_eq_u32_e32 vcc, 15, v32
	v_lshl_add_u32 v81, v27, 2, s3
	v_or_b32_e32 v27, 9, v15
	v_cndmask_b32_e64 v121, 0, 1.0, vcc
	v_cmp_eq_u32_e32 vcc, 16, v32
	v_writelane_b32 v255, s41, 30
	v_cmp_lt_u32_e64 s[40:41], v27, v3
	v_cndmask_b32_e64 v122, 0, 1.0, vcc
	v_cmp_eq_u32_e32 vcc, 17, v32
	v_writelane_b32 v255, s40, 31
	v_lshl_add_u32 v82, v27, 2, s42
	v_cndmask_b32_e64 v123, 0, 1.0, vcc
	v_cmp_eq_u32_e32 vcc, 18, v32
	v_writelane_b32 v255, s41, 32
	v_cmp_gt_u32_e64 s[40:41], v27, v3
	v_lshlrev_b32_e32 v42, 8, v27
	v_lshlrev_b32_e32 v27, 6, v27
	v_cndmask_b32_e64 v124, 0, 1.0, vcc
	v_cmp_eq_u32_e32 vcc, 19, v32
	v_bitop3_b32 v27, v16, s38, v27 bitop3:0x36
	v_writelane_b32 v255, s40, 33
	v_cndmask_b32_e64 v125, 0, 1.0, vcc
	v_cmp_eq_u32_e32 vcc, 20, v32
	v_lshl_add_u32 v83, v27, 2, s3
	v_or_b32_e32 v27, 10, v15
	v_cndmask_b32_e64 v126, 0, 1.0, vcc
	v_cmp_eq_u32_e32 vcc, 21, v32
	v_writelane_b32 v255, s41, 34
	v_cmp_lt_u32_e64 s[40:41], v27, v3
	v_cndmask_b32_e64 v127, 0, 1.0, vcc
	v_cmp_eq_u32_e32 vcc, 22, v32
	v_writelane_b32 v255, s40, 35
	v_lshl_add_u32 v84, v27, 2, s42
	v_cndmask_b32_e64 v128, 0, 1.0, vcc
	v_cmp_eq_u32_e32 vcc, 23, v32
	v_writelane_b32 v255, s41, 36
	v_cmp_gt_u32_e64 s[40:41], v27, v3
	v_lshlrev_b32_e32 v43, 8, v27
	v_lshlrev_b32_e32 v27, 6, v27
	v_cndmask_b32_e64 v129, 0, 1.0, vcc
	v_cmp_eq_u32_e32 vcc, 24, v32
	v_bitop3_b32 v27, v16, s38, v27 bitop3:0x36
	v_writelane_b32 v255, s40, 37
	v_cndmask_b32_e64 v136, 0, 1.0, vcc
	v_cmp_eq_u32_e32 vcc, 25, v32
	v_lshl_add_u32 v85, v27, 2, s3
	v_or_b32_e32 v27, 11, v15
	v_cndmask_b32_e64 v137, 0, 1.0, vcc
	v_cmp_eq_u32_e32 vcc, 26, v32
	v_writelane_b32 v255, s41, 38
	v_cmp_lt_u32_e64 s[40:41], v27, v3
	v_cndmask_b32_e64 v138, 0, 1.0, vcc
	v_cmp_eq_u32_e32 vcc, 27, v32
	v_writelane_b32 v255, s40, 39
	v_lshl_add_u32 v86, v27, 2, s42
	v_cndmask_b32_e64 v139, 0, 1.0, vcc
	v_cmp_eq_u32_e32 vcc, 28, v32
	v_writelane_b32 v255, s41, 40
	v_cmp_gt_u32_e64 s[40:41], v27, v3
	v_lshlrev_b32_e32 v44, 8, v27
	v_lshlrev_b32_e32 v27, 6, v27
	v_cndmask_b32_e64 v140, 0, 1.0, vcc
	v_cmp_eq_u32_e32 vcc, 29, v32
	v_bitop3_b32 v27, v16, s38, v27 bitop3:0x36
	v_writelane_b32 v255, s40, 41
	v_cndmask_b32_e64 v141, 0, 1.0, vcc
	v_cmp_eq_u32_e32 vcc, 30, v32
	v_lshl_add_u32 v87, v27, 2, s3
	v_or_b32_e32 v27, 16, v15
	v_cndmask_b32_e64 v142, 0, 1.0, vcc
	v_cmp_eq_u32_e32 vcc, 31, v32
	v_writelane_b32 v255, s41, 42
	v_cmp_lt_u32_e64 s[40:41], v27, v3
	v_cndmask_b32_e64 v143, 0, 1.0, vcc
	v_cmp_eq_u32_e32 vcc, 32, v32
	v_writelane_b32 v255, s40, 43
	v_lshl_add_u32 v88, v27, 2, s42
	v_cndmask_b32_e64 v144, 0, 1.0, vcc
	v_cmp_eq_u32_e32 vcc, 33, v32
	v_writelane_b32 v255, s41, 44
	v_cmp_gt_u32_e64 s[40:41], v27, v3
	v_lshlrev_b32_e32 v45, 8, v27
	v_lshlrev_b32_e32 v27, 6, v27
	v_cndmask_b32_e64 v145, 0, 1.0, vcc
	v_cmp_eq_u32_e32 vcc, 34, v32
	v_bitop3_b32 v27, v16, s38, v27 bitop3:0x36
	v_or_b32_e32 v46, 17, v15
	v_cndmask_b32_e64 v146, 0, 1.0, vcc
	v_cmp_eq_u32_e32 vcc, 35, v32
	v_lshl_add_u32 v89, v27, 2, s3
	v_lshlrev_b32_e32 v27, 6, v46
	v_cndmask_b32_e64 v147, 0, 1.0, vcc
	v_cmp_eq_u32_e32 vcc, 36, v32
	v_bitop3_b32 v27, v16, s38, v27 bitop3:0x36
	v_or_b32_e32 v48, 18, v15
	v_cndmask_b32_e64 v148, 0, 1.0, vcc
	v_cmp_eq_u32_e32 vcc, 37, v32
	v_lshl_add_u32 v91, v27, 2, s3
	v_lshlrev_b32_e32 v27, 6, v48
	v_cndmask_b32_e64 v149, 0, 1.0, vcc
	v_cmp_eq_u32_e32 vcc, 38, v32
	v_bitop3_b32 v27, v16, s38, v27 bitop3:0x36
	v_or_b32_e32 v230, 19, v15
	v_cndmask_b32_e64 v150, 0, 1.0, vcc
	v_cmp_eq_u32_e32 vcc, 39, v32
	v_lshl_add_u32 v93, v27, 2, s3
	v_lshlrev_b32_e32 v27, 6, v230
	v_cndmask_b32_e64 v151, 0, 1.0, vcc
	v_cmp_eq_u32_e32 vcc, 40, v32
	v_bitop3_b32 v27, v16, s38, v27 bitop3:0x36
	v_or_b32_e32 v231, 24, v15
	v_cndmask_b32_e64 v152, 0, 1.0, vcc
	v_cmp_eq_u32_e32 vcc, 41, v32
	v_lshl_add_u32 v95, v27, 2, s3
	v_lshlrev_b32_e32 v27, 6, v231
	v_cndmask_b32_e64 v153, 0, 1.0, vcc
	v_cmp_eq_u32_e32 vcc, 42, v32
	v_bitop3_b32 v27, v16, s38, v27 bitop3:0x36
	v_or_b32_e32 v232, 25, v15
	v_cndmask_b32_e64 v154, 0, 1.0, vcc
	v_cmp_eq_u32_e32 vcc, 43, v32
	v_lshl_add_u32 v97, v27, 2, s3
	v_lshlrev_b32_e32 v27, 6, v232
	v_cndmask_b32_e64 v155, 0, 1.0, vcc
	v_cmp_eq_u32_e32 vcc, 44, v32
	v_bitop3_b32 v27, v16, s38, v27 bitop3:0x36
	v_or_b32_e32 v233, 26, v15
	v_cndmask_b32_e64 v156, 0, 1.0, vcc
	v_cmp_eq_u32_e32 vcc, 45, v32
	v_lshl_add_u32 v99, v27, 2, s3
	v_lshlrev_b32_e32 v27, 6, v233
	v_cndmask_b32_e64 v157, 0, 1.0, vcc
	v_cmp_eq_u32_e32 vcc, 46, v32
	v_lshl_add_u32 v72, v15, 2, s42
	v_cmp_lt_u32_e64 s[6:7], v15, v3
	v_mul_u32_u24_e32 v36, 0x90, v15
	v_lshlrev_b32_e32 v37, 8, v15
	v_bitop3_b32 v27, v16, s38, v27 bitop3:0x36
	v_or_b32_e32 v15, 27, v15
	v_cndmask_b32_e64 v158, 0, 1.0, vcc
	v_cmp_eq_u32_e32 vcc, 47, v32
	v_lshl_add_u32 v101, v27, 2, s3
	v_lshlrev_b32_e32 v27, 6, v15
	v_cndmask_b32_e64 v159, 0, 1.0, vcc
	v_cmp_eq_u32_e32 vcc, 48, v32
	v_bitop3_b32 v26, v7, 63, 3 bitop3:0x6c
	v_bitop3_b32 v16, v16, s38, v27 bitop3:0x36
	v_cndmask_b32_e64 v160, 0, 1.0, vcc
	v_cmp_eq_u32_e32 vcc, 49, v32
; #define LAS __attribute__((address_space(3)))
; __device__ __forceinline__ void gdn_prep_phase(LAS unsigned char* lds, const GdnPrepArgs& A, int bid, int G, const unsigned char* zero_page) {
;     ...
;     if (!(pflg & 16)) {
;         const int dir = w >> 2, li = (w & 3) * 64 + lane, j = li >> 2, q = li & 3;
;         const LAS float* LP = (const LAS float*)(lds + (dir ? L_LPB : L_LPF)) + q * 16;
;         float t[16];
; #pragma unroll
;         for (int a = 0; a < 16; ++a) t[a] = 0.f;
;         f32x4 lq[3][4];
;     ...
;         SOLVE_LD(0); SOLVE_LD(1);
; #pragma unroll
;         for (int i = 0; i < 64; ++i) {
;             if (i + 2 < 48) SOLVE_LD(i + 2);
;             else if (i + 1 >= 48 && i + 1 < 64) SOLVE_LD(i + 1);
;             float p0 = 0.f, p1 = 0.f;
; #pragma unroll
;             for (int a4 = 0; a4 < (i + 15) / 16; ++a4) { const f32x4 lv = lq[i % 3][a4];
;                 p0 = __builtin_fmaf(lv.x, t[4 * a4], p0); p1 = __builtin_fmaf(lv.y, t[4 * a4 + 1], p1); p0 = __builtin_fmaf(lv.z, t[4 * a4 + 2], p0); p1 = __builtin_fmaf(lv.w, t[4 * a4 + 3], p1); }
;             float p = quad_sum(p0 + p1);
;             const float ti = (i == j ? 1.f : 0.f) - p;
;             if (q == (i & 3)) t[i >> 2] = ti;
;             if ((i & 7) == 3 && !(pflg & 64)) {
;                 constexpr int kk = 0; const int k8 = i >> 3, b = w + 8 * (k8 & 1); v4u f; int off; (void)kk;
;                 if (k8 < 2)      { f = frag16_rm(lds + L_KN, QS_, b >> 2, b & 3, lane); off = B_KA + b * 1024; }
;                 else if (k8 < 4) { f = frag16_rm(lds + L_QN, QS_, b >> 2, b & 3, lane); off = B_QA + b * 1024; }
;                 else if (k8 < 6) { f = frag16_tr(lds + L_KN, QS_, b >> 1, b & 1, lane); off = B_KT + b * 1024; }
;                 else             { f = frag16_rm(lds + (k8 == 6 ? L_AF : L_AB), AS_, w >> 1, w & 1, lane); off = (k8 == 6 ? B_AF : B_AB) + w * 1024; }
;                 *(v4u*)(blob + off + lane * 16) = f; }
;             __builtin_amdgcn_sched_barrier(0);
;         }
;     ...
;         const LAS float* sc = (const LAS float*)(lds + L_SC);
;         if (dir == 0) { const float bj = sc[128 + j];
; #pragma unroll
;             for (int a = 0; a < 16; ++a) *(LAS unsigned short*)(lds + L_TBF + (4 * a + q) * AS_ + j * 2) = (unsigned short)(pkbf(t[a] * bj, 0.f) & 0xffffu);
;         } else { const int jo = 63 - j; const float bj = sc[192 + jo];
; #pragma unroll
	v_lshl_add_u32 v103, v16, 2, s3
	v_mul_u32_u24_e32 v16, 0x90, v26
	v_bitop3_b32 v26, v7, 55, 3 bitop3:0x6c
	v_cndmask_b32_e64 v161, 0, 1.0, vcc
	v_cmp_eq_u32_e32 vcc, 50, v32
	v_mul_u32_u24_e32 v210, 0x90, v26
	v_bitop3_b32 v26, v7, 51, 3 bitop3:0x6c
	v_cndmask_b32_e64 v162, 0, 1.0, vcc
	v_cmp_eq_u32_e32 vcc, 51, v32
	v_mul_u32_u24_e32 v211, 0x90, v26
	v_bitop3_b32 v26, v7, 47, 3 bitop3:0x6c
	v_cndmask_b32_e64 v163, 0, 1.0, vcc
	v_cmp_eq_u32_e32 vcc, 52, v32
	v_mul_u32_u24_e32 v212, 0x90, v26
	v_bitop3_b32 v26, v7, 43, 3 bitop3:0x6c
	v_readlane_b32 s38, v251, 39
	v_cndmask_b32_e64 v173, 0, 1.0, vcc
	v_cmp_eq_u32_e32 vcc, 53, v32
	v_add_u32_e32 v54, 0, v130
	v_mul_u32_u24_e32 v213, 0x90, v26
	v_bitop3_b32 v26, v7, 39, 3 bitop3:0x6c
	v_lshlrev_b32_e32 v130, 3, v18
	v_readlane_b32 s39, v251, 40
	v_cndmask_b32_e64 v174, 0, 1.0, vcc
	v_cmp_eq_u32_e32 vcc, 54, v32
	v_writelane_b32 v255, s40, 45
	v_mul_u32_u24_e32 v214, 0x90, v26
	v_bitop3_b32 v26, v7, 35, 3 bitop3:0x6c
	v_lshl_add_u64 v[28:29], s[38:39], 0, v[130:131]
	v_readlane_b32 s38, v251, 41
	v_cndmask_b32_e64 v175, 0, 1.0, vcc
	v_cmp_eq_u32_e32 vcc, 55, v32
	v_writelane_b32 v255, s41, 46
	v_mul_u32_u24_e32 v215, 0x90, v26
	v_bitop3_b32 v26, v7, 31, 3 bitop3:0x6c
	v_readlane_b32 s39, v251, 42
	s_add_i32 s41, s34, 8
	v_cndmask_b32_e64 v176, 0, 1.0, vcc
	v_cmp_eq_u32_e32 vcc, 56, v32
	v_mul_u32_u24_e32 v216, 0x90, v26
	v_bitop3_b32 v26, v7, 27, 3 bitop3:0x6c
	v_lshl_add_u64 v[30:31], s[38:39], 0, v[130:131]
	s_lshl_b32 s38, s41, 2
	v_cndmask_b32_e64 v177, 0, 1.0, vcc
	v_cmp_eq_u32_e32 vcc, 57, v32
	v_mul_u32_u24_e32 v217, 0x90, v26
	v_bitop3_b32 v26, v7, 23, 3 bitop3:0x6c
	v_readlane_b32 s68, v250, 10
	s_and_b32 s38, s38, 0xffffff0
	v_cndmask_b32_e64 v178, 0, 1.0, vcc
	v_cmp_eq_u32_e32 vcc, 58, v32
	v_mul_u32_u24_e32 v218, 0x90, v26
	v_bitop3_b32 v26, v7, 19, 3 bitop3:0x6c
	v_readlane_b32 s72, v250, 14
	s_lshl_b32 s40, s34, 2
	v_or_b32_e32 v117, s38, v57
	s_lshl_b32 s38, s41, 10
	v_cndmask_b32_e64 v179, 0, 1.0, vcc
	v_cmp_eq_u32_e32 vcc, 59, v32
	s_lshl_b32 s41, s41, 4
	s_lshl_b32 s2, s34, 10
	v_mul_u32_u24_e32 v219, 0x90, v26
	v_bitop3_b32 v26, v7, 15, 3 bitop3:0x6c
	s_and_b32 s3, s40, 0xffffff0
	v_cndmask_b32_e64 v180, 0, 1.0, vcc
	v_cmp_eq_u32_e32 vcc, 60, v32
	s_and_b32 s72, s41, 0xffffffe0
	s_add_i32 s41, s34, -8
	v_mul_u32_u24_e32 v220, 0x90, v26
	v_bitop3_b32 v26, v7, 11, 3 bitop3:0x6c
	v_or_b32_e32 v108, s3, v57
	s_ashr_i32 s3, s2, 31
	v_cndmask_b32_e64 v181, 0, 1.0, vcc
	v_cmp_eq_u32_e32 vcc, 61, v32
	v_writelane_b32 v255, s41, 47
	v_lshrrev_b32_e32 v10, 4, v18
	v_bitop3_b32 v17, v7, 59, 3 bitop3:0x6c
	v_mul_u32_u24_e32 v221, 0x90, v26
	v_bitop3_b32 v26, v7, 7, 3 bitop3:0x6c
	v_bitop3_b32 v7, v7, 3, v7 bitop3:0xc
	v_readlane_b32 s70, v250, 12
	v_cndmask_b32_e64 v182, 0, 1.0, vcc
	v_cmp_eq_u32_e32 vcc, 62, v32
	v_writelane_b32 v255, s2, 48
	v_lshlrev_b32_e32 v22, 4, v18
	v_add_u32_e32 v65, s42, v4
	v_or_b32_e32 v2, 64, v18
	v_or_b32_e32 v4, 0x80, v18
	v_or_b32_e32 v6, 0xc0, v18
	v_lshlrev_b32_e32 v47, 8, v46
	v_lshlrev_b32_e32 v49, 8, v48
	v_lshlrev_b32_e32 v203, 8, v230
	v_lshlrev_b32_e32 v204, 8, v231
	v_lshlrev_b32_e32 v205, 8, v232
	v_lshlrev_b32_e32 v206, 8, v233
	v_lshlrev_b32_e32 v207, 8, v15
	v_mul_u32_u24_e32 v17, 0x90, v17
	v_mul_u32_u24_e32 v222, 0x90, v26
	v_mul_u32_u24_e32 v7, 0x90, v7
	v_mul_u32_u24_e32 v224, 0x90, v5
	v_readlane_b32 s69, v250, 11
	v_readlane_b32 s71, v250, 13
	v_readlane_b32 s74, v250, 16
	v_readlane_b32 s75, v250, 17
	v_readlane_b32 s76, v250, 18
	v_readlane_b32 s77, v250, 19
	v_readlane_b32 s78, v250, 20
	v_readlane_b32 s79, v250, 21
	v_readlane_b32 s80, v250, 22
	v_readlane_b32 s81, v250, 23
	s_movk_i32 s70, 0x110
	v_cndmask_b32_e64 v183, 0, 1.0, vcc
	v_cmp_eq_u32_e32 vcc, 63, v32
	v_or_b32_e32 v189, s40, v10
	v_writelane_b32 v255, s3, 49
	s_add_i32 s40, s2, 0
	v_lshlrev_b32_e32 v20, 8, v18
	v_and_b32_e32 v24, 0xf0, v22
	v_mov_b32_e32 v25, v131
	v_lshl_add_u32 v55, v3, 2, s42
	v_mov_b32_e32 v23, v131
	v_lshl_add_u32 v66, v2, 2, s42
	v_lshl_add_u32 v67, v4, 2, s42
	v_lshl_add_u32 v68, v6, 2, s42
	v_lshlrev_b32_e32 v70, 2, v21
	s_mulk_i32 s53, 0x110
	v_add_u32_e32 v71, 0x11000, v54
	v_mov_b32_e32 v21, v131
	v_lshl_add_u32 v90, v46, 2, s42
	v_lshl_add_u32 v92, v48, 2, s42
	v_lshl_add_u32 v94, v230, 2, s42
	v_lshl_add_u32 v96, v231, 2, s42
	v_lshl_add_u32 v98, v232, 2, s42
	v_lshl_add_u32 v100, v233, 2, s42
	v_lshl_add_u32 v102, v15, 2, s42
	v_lshl_add_u64 v[26:27], s[74:75], 0, v[130:131]
	v_mul_lo_u32 v108, v108, s70
	v_mul_lo_u32 v117, v117, s70
	s_ashr_i32 s39, s38, 31
	v_cndmask_b32_e64 v184, 0, 1.0, vcc
	s_and_b32 s71, s67, 0xffffffe0
	v_add_u32_e32 v185, 0x1d800, v33
	v_add_u32_e32 v186, 0x1d820, v33
	v_add_u32_e32 v187, 0x1fc00, v33
	v_add_u32_e32 v188, 0x1fc20, v33
	v_writelane_b32 v255, s40, 50
	v_add_u32_e32 v190, v11, v12
	v_add_u32_e32 v191, v14, v12
	v_add_u32_e32 v192, v13, v37
	v_add_u32_e32 v193, v13, v38
	v_add_u32_e32 v194, v13, v39
	v_add_u32_e32 v195, v13, v40
	v_add_u32_e32 v196, v13, v41
	v_add_u32_e32 v197, v13, v42
	v_add_u32_e32 v198, v13, v43
	v_add_u32_e32 v199, v13, v44
	v_add_u32_e32 v200, v13, v45
	v_add_u32_e32 v201, v13, v47
	v_add_u32_e32 v202, v13, v49
	v_add_u32_e32 v203, v13, v203
	v_add_u32_e32 v204, v13, v204
	v_add_u32_e32 v205, v13, v205
	v_add_u32_e32 v206, v13, v206
	v_add_u32_e32 v207, v13, v207
	v_add_u32_e32 v208, v34, v16
	v_add_u32_e32 v209, v34, v17
	v_add_u32_e32 v210, v34, v210
	v_add_u32_e32 v211, v34, v211
	v_add_u32_e32 v212, v34, v212
	v_add_u32_e32 v213, v34, v213
	v_add_u32_e32 v214, v34, v214
	v_add_u32_e32 v215, v34, v215
	v_add_u32_e32 v216, v34, v216
	v_add_u32_e32 v217, v34, v217
	v_add_u32_e32 v218, v34, v218
	v_add_u32_e32 v219, v34, v219
	v_add_u32_e32 v220, v34, v220
	v_add_u32_e32 v221, v34, v221
	v_add_u32_e32 v222, v34, v222
	v_add_u32_e32 v223, v34, v7
	v_add_u32_e32 v224, v35, v224
	v_lshlrev_b32_e32 v225, 2, v2
	v_lshlrev_b32_e32 v226, 2, v4
	v_lshlrev_b32_e32 v227, 2, v6
	v_add_u32_e32 v228, v8, v36
	v_add_u32_e32 v229, v9, v36
	s_mov_b32 s56, s85
	v_cmp_lt_u32_e64 s[74:75], v46, v3
	v_cmp_gt_u32_e64 s[76:77], v46, v3
	v_cmp_lt_u32_e64 s[58:59], v48, v3
	v_cmp_gt_u32_e64 s[60:61], v48, v3
	v_cmp_lt_u32_e64 s[62:63], v230, v3
	v_cmp_gt_u32_e64 s[64:65], v230, v3
	v_cmp_lt_u32_e64 s[84:85], v231, v3
	v_cmp_gt_u32_e64 s[78:79], v231, v3
	v_cmp_lt_u32_e64 s[80:81], v232, v3
	v_cmp_gt_u32_e64 s[26:27], v232, v3
	v_cmp_lt_u32_e64 s[28:29], v233, v3
	v_cmp_gt_u32_e64 s[30:31], v233, v3
	v_cmp_lt_u32_e64 s[24:25], v15, v3
	v_cmp_gt_u32_e64 s[36:37], v15, v3
	v_cmp_eq_u32_e64 s[86:87], 0, v5
	v_cmp_eq_u32_e64 s[88:89], 1, v5
	v_cmp_eq_u32_e64 s[90:91], 2, v5
	v_cmp_eq_u32_e64 s[92:93], 3, v5
	s_mov_b32 s68, 0x55555556
	s_movk_i32 s69, 0x800
	v_readlane_b32 s73, v250, 15
	v_readlane_b32 s82, v250, 24
	v_readlane_b32 s83, v250, 25
	s_waitcnt vmcnt(0)
	s_nop 0
	s_branch .LBB0_201

; #define SOLVE_LD(i_) do { _Pragma("unroll") for (int a4 = 0; a4 < ((i_) + 15) / 16; ++a4) lq[(i_) % 3][a4] = *(const LAS f32x4*)(LP + (i_) * 64 + 4 * a4); } while (0)
; __device__ __forceinline__ void gdn_prep_phase(LAS unsigned char* lds, const GdnPrepArgs& A, int bid, int G, const unsigned char* zero_page) {
;     ...
;         SOLVE_LD(0); SOLVE_LD(1);
; #pragma unroll
;         for (int i = 0; i < 64; ++i) {
;             if (i + 2 < 48) SOLVE_LD(i + 2);
;             else if (i + 1 >= 48 && i + 1 < 64) SOLVE_LD(i + 1);
;             float p0 = 0.f, p1 = 0.f;
; #pragma unroll
;             for (int a4 = 0; a4 < (i + 15) / 16; ++a4) { const f32x4 lv = lq[i % 3][a4];
;                 p0 = __builtin_fmaf(lv.x, t[4 * a4], p0); p1 = __builtin_fmaf(lv.y, t[4 * a4 + 1], p1); p0 = __builtin_fmaf(lv.z, t[4 * a4 + 2], p0); p1 = __builtin_fmaf(lv.w, t[4 * a4 + 3], p1); }
;             float p = quad_sum(p0 + p1);
;             const float ti = (i == j ? 1.f : 0.f) - p;
;             if (q == (i & 3)) t[i >> 2] = ti;
;             if ((i & 7) == 3 && !(pflg & 64)) {
;                 constexpr int kk = 0; const int k8 = i >> 3, b = w + 8 * (k8 & 1); v4u f; int off; (void)kk;
;                 if (k8 < 2)      { f = frag16_rm(lds + L_KN, QS_, b >> 2, b & 3, lane); off = B_KA + b * 1024; }
;                 else if (k8 < 4) { f = frag16_rm(lds + L_QN, QS_, b >> 2, b & 3, lane); off = B_QA + b * 1024; }
;                 else if (k8 < 6) { f = frag16_tr(lds + L_KN, QS_, b >> 1, b & 1, lane); off = B_KT + b * 1024; }
;                 else             { f = frag16_rm(lds + (k8 == 6 ? L_AF : L_AB), AS_, w >> 1, w & 1, lane); off = (k8 == 6 ? B_AF : B_AB) + w * 1024; }
;                 *(v4u*)(blob + off + lane * 16) = f; }
.LBB0_337:
	s_waitcnt lgkmcnt(0)
	s_barrier
	s_cmp_eq_u32 s101, 3
	s_cbranch_scc1 .Ls4v3
	s_cmp_eq_u32 s101, 2
	s_cbranch_scc1 .Ls4v2
	s_cmp_eq_u32 s101, 1
	s_cbranch_scc1 .Ls4v1
	ds_read_b128 v[2:5], v56 offset:256
	ds_read_b128 v[8:11], v56 offset:512
	v_mov_b32_dpp v12, v131 quad_perm:[1,0,3,2] row_mask:0xf bank_mask:0xf bound_ctrl:1
	v_add_f32_e32 v12, 0, v12
	v_lshl_add_u64 v[6:7], s[40:41], 0, v[22:23]
	s_nop 0
	v_add_f32_dpp v12, v12, v12 quad_perm:[2,3,0,1] row_mask:0xf bank_mask:0xf bound_ctrl:1
	v_sub_f32_e32 v12, v104, v12
	v_cndmask_b32_e64 v130, 0, v12, s[86:87]
	s_waitcnt lgkmcnt(1)
	v_pk_fma_f32 v[2:3], v[2:3], v[130:131], 0 op_sel_hi:[1,1,0]
	ds_read_b128 v[12:15], v56 offset:768
	v_pk_fma_f32 v[2:3], v[4:5], 0, v[2:3] op_sel_hi:[1,0,1]
	s_nop 0
	v_add_f32_e32 v2, v2, v3
	s_nop 1
	v_add_f32_dpp v2, v2, v2 quad_perm:[1,0,3,2] row_mask:0xf bank_mask:0xf bound_ctrl:1
	s_nop 1
	v_add_f32_dpp v2, v2, v2 quad_perm:[2,3,0,1] row_mask:0xf bank_mask:0xf bound_ctrl:1
	v_sub_f32_e32 v2, v105, v2
	v_cndmask_b32_e64 v130, v130, v2, s[88:89]
	s_waitcnt lgkmcnt(1)
	v_pk_fma_f32 v[8:9], v[8:9], v[130:131], 0 op_sel_hi:[1,1,0]
	ds_read_b128 v[2:5], v56 offset:1024
	v_pk_fma_f32 v[8:9], v[10:11], 0, v[8:9] op_sel_hi:[1,0,1]
	s_nop 0
	v_add_f32_e32 v8, v8, v9
	s_nop 1
	v_add_f32_dpp v8, v8, v8 quad_perm:[1,0,3,2] row_mask:0xf bank_mask:0xf bound_ctrl:1
	s_nop 1
	v_add_f32_dpp v8, v8, v8 quad_perm:[2,3,0,1] row_mask:0xf bank_mask:0xf bound_ctrl:1
	v_sub_f32_e32 v8, v106, v8
	v_cndmask_b32_e64 v130, v130, v8, s[90:91]
	s_waitcnt lgkmcnt(1)
	v_pk_fma_f32 v[8:9], v[12:13], v[130:131], 0 op_sel_hi:[1,1,0]
	ds_read_b128 v[32:35], v56 offset:1280
	v_pk_fma_f32 v[8:9], v[14:15], 0, v[8:9] op_sel_hi:[1,0,1]
	v_readlane_b32 s2, v255, 48
	v_add_f32_e32 v8, v8, v9
	v_add_u32_e32 v9, v63, v108
	ds_read2_b64 v[10:13], v9 offset1:4
	v_add_f32_dpp v8, v8, v8 quad_perm:[1,0,3,2] row_mask:0xf bank_mask:0xf bound_ctrl:1
	v_readlane_b32 s3, v255, 49
	s_nop 0
	v_add_f32_dpp v8, v8, v8 quad_perm:[2,3,0,1] row_mask:0xf bank_mask:0xf bound_ctrl:1
	v_sub_f32_e32 v8, v107, v8
	v_cndmask_b32_e64 v130, v130, v8, s[92:93]
	v_lshl_add_u64 v[8:9], v[6:7], 0, s[2:3]
	s_waitcnt lgkmcnt(0)
	global_store_dwordx4 v[8:9], v[10:13], off
	v_pk_fma_f32 v[2:3], v[2:3], v[130:131], 0 op_sel_hi:[1,1,0]
	ds_read_b128 v[10:13], v56 offset:1536
	v_pk_fma_f32 v[2:3], v[4:5], 0, v[2:3] op_sel_hi:[1,0,1]
	s_nop 0
	v_add_f32_e32 v2, v2, v3
	s_nop 1
	v_add_f32_dpp v2, v2, v2 quad_perm:[1,0,3,2] row_mask:0xf bank_mask:0xf bound_ctrl:1
	s_nop 1
	v_add_f32_dpp v2, v2, v2 quad_perm:[2,3,0,1] row_mask:0xf bank_mask:0xf bound_ctrl:1
	v_sub_f32_e32 v2, v109, v2
	v_cndmask_b32_e64 v15, 0, v2, s[86:87]
	v_mov_b32_e32 v14, v130
	v_pk_fma_f32 v[16:17], v[32:33], v[14:15], 0 op_sel_hi:[1,1,0]
	ds_read_b128 v[2:5], v56 offset:1792
	v_pk_fma_f32 v[16:17], v[34:35], 0, v[16:17] op_sel_hi:[1,0,1]
	s_nop 0
	v_add_f32_e32 v14, v16, v17
	s_nop 1
	v_add_f32_dpp v14, v14, v14 quad_perm:[1,0,3,2] row_mask:0xf bank_mask:0xf bound_ctrl:1
	s_nop 1
	v_add_f32_dpp v14, v14, v14 quad_perm:[2,3,0,1] row_mask:0xf bank_mask:0xf bound_ctrl:1
	v_sub_f32_e32 v14, v110, v14
	v_cndmask_b32_e64 v33, v15, v14, s[88:89]
	v_mov_b32_e32 v32, v130
	s_waitcnt lgkmcnt(1)
	v_pk_fma_f32 v[10:11], v[10:11], v[32:33], 0 op_sel_hi:[1,1,0]
	ds_read_b128 v[14:17], v56 offset:2048
	v_pk_fma_f32 v[10:11], v[12:13], 0, v[10:11] op_sel_hi:[1,0,1]
	s_nop 0
	v_add_f32_e32 v10, v10, v11
	s_nop 1
	v_add_f32_dpp v10, v10, v10 quad_perm:[1,0,3,2] row_mask:0xf bank_mask:0xf bound_ctrl:1
	s_nop 1
	v_add_f32_dpp v10, v10, v10 quad_perm:[2,3,0,1] row_mask:0xf bank_mask:0xf bound_ctrl:1
	v_sub_f32_e32 v10, v111, v10
	v_cndmask_b32_e64 v33, v33, v10, s[90:91]
	s_waitcnt lgkmcnt(1)
	v_pk_fma_f32 v[2:3], v[2:3], v[32:33], 0 op_sel_hi:[1,1,0]
	ds_read_b128 v[10:13], v56 offset:2304
	v_pk_fma_f32 v[2:3], v[4:5], 0, v[2:3] op_sel_hi:[1,0,1]
	s_nop 0
	v_add_f32_e32 v2, v2, v3
	s_nop 1
	v_add_f32_dpp v2, v2, v2 quad_perm:[1,0,3,2] row_mask:0xf bank_mask:0xf bound_ctrl:1
	s_nop 1
	v_add_f32_dpp v2, v2, v2 quad_perm:[2,3,0,1] row_mask:0xf bank_mask:0xf bound_ctrl:1
	v_sub_f32_e32 v2, v112, v2
	v_cndmask_b32_e64 v3, v33, v2, s[92:93]
	v_mov_b32_e32 v2, v130
	s_waitcnt lgkmcnt(1)
	v_pk_fma_f32 v[4:5], v[14:15], v[2:3], 0 op_sel_hi:[1,1,0]
	ds_read_b128 v[32:35], v56 offset:2560
	v_pk_fma_f32 v[4:5], v[16:17], 0, v[4:5] op_sel_hi:[1,0,1]
	s_nop 0
	v_add_f32_e32 v4, v4, v5
	s_nop 1
	v_add_f32_dpp v4, v4, v4 quad_perm:[1,0,3,2] row_mask:0xf bank_mask:0xf bound_ctrl:1
	s_nop 1
	v_add_f32_dpp v4, v4, v4 quad_perm:[2,3,0,1] row_mask:0xf bank_mask:0xf bound_ctrl:1
	v_sub_f32_e32 v4, v113, v4
	v_cndmask_b32_e64 v4, 0, v4, s[86:87]
	s_waitcnt lgkmcnt(1)
	v_pk_fma_f32 v[10:11], v[10:11], v[2:3], 0 op_sel_hi:[1,1,0]
	v_mov_b32_e32 v5, v131
	v_pk_fma_f32 v[10:11], v[12:13], v[4:5], v[10:11]
	ds_read_b128 v[14:17], v56 offset:2816
	v_add_f32_e32 v5, v10, v11
	s_nop 1
	v_add_f32_dpp v5, v5, v5 quad_perm:[1,0,3,2] row_mask:0xf bank_mask:0xf bound_ctrl:1
	s_nop 1
	v_add_f32_dpp v5, v5, v5 quad_perm:[2,3,0,1] row_mask:0xf bank_mask:0xf bound_ctrl:1
	v_sub_f32_e32 v5, v114, v5
	v_cndmask_b32_e64 v4, v4, v5, s[88:89]
	s_waitcnt lgkmcnt(1)
	v_pk_fma_f32 v[32:33], v[32:33], v[2:3], 0 op_sel_hi:[1,1,0]
	v_mov_b32_e32 v5, v131
	v_pk_fma_f32 v[32:33], v[34:35], v[4:5], v[32:33]
	ds_read_b128 v[10:13], v56 offset:3072
	v_add_f32_e32 v5, v32, v33
	s_nop 1
	v_add_f32_dpp v5, v5, v5 quad_perm:[1,0,3,2] row_mask:0xf bank_mask:0xf bound_ctrl:1
	s_nop 1
	v_add_f32_dpp v5, v5, v5 quad_perm:[2,3,0,1] row_mask:0xf bank_mask:0xf bound_ctrl:1
	v_sub_f32_e32 v5, v115, v5
	v_cndmask_b32_e64 v4, v4, v5, s[90:91]
	s_waitcnt lgkmcnt(1)
; #define SOLVE_LD(i_) do { _Pragma("unroll") for (int a4 = 0; a4 < ((i_) + 15) / 16; ++a4) lq[(i_) % 3][a4] = *(const LAS f32x4*)(LP + (i_) * 64 + 4 * a4); } while (0)
; __device__ __forceinline__ void gdn_prep_phase(LAS unsigned char* lds, const GdnPrepArgs& A, int bid, int G, const unsigned char* zero_page) {
;     ...
;         SOLVE_LD(0); SOLVE_LD(1);
; #pragma unroll
;         for (int i = 0; i < 64; ++i) {
;             if (i + 2 < 48) SOLVE_LD(i + 2);
;             else if (i + 1 >= 48 && i + 1 < 64) SOLVE_LD(i + 1);
;             float p0 = 0.f, p1 = 0.f;
; #pragma unroll
;             for (int a4 = 0; a4 < (i + 15) / 16; ++a4) { const f32x4 lv = lq[i % 3][a4];
;                 p0 = __builtin_fmaf(lv.x, t[4 * a4], p0); p1 = __builtin_fmaf(lv.y, t[4 * a4 + 1], p1); p0 = __builtin_fmaf(lv.z, t[4 * a4 + 2], p0); p1 = __builtin_fmaf(lv.w, t[4 * a4 + 3], p1); }
;             float p = quad_sum(p0 + p1);
;             const float ti = (i == j ? 1.f : 0.f) - p;
;             if (q == (i & 3)) t[i >> 2] = ti;
;             if ((i & 7) == 3 && !(pflg & 64)) {
;                 constexpr int kk = 0; const int k8 = i >> 3, b = w + 8 * (k8 & 1); v4u f; int off; (void)kk;
;                 if (k8 < 2)      { f = frag16_rm(lds + L_KN, QS_, b >> 2, b & 3, lane); off = B_KA + b * 1024; }
;                 else if (k8 < 4) { f = frag16_rm(lds + L_QN, QS_, b >> 2, b & 3, lane); off = B_QA + b * 1024; }
;                 else if (k8 < 6) { f = frag16_tr(lds + L_KN, QS_, b >> 1, b & 1, lane); off = B_KT + b * 1024; }
;                 else             { f = frag16_rm(lds + (k8 == 6 ? L_AF : L_AB), AS_, w >> 1, w & 1, lane); off = (k8 == 6 ? B_AF : B_AB) + w * 1024; }
;                 *(v4u*)(blob + off + lane * 16) = f; }
	v_pk_fma_f32 v[14:15], v[14:15], v[2:3], 0 op_sel_hi:[1,1,0]
	v_mov_b32_e32 v5, v131
	v_pk_fma_f32 v[14:15], v[16:17], v[4:5], v[14:15]
	ds_read_b128 v[34:37], v56 offset:3328
	v_add_f32_e32 v5, v14, v15
	v_add_u32_e32 v14, v63, v117
	ds_read2_b64 v[14:17], v14 offset1:4
	v_add_f32_dpp v5, v5, v5 quad_perm:[1,0,3,2] row_mask:0xf bank_mask:0xf bound_ctrl:1
	v_lshl_add_u64 v[32:33], v[6:7], 0, s[38:39]
	s_waitcnt lgkmcnt(0)
	global_store_dwordx4 v[32:33], v[14:17], off
	v_add_f32_dpp v5, v5, v5 quad_perm:[2,3,0,1] row_mask:0xf bank_mask:0xf bound_ctrl:1
	v_sub_f32_e32 v5, v116, v5
	v_cndmask_b32_e64 v4, v4, v5, s[92:93]
	v_pk_fma_f32 v[10:11], v[10:11], v[2:3], 0 op_sel_hi:[1,1,0]
	v_mov_b32_e32 v5, v131
	v_pk_fma_f32 v[10:11], v[12:13], v[4:5], v[10:11]
	ds_read_b128 v[14:17], v56 offset:3584
	v_add_f32_e32 v5, v10, v11
	s_nop 1
	v_add_f32_dpp v5, v5, v5 quad_perm:[1,0,3,2] row_mask:0xf bank_mask:0xf bound_ctrl:1
	s_nop 1
	v_add_f32_dpp v5, v5, v5 quad_perm:[2,3,0,1] row_mask:0xf bank_mask:0xf bound_ctrl:1
	v_sub_f32_e32 v5, v118, v5
	v_cndmask_b32_e64 v5, 0, v5, s[86:87]
	v_pk_fma_f32 v[34:35], v[34:35], v[2:3], 0 op_sel_hi:[1,1,0]
	ds_read_b128 v[10:13], v56 offset:3840
	v_pk_fma_f32 v[34:35], v[36:37], v[4:5], v[34:35]
	s_nop 0
	v_add_f32_e32 v34, v34, v35
	s_nop 1
	v_add_f32_dpp v34, v34, v34 quad_perm:[1,0,3,2] row_mask:0xf bank_mask:0xf bound_ctrl:1
	s_nop 1
	v_add_f32_dpp v34, v34, v34 quad_perm:[2,3,0,1] row_mask:0xf bank_mask:0xf bound_ctrl:1
	v_sub_f32_e32 v34, v119, v34
	v_cndmask_b32_e64 v5, v5, v34, s[88:89]
	s_waitcnt lgkmcnt(1)
	v_pk_fma_f32 v[14:15], v[14:15], v[2:3], 0 op_sel_hi:[1,1,0]
	ds_read_b128 v[34:37], v56 offset:4096
	v_pk_fma_f32 v[14:15], v[16:17], v[4:5], v[14:15]
	s_nop 0
	v_add_f32_e32 v14, v14, v15
	s_nop 1
	v_add_f32_dpp v14, v14, v14 quad_perm:[1,0,3,2] row_mask:0xf bank_mask:0xf bound_ctrl:1
	s_nop 1
	v_add_f32_dpp v14, v14, v14 quad_perm:[2,3,0,1] row_mask:0xf bank_mask:0xf bound_ctrl:1
	v_sub_f32_e32 v14, v120, v14
	v_cndmask_b32_e64 v5, v5, v14, s[90:91]
	s_waitcnt lgkmcnt(1)
	v_pk_fma_f32 v[10:11], v[10:11], v[2:3], 0 op_sel_hi:[1,1,0]
	ds_read_b128 v[14:17], v56 offset:4352
	ds_read_b128 v[38:41], v56 offset:4368
	v_pk_fma_f32 v[10:11], v[12:13], v[4:5], v[10:11]
	s_nop 0
	v_add_f32_e32 v10, v10, v11
	s_nop 1
	v_add_f32_dpp v10, v10, v10 quad_perm:[1,0,3,2] row_mask:0xf bank_mask:0xf bound_ctrl:1
	s_nop 1
	v_add_f32_dpp v10, v10, v10 quad_perm:[2,3,0,1] row_mask:0xf bank_mask:0xf bound_ctrl:1
	v_sub_f32_e32 v10, v121, v10
	v_cndmask_b32_e64 v5, v5, v10, s[92:93]
	s_waitcnt lgkmcnt(2)
	v_pk_fma_f32 v[34:35], v[34:35], v[2:3], 0 op_sel_hi:[1,1,0]
	ds_read_b128 v[10:13], v56 offset:4608
	ds_read_b128 v[42:45], v56 offset:4624
	v_pk_fma_f32 v[34:35], v[36:37], v[4:5], v[34:35]
	s_nop 0
	v_add_f32_e32 v34, v34, v35
	s_nop 1
	v_add_f32_dpp v34, v34, v34 quad_perm:[1,0,3,2] row_mask:0xf bank_mask:0xf bound_ctrl:1
	s_nop 1
	v_add_f32_dpp v34, v34, v34 quad_perm:[2,3,0,1] row_mask:0xf bank_mask:0xf bound_ctrl:1
	v_sub_f32_e32 v34, v122, v34
	v_cndmask_b32_e64 v230, 0, v34, s[86:87]
	s_waitcnt lgkmcnt(3)
	v_pk_fma_f32 v[14:15], v[14:15], v[2:3], 0 op_sel_hi:[1,1,0]
	v_mov_b32_e32 v231, v131
	v_pk_fma_f32 v[14:15], v[16:17], v[4:5], v[14:15]
	ds_read_b128 v[34:37], v56 offset:4864
	ds_read_b128 v[46:49], v56 offset:4880
	s_waitcnt lgkmcnt(4)
	v_pk_fma_f32 v[14:15], v[38:39], v[230:231], v[14:15]
	s_nop 0
	v_pk_fma_f32 v[14:15], v[40:41], 0, v[14:15] op_sel_hi:[1,0,1]
	s_nop 0
	v_add_f32_e32 v14, v14, v15
	s_nop 1
	v_add_f32_dpp v14, v14, v14 quad_perm:[1,0,3,2] row_mask:0xf bank_mask:0xf bound_ctrl:1
	s_nop 1
	v_add_f32_dpp v14, v14, v14 quad_perm:[2,3,0,1] row_mask:0xf bank_mask:0xf bound_ctrl:1
	v_sub_f32_e32 v14, v123, v14
	v_cndmask_b32_e64 v230, v230, v14, s[88:89]
	s_waitcnt lgkmcnt(3)
	v_pk_fma_f32 v[10:11], v[10:11], v[2:3], 0 op_sel_hi:[1,1,0]
	ds_read_b128 v[14:17], v56 offset:5120
	ds_read_b128 v[38:41], v56 offset:5136
	v_pk_fma_f32 v[10:11], v[12:13], v[4:5], v[10:11]
	s_waitcnt lgkmcnt(4)
	v_pk_fma_f32 v[10:11], v[42:43], v[230:231], v[10:11]
	s_nop 0
	v_pk_fma_f32 v[10:11], v[44:45], 0, v[10:11] op_sel_hi:[1,0,1]
	s_nop 0
	v_add_f32_e32 v10, v10, v11
	s_nop 1
	v_add_f32_dpp v10, v10, v10 quad_perm:[1,0,3,2] row_mask:0xf bank_mask:0xf bound_ctrl:1
	s_nop 1
	v_add_f32_dpp v10, v10, v10 quad_perm:[2,3,0,1] row_mask:0xf bank_mask:0xf bound_ctrl:1
	v_sub_f32_e32 v10, v124, v10
	v_cndmask_b32_e64 v10, v230, v10, s[90:91]
	s_waitcnt lgkmcnt(3)
	v_pk_fma_f32 v[12:13], v[34:35], v[2:3], 0 op_sel_hi:[1,1,0]
	v_mov_b32_e32 v11, v131
	v_pk_fma_f32 v[12:13], v[36:37], v[4:5], v[12:13]
	ds_read_b128 v[42:45], v56 offset:5376
	ds_read_b128 v[230:233], v56 offset:5392
	s_waitcnt lgkmcnt(4)
	v_pk_fma_f32 v[12:13], v[46:47], v[10:11], v[12:13]
	s_movk_i32 s40, 0x4000
	v_pk_fma_f32 v[12:13], v[48:49], 0, v[12:13] op_sel_hi:[1,0,1]
	s_nop 0
	v_add_f32_e32 v11, v12, v13
	v_add_co_u32_e32 v12, vcc, s40, v8
	s_nop 0
	v_add_f32_dpp v11, v11, v11 quad_perm:[1,0,3,2] row_mask:0xf bank_mask:0xf bound_ctrl:1
	v_addc_co_u32_e32 v13, vcc, 0, v9, vcc
	s_nop 0
	v_add_f32_dpp v11, v11, v11 quad_perm:[2,3,0,1] row_mask:0xf bank_mask:0xf bound_ctrl:1
	v_sub_f32_e32 v11, v125, v11
	v_cndmask_b32_e64 v10, v10, v11, s[92:93]
	v_add_u32_e32 v11, v62, v108
	v_add_u32_e32 v11, 0xc800, v11
	ds_read2_b64 v[34:37], v11 offset0:128 offset1:132
	s_waitcnt lgkmcnt(0)
; #define SOLVE_LD(i_) do { _Pragma("unroll") for (int a4 = 0; a4 < ((i_) + 15) / 16; ++a4) lq[(i_) % 3][a4] = *(const LAS f32x4*)(LP + (i_) * 64 + 4 * a4); } while (0)
; __device__ __forceinline__ void gdn_prep_phase(LAS unsigned char* lds, const GdnPrepArgs& A, int bid, int G, const unsigned char* zero_page) {
;     ...
;         SOLVE_LD(0); SOLVE_LD(1);
; #pragma unroll
;         for (int i = 0; i < 64; ++i) {
;             if (i + 2 < 48) SOLVE_LD(i + 2);
;             else if (i + 1 >= 48 && i + 1 < 64) SOLVE_LD(i + 1);
;             float p0 = 0.f, p1 = 0.f;
; #pragma unroll
;             for (int a4 = 0; a4 < (i + 15) / 16; ++a4) { const f32x4 lv = lq[i % 3][a4];
;                 p0 = __builtin_fmaf(lv.x, t[4 * a4], p0); p1 = __builtin_fmaf(lv.y, t[4 * a4 + 1], p1); p0 = __builtin_fmaf(lv.z, t[4 * a4 + 2], p0); p1 = __builtin_fmaf(lv.w, t[4 * a4 + 3], p1); }
;             float p = quad_sum(p0 + p1);
;             const float ti = (i == j ? 1.f : 0.f) - p;
;             if (q == (i & 3)) t[i >> 2] = ti;
;             if ((i & 7) == 3 && !(pflg & 64)) {
;                 constexpr int kk = 0; const int k8 = i >> 3, b = w + 8 * (k8 & 1); v4u f; int off; (void)kk;
;                 if (k8 < 2)      { f = frag16_rm(lds + L_KN, QS_, b >> 2, b & 3, lane); off = B_KA + b * 1024; }
;                 else if (k8 < 4) { f = frag16_rm(lds + L_QN, QS_, b >> 2, b & 3, lane); off = B_QA + b * 1024; }
;                 else if (k8 < 6) { f = frag16_tr(lds + L_KN, QS_, b >> 1, b & 1, lane); off = B_KT + b * 1024; }
;                 else             { f = frag16_rm(lds + (k8 == 6 ? L_AF : L_AB), AS_, w >> 1, w & 1, lane); off = (k8 == 6 ? B_AF : B_AB) + w * 1024; }
;                 *(v4u*)(blob + off + lane * 16) = f; }
	global_store_dwordx4 v[12:13], v[34:37], off
	v_pk_fma_f32 v[12:13], v[14:15], v[2:3], 0 op_sel_hi:[1,1,0]
	v_mov_b32_e32 v11, v131
	v_pk_fma_f32 v[12:13], v[16:17], v[4:5], v[12:13]
	ds_read_b128 v[34:37], v56 offset:5632
	ds_read_b128 v[46:49], v56 offset:5648
	v_pk_fma_f32 v[12:13], v[38:39], v[10:11], v[12:13]
	s_nop 0
	v_pk_fma_f32 v[12:13], v[40:41], 0, v[12:13] op_sel_hi:[1,0,1]
	s_nop 0
	v_add_f32_e32 v11, v12, v13
	s_nop 1
	v_add_f32_dpp v11, v11, v11 quad_perm:[1,0,3,2] row_mask:0xf bank_mask:0xf bound_ctrl:1
	s_nop 1
	v_add_f32_dpp v11, v11, v11 quad_perm:[2,3,0,1] row_mask:0xf bank_mask:0xf bound_ctrl:1
	v_sub_f32_e32 v11, v126, v11
	v_cndmask_b32_e64 v11, 0, v11, s[86:87]
	v_pk_fma_f32 v[16:17], v[42:43], v[2:3], 0 op_sel_hi:[1,1,0]
	ds_read_b128 v[12:15], v56 offset:5888
	ds_read_b128 v[38:41], v56 offset:5904
	v_pk_fma_f32 v[16:17], v[44:45], v[4:5], v[16:17]
	s_nop 0
	v_pk_fma_f32 v[16:17], v[230:231], v[10:11], v[16:17]
	s_nop 0
	v_pk_fma_f32 v[16:17], v[232:233], 0, v[16:17] op_sel_hi:[1,0,1]
	s_nop 0
	v_add_f32_e32 v16, v16, v17
	s_nop 1
	v_add_f32_dpp v16, v16, v16 quad_perm:[1,0,3,2] row_mask:0xf bank_mask:0xf bound_ctrl:1
	s_nop 1
	v_add_f32_dpp v16, v16, v16 quad_perm:[2,3,0,1] row_mask:0xf bank_mask:0xf bound_ctrl:1
	v_sub_f32_e32 v16, v127, v16
	v_cndmask_b32_e64 v11, v11, v16, s[88:89]
	s_waitcnt lgkmcnt(3)
	v_pk_fma_f32 v[16:17], v[34:35], v[2:3], 0 op_sel_hi:[1,1,0]
	ds_read_b128 v[42:45], v56 offset:6144
	ds_read_b128 v[230:233], v56 offset:6160
	v_pk_fma_f32 v[16:17], v[36:37], v[4:5], v[16:17]
	s_waitcnt lgkmcnt(4)
	v_pk_fma_f32 v[16:17], v[46:47], v[10:11], v[16:17]
	s_nop 0
	v_pk_fma_f32 v[16:17], v[48:49], 0, v[16:17] op_sel_hi:[1,0,1]
	s_nop 0
	v_add_f32_e32 v16, v16, v17
	s_nop 1
	v_add_f32_dpp v16, v16, v16 quad_perm:[1,0,3,2] row_mask:0xf bank_mask:0xf bound_ctrl:1
	s_nop 1
	v_add_f32_dpp v16, v16, v16 quad_perm:[2,3,0,1] row_mask:0xf bank_mask:0xf bound_ctrl:1
	v_sub_f32_e32 v16, v128, v16
	v_cndmask_b32_e64 v11, v11, v16, s[90:91]
	s_waitcnt lgkmcnt(3)
	v_pk_fma_f32 v[12:13], v[12:13], v[2:3], 0 op_sel_hi:[1,1,0]
	ds_read_b128 v[34:37], v56 offset:6400
	ds_read_b128 v[46:49], v56 offset:6416
	v_pk_fma_f32 v[12:13], v[14:15], v[4:5], v[12:13]
	s_waitcnt lgkmcnt(4)
	v_pk_fma_f32 v[12:13], v[38:39], v[10:11], v[12:13]
	s_nop 0
	v_pk_fma_f32 v[12:13], v[40:41], 0, v[12:13] op_sel_hi:[1,0,1]
	s_nop 0
	v_add_f32_e32 v12, v12, v13
	s_nop 1
	v_add_f32_dpp v12, v12, v12 quad_perm:[1,0,3,2] row_mask:0xf bank_mask:0xf bound_ctrl:1
	s_nop 1
	v_add_f32_dpp v12, v12, v12 quad_perm:[2,3,0,1] row_mask:0xf bank_mask:0xf bound_ctrl:1
	v_sub_f32_e32 v12, v129, v12
	v_cndmask_b32_e64 v11, v11, v12, s[92:93]
	s_waitcnt lgkmcnt(3)
	v_pk_fma_f32 v[16:17], v[42:43], v[2:3], 0 op_sel_hi:[1,1,0]
	ds_read_b128 v[12:15], v56 offset:6656
	ds_read_b128 v[38:41], v56 offset:6672
	v_pk_fma_f32 v[16:17], v[44:45], v[4:5], v[16:17]
	s_waitcnt lgkmcnt(4)
	v_pk_fma_f32 v[16:17], v[230:231], v[10:11], v[16:17]
	s_nop 0
	v_pk_fma_f32 v[16:17], v[232:233], 0, v[16:17] op_sel_hi:[1,0,1]
	s_nop 0
	v_add_f32_e32 v16, v16, v17
	s_nop 1
	v_add_f32_dpp v16, v16, v16 quad_perm:[1,0,3,2] row_mask:0xf bank_mask:0xf bound_ctrl:1
	s_nop 1
	v_add_f32_dpp v16, v16, v16 quad_perm:[2,3,0,1] row_mask:0xf bank_mask:0xf bound_ctrl:1
	v_sub_f32_e32 v16, v136, v16
	v_cndmask_b32_e64 v16, 0, v16, s[86:87]
	s_waitcnt lgkmcnt(3)
	v_pk_fma_f32 v[34:35], v[34:35], v[2:3], 0 op_sel_hi:[1,1,0]
	v_mov_b32_e32 v17, v131
	v_pk_fma_f32 v[34:35], v[36:37], v[4:5], v[34:35]
	ds_read_b128 v[42:45], v56 offset:6912
	ds_read_b128 v[230:233], v56 offset:6928
	s_waitcnt lgkmcnt(4)
	v_pk_fma_f32 v[34:35], v[46:47], v[10:11], v[34:35]
	s_nop 0
	v_pk_fma_f32 v[34:35], v[48:49], v[16:17], v[34:35]
	s_nop 0
	v_add_f32_e32 v17, v34, v35
	s_nop 1
	v_add_f32_dpp v17, v17, v17 quad_perm:[1,0,3,2] row_mask:0xf bank_mask:0xf bound_ctrl:1
	s_nop 1
	v_add_f32_dpp v17, v17, v17 quad_perm:[2,3,0,1] row_mask:0xf bank_mask:0xf bound_ctrl:1
	v_sub_f32_e32 v17, v137, v17
	v_cndmask_b32_e64 v16, v16, v17, s[88:89]
	s_waitcnt lgkmcnt(3)
	v_pk_fma_f32 v[12:13], v[12:13], v[2:3], 0 op_sel_hi:[1,1,0]
	v_mov_b32_e32 v17, v131
	v_pk_fma_f32 v[12:13], v[14:15], v[4:5], v[12:13]
	ds_read_b128 v[34:37], v56 offset:7168
	ds_read_b128 v[46:49], v56 offset:7184
	s_waitcnt lgkmcnt(4)
	v_pk_fma_f32 v[12:13], v[38:39], v[10:11], v[12:13]
	s_nop 0
	v_pk_fma_f32 v[12:13], v[40:41], v[16:17], v[12:13]
	s_nop 0
	v_add_f32_e32 v12, v12, v13
	s_nop 1
	v_add_f32_dpp v12, v12, v12 quad_perm:[1,0,3,2] row_mask:0xf bank_mask:0xf bound_ctrl:1
	s_nop 1
	v_add_f32_dpp v12, v12, v12 quad_perm:[2,3,0,1] row_mask:0xf bank_mask:0xf bound_ctrl:1
	v_sub_f32_e32 v12, v138, v12
	v_cndmask_b32_e64 v12, v16, v12, s[90:91]
	s_waitcnt lgkmcnt(3)
	v_pk_fma_f32 v[42:43], v[42:43], v[2:3], 0 op_sel_hi:[1,1,0]
	v_mov_b32_e32 v13, v131
	v_pk_fma_f32 v[42:43], v[44:45], v[4:5], v[42:43]
	ds_read_b128 v[14:17], v56 offset:7424
	ds_read_b128 v[38:41], v56 offset:7440
	s_waitcnt lgkmcnt(4)
	v_pk_fma_f32 v[42:43], v[230:231], v[10:11], v[42:43]
	v_add_co_u32_e32 v230, vcc, s40, v32
	v_pk_fma_f32 v[42:43], v[232:233], v[12:13], v[42:43]
	s_nop 0
	v_addc_co_u32_e32 v231, vcc, 0, v33, vcc
	v_add_f32_e32 v13, v42, v43
	s_nop 1
	v_add_f32_dpp v13, v13, v13 quad_perm:[1,0,3,2] row_mask:0xf bank_mask:0xf bound_ctrl:1
	s_nop 1
	v_add_f32_dpp v13, v13, v13 quad_perm:[2,3,0,1] row_mask:0xf bank_mask:0xf bound_ctrl:1
	v_sub_f32_e32 v13, v139, v13
	v_cndmask_b32_e64 v12, v12, v13, s[92:93]
	v_add_u32_e32 v13, v62, v117
	v_add_u32_e32 v13, 0xc800, v13
	ds_read2_b64 v[42:45], v13 offset0:128 offset1:132
	s_waitcnt lgkmcnt(0)
; #define SOLVE_LD(i_) do { _Pragma("unroll") for (int a4 = 0; a4 < ((i_) + 15) / 16; ++a4) lq[(i_) % 3][a4] = *(const LAS f32x4*)(LP + (i_) * 64 + 4 * a4); } while (0)
; __device__ __forceinline__ void gdn_prep_phase(LAS unsigned char* lds, const GdnPrepArgs& A, int bid, int G, const unsigned char* zero_page) {
;     ...
;         SOLVE_LD(0); SOLVE_LD(1);
; #pragma unroll
;         for (int i = 0; i < 64; ++i) {
;             if (i + 2 < 48) SOLVE_LD(i + 2);
;             else if (i + 1 >= 48 && i + 1 < 64) SOLVE_LD(i + 1);
;             float p0 = 0.f, p1 = 0.f;
; #pragma unroll
;             for (int a4 = 0; a4 < (i + 15) / 16; ++a4) { const f32x4 lv = lq[i % 3][a4];
;                 p0 = __builtin_fmaf(lv.x, t[4 * a4], p0); p1 = __builtin_fmaf(lv.y, t[4 * a4 + 1], p1); p0 = __builtin_fmaf(lv.z, t[4 * a4 + 2], p0); p1 = __builtin_fmaf(lv.w, t[4 * a4 + 3], p1); }
;             float p = quad_sum(p0 + p1);
;             const float ti = (i == j ? 1.f : 0.f) - p;
;             if (q == (i & 3)) t[i >> 2] = ti;
;             if ((i & 7) == 3 && !(pflg & 64)) {
;                 constexpr int kk = 0; const int k8 = i >> 3, b = w + 8 * (k8 & 1); v4u f; int off; (void)kk;
;                 if (k8 < 2)      { f = frag16_rm(lds + L_KN, QS_, b >> 2, b & 3, lane); off = B_KA + b * 1024; }
;                 else if (k8 < 4) { f = frag16_rm(lds + L_QN, QS_, b >> 2, b & 3, lane); off = B_QA + b * 1024; }
;                 else if (k8 < 6) { f = frag16_tr(lds + L_KN, QS_, b >> 1, b & 1, lane); off = B_KT + b * 1024; }
;                 else             { f = frag16_rm(lds + (k8 == 6 ? L_AF : L_AB), AS_, w >> 1, w & 1, lane); off = (k8 == 6 ? B_AF : B_AB) + w * 1024; }
;                 *(v4u*)(blob + off + lane * 16) = f; }
	global_store_dwordx4 v[230:231], v[42:45], off
	v_pk_fma_f32 v[34:35], v[34:35], v[2:3], 0 op_sel_hi:[1,1,0]
	v_mov_b32_e32 v13, v131
	v_pk_fma_f32 v[34:35], v[36:37], v[4:5], v[34:35]
	ds_read_b128 v[42:45], v56 offset:7680
	ds_read_b128 v[230:233], v56 offset:7696
	v_pk_fma_f32 v[34:35], v[46:47], v[10:11], v[34:35]
	s_nop 0
	v_pk_fma_f32 v[34:35], v[48:49], v[12:13], v[34:35]
	s_nop 0
	v_add_f32_e32 v13, v34, v35
	s_nop 1
	v_add_f32_dpp v13, v13, v13 quad_perm:[1,0,3,2] row_mask:0xf bank_mask:0xf bound_ctrl:1
	s_nop 1
	v_add_f32_dpp v13, v13, v13 quad_perm:[2,3,0,1] row_mask:0xf bank_mask:0xf bound_ctrl:1
	v_sub_f32_e32 v13, v140, v13
	v_cndmask_b32_e64 v13, 0, v13, s[86:87]
	v_pk_fma_f32 v[14:15], v[14:15], v[2:3], 0 op_sel_hi:[1,1,0]
	ds_read_b128 v[34:37], v56 offset:7936
	ds_read_b128 v[46:49], v56 offset:7952
	v_pk_fma_f32 v[14:15], v[16:17], v[4:5], v[14:15]
	s_nop 0
	v_pk_fma_f32 v[14:15], v[38:39], v[10:11], v[14:15]
	s_nop 0
	v_pk_fma_f32 v[14:15], v[40:41], v[12:13], v[14:15]
	s_nop 0
	v_add_f32_e32 v14, v14, v15
	s_nop 1
	v_add_f32_dpp v14, v14, v14 quad_perm:[1,0,3,2] row_mask:0xf bank_mask:0xf bound_ctrl:1
	s_nop 1
	v_add_f32_dpp v14, v14, v14 quad_perm:[2,3,0,1] row_mask:0xf bank_mask:0xf bound_ctrl:1
	v_sub_f32_e32 v14, v141, v14
	v_cndmask_b32_e64 v13, v13, v14, s[88:89]
	s_waitcnt lgkmcnt(3)
	v_pk_fma_f32 v[42:43], v[42:43], v[2:3], 0 op_sel_hi:[1,1,0]
	ds_read_b128 v[14:17], v56 offset:8192
	ds_read_b128 v[38:41], v56 offset:8208
	v_pk_fma_f32 v[42:43], v[44:45], v[4:5], v[42:43]
	s_waitcnt lgkmcnt(4)
	v_pk_fma_f32 v[42:43], v[230:231], v[10:11], v[42:43]
	s_nop 0
	v_pk_fma_f32 v[42:43], v[232:233], v[12:13], v[42:43]
	s_nop 0
	v_add_f32_e32 v42, v42, v43
	s_nop 1
	v_add_f32_dpp v42, v42, v42 quad_perm:[1,0,3,2] row_mask:0xf bank_mask:0xf bound_ctrl:1
	s_nop 1
	v_add_f32_dpp v42, v42, v42 quad_perm:[2,3,0,1] row_mask:0xf bank_mask:0xf bound_ctrl:1
	v_sub_f32_e32 v42, v142, v42
	v_cndmask_b32_e64 v13, v13, v42, s[90:91]
	s_waitcnt lgkmcnt(3)
	v_pk_fma_f32 v[34:35], v[34:35], v[2:3], 0 op_sel_hi:[1,1,0]
	ds_read_b128 v[42:45], v56 offset:8448
	ds_read_b128 v[230:233], v56 offset:8464
	ds_read_b128 v[234:237], v56 offset:8480
	v_pk_fma_f32 v[34:35], v[36:37], v[4:5], v[34:35]
	s_waitcnt lgkmcnt(5)
	v_pk_fma_f32 v[34:35], v[46:47], v[10:11], v[34:35]
	s_nop 0
	v_pk_fma_f32 v[34:35], v[48:49], v[12:13], v[34:35]
	s_nop 0
	v_add_f32_e32 v34, v34, v35
	s_nop 1
	v_add_f32_dpp v34, v34, v34 quad_perm:[1,0,3,2] row_mask:0xf bank_mask:0xf bound_ctrl:1
	s_nop 1
	v_add_f32_dpp v34, v34, v34 quad_perm:[2,3,0,1] row_mask:0xf bank_mask:0xf bound_ctrl:1
	v_sub_f32_e32 v34, v143, v34
	v_cndmask_b32_e64 v13, v13, v34, s[92:93]
	s_waitcnt lgkmcnt(4)
	v_pk_fma_f32 v[14:15], v[14:15], v[2:3], 0 op_sel_hi:[1,1,0]
	ds_read_b128 v[34:37], v56 offset:8704
	ds_read_b128 v[46:49], v56 offset:8720
	ds_read_b128 v[238:241], v56 offset:8736
	v_pk_fma_f32 v[14:15], v[16:17], v[4:5], v[14:15]
	s_waitcnt lgkmcnt(6)
	v_pk_fma_f32 v[14:15], v[38:39], v[10:11], v[14:15]
	s_nop 0
	v_pk_fma_f32 v[14:15], v[40:41], v[12:13], v[14:15]
	s_nop 0
	v_add_f32_e32 v14, v14, v15
	s_nop 1
	v_add_f32_dpp v14, v14, v14 quad_perm:[1,0,3,2] row_mask:0xf bank_mask:0xf bound_ctrl:1
	s_nop 1
	v_add_f32_dpp v14, v14, v14 quad_perm:[2,3,0,1] row_mask:0xf bank_mask:0xf bound_ctrl:1
	v_sub_f32_e32 v14, v144, v14
	v_cndmask_b32_e64 v246, 0, v14, s[86:87]
	s_waitcnt lgkmcnt(5)
	v_pk_fma_f32 v[42:43], v[42:43], v[2:3], 0 op_sel_hi:[1,1,0]
	v_mov_b32_e32 v247, v131
	v_pk_fma_f32 v[42:43], v[44:45], v[4:5], v[42:43]
	ds_read_b128 v[14:17], v56 offset:8960
	ds_read_b128 v[38:41], v56 offset:8976
	ds_read_b128 v[242:245], v56 offset:8992
	s_waitcnt lgkmcnt(7)
	v_pk_fma_f32 v[42:43], v[230:231], v[10:11], v[42:43]
	s_nop 0
	v_pk_fma_f32 v[42:43], v[232:233], v[12:13], v[42:43]
	s_waitcnt lgkmcnt(6)
	v_pk_fma_f32 v[42:43], v[234:235], v[246:247], v[42:43]
	s_nop 0
	v_pk_fma_f32 v[42:43], v[236:237], 0, v[42:43] op_sel_hi:[1,0,1]
	s_nop 0
	v_add_f32_e32 v42, v42, v43
	s_nop 1
	v_add_f32_dpp v42, v42, v42 quad_perm:[1,0,3,2] row_mask:0xf bank_mask:0xf bound_ctrl:1
	s_nop 1
	v_add_f32_dpp v42, v42, v42 quad_perm:[2,3,0,1] row_mask:0xf bank_mask:0xf bound_ctrl:1
	v_sub_f32_e32 v42, v145, v42
	v_cndmask_b32_e64 v246, v246, v42, s[88:89]
	s_waitcnt lgkmcnt(5)
	v_pk_fma_f32 v[34:35], v[34:35], v[2:3], 0 op_sel_hi:[1,1,0]
	ds_read_b128 v[42:45], v56 offset:9216
	ds_read_b128 v[230:233], v56 offset:9232
	ds_read_b128 v[234:237], v56 offset:9248
	v_pk_fma_f32 v[34:35], v[36:37], v[4:5], v[34:35]
	s_waitcnt lgkmcnt(7)
	v_pk_fma_f32 v[34:35], v[46:47], v[10:11], v[34:35]
	s_nop 0
	v_pk_fma_f32 v[34:35], v[48:49], v[12:13], v[34:35]
	s_waitcnt lgkmcnt(6)
	v_pk_fma_f32 v[34:35], v[238:239], v[246:247], v[34:35]
	s_nop 0
	v_pk_fma_f32 v[34:35], v[240:241], 0, v[34:35] op_sel_hi:[1,0,1]
	s_nop 0
	v_add_f32_e32 v34, v34, v35
	s_nop 1
	v_add_f32_dpp v34, v34, v34 quad_perm:[1,0,3,2] row_mask:0xf bank_mask:0xf bound_ctrl:1
	s_nop 1
	v_add_f32_dpp v34, v34, v34 quad_perm:[2,3,0,1] row_mask:0xf bank_mask:0xf bound_ctrl:1
	v_sub_f32_e32 v34, v146, v34
	v_cndmask_b32_e64 v238, v246, v34, s[90:91]
	s_waitcnt lgkmcnt(5)
	v_pk_fma_f32 v[14:15], v[14:15], v[2:3], 0 op_sel_hi:[1,1,0]
	v_mov_b32_e32 v239, v131
	v_pk_fma_f32 v[14:15], v[16:17], v[4:5], v[14:15]
	ds_read_b128 v[34:37], v56 offset:9472
	ds_read_b128 v[46:49], v56 offset:9488
	s_waitcnt lgkmcnt(6)
	v_pk_fma_f32 v[14:15], v[38:39], v[10:11], v[14:15]
	s_mov_b32 s40, 0x8000
	v_pk_fma_f32 v[14:15], v[40:41], v[12:13], v[14:15]
	s_waitcnt lgkmcnt(5)
; #define SOLVE_LD(i_) do { _Pragma("unroll") for (int a4 = 0; a4 < ((i_) + 15) / 16; ++a4) lq[(i_) % 3][a4] = *(const LAS f32x4*)(LP + (i_) * 64 + 4 * a4); } while (0)
; __device__ __forceinline__ void gdn_prep_phase(LAS unsigned char* lds, const GdnPrepArgs& A, int bid, int G, const unsigned char* zero_page) {
;     ...
;         SOLVE_LD(0); SOLVE_LD(1);
; #pragma unroll
;         for (int i = 0; i < 64; ++i) {
;             if (i + 2 < 48) SOLVE_LD(i + 2);
;             else if (i + 1 >= 48 && i + 1 < 64) SOLVE_LD(i + 1);
;             float p0 = 0.f, p1 = 0.f;
; #pragma unroll
;             for (int a4 = 0; a4 < (i + 15) / 16; ++a4) { const f32x4 lv = lq[i % 3][a4];
;                 p0 = __builtin_fmaf(lv.x, t[4 * a4], p0); p1 = __builtin_fmaf(lv.y, t[4 * a4 + 1], p1); p0 = __builtin_fmaf(lv.z, t[4 * a4 + 2], p0); p1 = __builtin_fmaf(lv.w, t[4 * a4 + 3], p1); }
;             float p = quad_sum(p0 + p1);
;             const float ti = (i == j ? 1.f : 0.f) - p;
;             if (q == (i & 3)) t[i >> 2] = ti;
;             if ((i & 7) == 3 && !(pflg & 64)) {
;                 constexpr int kk = 0; const int k8 = i >> 3, b = w + 8 * (k8 & 1); v4u f; int off; (void)kk;
;                 if (k8 < 2)      { f = frag16_rm(lds + L_KN, QS_, b >> 2, b & 3, lane); off = B_KA + b * 1024; }
;                 else if (k8 < 4) { f = frag16_rm(lds + L_QN, QS_, b >> 2, b & 3, lane); off = B_QA + b * 1024; }
;                 else if (k8 < 6) { f = frag16_tr(lds + L_KN, QS_, b >> 1, b & 1, lane); off = B_KT + b * 1024; }
;                 else             { f = frag16_rm(lds + (k8 == 6 ? L_AF : L_AB), AS_, w >> 1, w & 1, lane); off = (k8 == 6 ? B_AF : B_AB) + w * 1024; }
;                 *(v4u*)(blob + off + lane * 16) = f; }
	v_pk_fma_f32 v[14:15], v[242:243], v[238:239], v[14:15]
	s_nop 0
	v_pk_fma_f32 v[14:15], v[244:245], 0, v[14:15] op_sel_hi:[1,0,1]
	s_nop 0
	v_add_f32_e32 v14, v14, v15
	v_add_u32_e32 v15, s71, v61
	ds_read_u16 v16, v15 offset:816
	ds_read_u16 v17, v15 offset:4352
	ds_read_u16 v239, v15 offset:4624
	ds_read_u16 v240, v15 offset:4896
	ds_read_u16 v241, v15 offset:5168
	ds_read_b128 v[38:41], v56 offset:9504
	ds_read_u16 v242, v15
	ds_read_u16 v243, v15 offset:272
	ds_read_u16 v15, v15 offset:544
	v_add_f32_dpp v14, v14, v14 quad_perm:[1,0,3,2] row_mask:0xf bank_mask:0xf bound_ctrl:1
	s_waitcnt lgkmcnt(4)
	v_perm_b32 v241, v241, v240, s33
	v_perm_b32 v240, v239, v17, s33
	v_add_f32_dpp v14, v14, v14 quad_perm:[2,3,0,1] row_mask:0xf bank_mask:0xf bound_ctrl:1
	v_sub_f32_e32 v14, v147, v14
	s_waitcnt lgkmcnt(0)
	v_perm_b32 v239, v16, v15, s33
	v_add_co_u32_e32 v16, vcc, s40, v8
	v_cndmask_b32_e64 v14, v238, v14, s[92:93]
	v_perm_b32 v238, v243, v242, s33
	v_addc_co_u32_e32 v17, vcc, 0, v9, vcc
	global_store_dwordx4 v[16:17], v[238:241], off offset:2048
	v_pk_fma_f32 v[16:17], v[42:43], v[2:3], 0 op_sel_hi:[1,1,0]
	v_mov_b32_e32 v15, v131
	v_pk_fma_f32 v[16:17], v[44:45], v[4:5], v[16:17]
	ds_read_b128 v[238:241], v56 offset:9728
	ds_read_b128 v[242:245], v56 offset:9744
	ds_read_b128 v[246:249], v56 offset:9760
	v_pk_fma_f32 v[16:17], v[230:231], v[10:11], v[16:17]
	s_nop 0
	v_pk_fma_f32 v[16:17], v[232:233], v[12:13], v[16:17]
	s_nop 0
	v_pk_fma_f32 v[16:17], v[234:235], v[14:15], v[16:17]
	s_nop 0
	v_pk_fma_f32 v[16:17], v[236:237], 0, v[16:17] op_sel_hi:[1,0,1]
	s_nop 0
	v_add_f32_e32 v15, v16, v17
	s_nop 1
	v_add_f32_dpp v15, v15, v15 quad_perm:[1,0,3,2] row_mask:0xf bank_mask:0xf bound_ctrl:1
	s_nop 1
	v_add_f32_dpp v15, v15, v15 quad_perm:[2,3,0,1] row_mask:0xf bank_mask:0xf bound_ctrl:1
	v_sub_f32_e32 v15, v148, v15
	v_cndmask_b32_e64 v15, 0, v15, s[86:87]
	v_pk_fma_f32 v[16:17], v[34:35], v[2:3], 0 op_sel_hi:[1,1,0]
	ds_read_b128 v[42:45], v56 offset:9984
	ds_read_b128 v[230:233], v56 offset:10000
	ds_read_b128 v[234:237], v56 offset:10016
	v_pk_fma_f32 v[16:17], v[36:37], v[4:5], v[16:17]
	s_nop 0
	v_pk_fma_f32 v[16:17], v[46:47], v[10:11], v[16:17]
	s_nop 0
	v_pk_fma_f32 v[16:17], v[48:49], v[12:13], v[16:17]
	s_nop 0
	v_pk_fma_f32 v[16:17], v[38:39], v[14:15], v[16:17]
	s_nop 0
	v_pk_fma_f32 v[16:17], v[40:41], 0, v[16:17] op_sel_hi:[1,0,1]
	s_nop 0
	v_add_f32_e32 v16, v16, v17
	s_nop 1
	v_add_f32_dpp v16, v16, v16 quad_perm:[1,0,3,2] row_mask:0xf bank_mask:0xf bound_ctrl:1
	s_nop 1
	v_add_f32_dpp v16, v16, v16 quad_perm:[2,3,0,1] row_mask:0xf bank_mask:0xf bound_ctrl:1
	v_sub_f32_e32 v16, v149, v16
	v_cndmask_b32_e64 v15, v15, v16, s[88:89]
	s_waitcnt lgkmcnt(5)
	v_pk_fma_f32 v[16:17], v[238:239], v[2:3], 0 op_sel_hi:[1,1,0]
	ds_read_b128 v[34:37], v56 offset:10240
	ds_read_b128 v[38:41], v56 offset:10256
	ds_read_b128 v[46:49], v56 offset:10272
	v_pk_fma_f32 v[16:17], v[240:241], v[4:5], v[16:17]
	s_waitcnt lgkmcnt(7)
	v_pk_fma_f32 v[16:17], v[242:243], v[10:11], v[16:17]
	s_nop 0
	v_pk_fma_f32 v[16:17], v[244:245], v[12:13], v[16:17]
	s_waitcnt lgkmcnt(6)
	v_pk_fma_f32 v[16:17], v[246:247], v[14:15], v[16:17]
	s_nop 0
	v_pk_fma_f32 v[16:17], v[248:249], 0, v[16:17] op_sel_hi:[1,0,1]
	s_nop 0
	v_add_f32_e32 v16, v16, v17
	s_nop 1
	v_add_f32_dpp v16, v16, v16 quad_perm:[1,0,3,2] row_mask:0xf bank_mask:0xf bound_ctrl:1
	s_nop 1
	v_add_f32_dpp v16, v16, v16 quad_perm:[2,3,0,1] row_mask:0xf bank_mask:0xf bound_ctrl:1
	v_sub_f32_e32 v16, v150, v16
	v_cndmask_b32_e64 v15, v15, v16, s[90:91]
	s_waitcnt lgkmcnt(5)
	v_pk_fma_f32 v[16:17], v[42:43], v[2:3], 0 op_sel_hi:[1,1,0]
	ds_read_b128 v[238:241], v56 offset:10496
	ds_read_b128 v[242:245], v56 offset:10512
	ds_read_b128 v[246:249], v56 offset:10528
	v_pk_fma_f32 v[16:17], v[44:45], v[4:5], v[16:17]
	s_waitcnt lgkmcnt(7)
	v_pk_fma_f32 v[16:17], v[230:231], v[10:11], v[16:17]
	s_nop 0
	v_pk_fma_f32 v[16:17], v[232:233], v[12:13], v[16:17]
	s_waitcnt lgkmcnt(6)
	v_pk_fma_f32 v[16:17], v[234:235], v[14:15], v[16:17]
	s_nop 0
	v_pk_fma_f32 v[16:17], v[236:237], 0, v[16:17] op_sel_hi:[1,0,1]
	s_nop 0
	v_add_f32_e32 v16, v16, v17
	s_nop 1
	v_add_f32_dpp v16, v16, v16 quad_perm:[1,0,3,2] row_mask:0xf bank_mask:0xf bound_ctrl:1
	s_nop 1
	v_add_f32_dpp v16, v16, v16 quad_perm:[2,3,0,1] row_mask:0xf bank_mask:0xf bound_ctrl:1
	v_sub_f32_e32 v16, v151, v16
	v_cndmask_b32_e64 v15, v15, v16, s[92:93]
	s_waitcnt lgkmcnt(5)
	v_pk_fma_f32 v[16:17], v[34:35], v[2:3], 0 op_sel_hi:[1,1,0]
	ds_read_b128 v[42:45], v56 offset:10752
	ds_read_b128 v[230:233], v56 offset:10768
	ds_read_b128 v[234:237], v56 offset:10784
	v_pk_fma_f32 v[16:17], v[36:37], v[4:5], v[16:17]
	s_waitcnt lgkmcnt(7)
	v_pk_fma_f32 v[16:17], v[38:39], v[10:11], v[16:17]
	s_nop 0
	v_pk_fma_f32 v[16:17], v[40:41], v[12:13], v[16:17]
	s_waitcnt lgkmcnt(6)
	v_pk_fma_f32 v[16:17], v[46:47], v[14:15], v[16:17]
	s_nop 0
	v_pk_fma_f32 v[16:17], v[48:49], 0, v[16:17] op_sel_hi:[1,0,1]
	s_nop 0
	v_add_f32_e32 v16, v16, v17
	s_nop 1
	v_add_f32_dpp v16, v16, v16 quad_perm:[1,0,3,2] row_mask:0xf bank_mask:0xf bound_ctrl:1
	s_nop 1
	v_add_f32_dpp v16, v16, v16 quad_perm:[2,3,0,1] row_mask:0xf bank_mask:0xf bound_ctrl:1
	v_sub_f32_e32 v16, v152, v16
	v_cndmask_b32_e64 v16, 0, v16, s[86:87]
	s_waitcnt lgkmcnt(5)
	v_pk_fma_f32 v[238:239], v[238:239], v[2:3], 0 op_sel_hi:[1,1,0]
	v_mov_b32_e32 v17, v131
	v_pk_fma_f32 v[238:239], v[240:241], v[4:5], v[238:239]
	ds_read_b128 v[34:37], v56 offset:11008
	ds_read_b128 v[38:41], v56 offset:11024
	ds_read_b128 v[46:49], v56 offset:11040
	s_waitcnt lgkmcnt(7)
; #define SOLVE_LD(i_) do { _Pragma("unroll") for (int a4 = 0; a4 < ((i_) + 15) / 16; ++a4) lq[(i_) % 3][a4] = *(const LAS f32x4*)(LP + (i_) * 64 + 4 * a4); } while (0)
; __device__ __forceinline__ void gdn_prep_phase(LAS unsigned char* lds, const GdnPrepArgs& A, int bid, int G, const unsigned char* zero_page) {
;     ...
;         SOLVE_LD(0); SOLVE_LD(1);
; #pragma unroll
;         for (int i = 0; i < 64; ++i) {
;             if (i + 2 < 48) SOLVE_LD(i + 2);
;             else if (i + 1 >= 48 && i + 1 < 64) SOLVE_LD(i + 1);
;             float p0 = 0.f, p1 = 0.f;
; #pragma unroll
;             for (int a4 = 0; a4 < (i + 15) / 16; ++a4) { const f32x4 lv = lq[i % 3][a4];
;                 p0 = __builtin_fmaf(lv.x, t[4 * a4], p0); p1 = __builtin_fmaf(lv.y, t[4 * a4 + 1], p1); p0 = __builtin_fmaf(lv.z, t[4 * a4 + 2], p0); p1 = __builtin_fmaf(lv.w, t[4 * a4 + 3], p1); }
;             float p = quad_sum(p0 + p1);
;             const float ti = (i == j ? 1.f : 0.f) - p;
;             if (q == (i & 3)) t[i >> 2] = ti;
;             if ((i & 7) == 3 && !(pflg & 64)) {
;                 constexpr int kk = 0; const int k8 = i >> 3, b = w + 8 * (k8 & 1); v4u f; int off; (void)kk;
;                 if (k8 < 2)      { f = frag16_rm(lds + L_KN, QS_, b >> 2, b & 3, lane); off = B_KA + b * 1024; }
;                 else if (k8 < 4) { f = frag16_rm(lds + L_QN, QS_, b >> 2, b & 3, lane); off = B_QA + b * 1024; }
;                 else if (k8 < 6) { f = frag16_tr(lds + L_KN, QS_, b >> 1, b & 1, lane); off = B_KT + b * 1024; }
;                 else             { f = frag16_rm(lds + (k8 == 6 ? L_AF : L_AB), AS_, w >> 1, w & 1, lane); off = (k8 == 6 ? B_AF : B_AB) + w * 1024; }
;                 *(v4u*)(blob + off + lane * 16) = f; }
	v_pk_fma_f32 v[238:239], v[242:243], v[10:11], v[238:239]
	s_nop 0
	v_pk_fma_f32 v[238:239], v[244:245], v[12:13], v[238:239]
	s_waitcnt lgkmcnt(6)
	v_pk_fma_f32 v[238:239], v[246:247], v[14:15], v[238:239]
	s_nop 0
	v_pk_fma_f32 v[238:239], v[248:249], v[16:17], v[238:239]
	s_nop 0
	v_add_f32_e32 v17, v238, v239
	s_nop 1
	v_add_f32_dpp v17, v17, v17 quad_perm:[1,0,3,2] row_mask:0xf bank_mask:0xf bound_ctrl:1
	s_nop 1
	v_add_f32_dpp v17, v17, v17 quad_perm:[2,3,0,1] row_mask:0xf bank_mask:0xf bound_ctrl:1
	v_sub_f32_e32 v17, v153, v17
	v_cndmask_b32_e64 v16, v16, v17, s[88:89]
	s_waitcnt lgkmcnt(5)
	v_pk_fma_f32 v[42:43], v[42:43], v[2:3], 0 op_sel_hi:[1,1,0]
	v_mov_b32_e32 v17, v131
	v_pk_fma_f32 v[42:43], v[44:45], v[4:5], v[42:43]
	ds_read_b128 v[238:241], v56 offset:11264
	ds_read_b128 v[242:245], v56 offset:11280
	ds_read_b128 v[246:249], v56 offset:11296
	s_waitcnt lgkmcnt(7)
	v_pk_fma_f32 v[42:43], v[230:231], v[10:11], v[42:43]
	s_nop 0
	v_pk_fma_f32 v[42:43], v[232:233], v[12:13], v[42:43]
	s_waitcnt lgkmcnt(6)
	v_pk_fma_f32 v[42:43], v[234:235], v[14:15], v[42:43]
	s_nop 0
	v_pk_fma_f32 v[42:43], v[236:237], v[16:17], v[42:43]
	s_nop 0
	v_add_f32_e32 v17, v42, v43
	s_nop 1
	v_add_f32_dpp v17, v17, v17 quad_perm:[1,0,3,2] row_mask:0xf bank_mask:0xf bound_ctrl:1
	s_nop 1
	v_add_f32_dpp v17, v17, v17 quad_perm:[2,3,0,1] row_mask:0xf bank_mask:0xf bound_ctrl:1
	v_sub_f32_e32 v17, v154, v17
	v_cndmask_b32_e64 v16, v16, v17, s[90:91]
	s_waitcnt lgkmcnt(5)
	v_pk_fma_f32 v[34:35], v[34:35], v[2:3], 0 op_sel_hi:[1,1,0]
	v_mov_b32_e32 v17, v131
	v_pk_fma_f32 v[34:35], v[36:37], v[4:5], v[34:35]
	ds_read_b128 v[42:45], v56 offset:11520
	ds_read_b128 v[230:233], v56 offset:11536
	s_waitcnt lgkmcnt(6)
	v_pk_fma_f32 v[34:35], v[38:39], v[10:11], v[34:35]
	v_add_u32_e32 v38, s72, v61
	v_pk_fma_f32 v[34:35], v[40:41], v[12:13], v[34:35]
	v_add_co_u32_e32 v32, vcc, s40, v32
	s_waitcnt lgkmcnt(5)
	v_pk_fma_f32 v[34:35], v[46:47], v[14:15], v[34:35]
	v_addc_co_u32_e32 v33, vcc, 0, v33, vcc
	v_pk_fma_f32 v[34:35], v[48:49], v[16:17], v[34:35]
	s_nop 0
	v_add_f32_e32 v17, v34, v35
	ds_read_u16 v39, v38 offset:816
	ds_read_u16 v40, v38 offset:4352
	ds_read_u16 v46, v38 offset:4624
	ds_read_u16 v41, v38 offset:4896
	ds_read_u16 v47, v38 offset:5168
	ds_read_b128 v[34:37], v56 offset:11552
	ds_read_u16 v48, v38
	ds_read_u16 v49, v38 offset:272
	ds_read_u16 v38, v38 offset:544
	v_add_f32_dpp v17, v17, v17 quad_perm:[1,0,3,2] row_mask:0xf bank_mask:0xf bound_ctrl:1
	s_waitcnt lgkmcnt(4)
	v_perm_b32 v41, v47, v41, s33
	v_perm_b32 v40, v46, v40, s33
	v_add_f32_dpp v17, v17, v17 quad_perm:[2,3,0,1] row_mask:0xf bank_mask:0xf bound_ctrl:1
	v_sub_f32_e32 v17, v155, v17
	v_cndmask_b32_e64 v16, v16, v17, s[92:93]
	s_waitcnt lgkmcnt(0)
	v_perm_b32 v39, v39, v38, s33
	v_perm_b32 v38, v49, v48, s33
	global_store_dwordx4 v[32:33], v[38:41], off offset:2048
	v_pk_fma_f32 v[32:33], v[238:239], v[2:3], 0 op_sel_hi:[1,1,0]
	v_mov_b32_e32 v17, v131
	v_pk_fma_f32 v[32:33], v[240:241], v[4:5], v[32:33]
	ds_read_b128 v[38:41], v56 offset:11776
	ds_read_b128 v[46:49], v56 offset:11792
	ds_read_b128 v[234:237], v56 offset:11808
	v_pk_fma_f32 v[32:33], v[242:243], v[10:11], v[32:33]
	s_nop 0
	v_pk_fma_f32 v[32:33], v[244:245], v[12:13], v[32:33]
	s_nop 0
	v_pk_fma_f32 v[32:33], v[246:247], v[14:15], v[32:33]
	s_nop 0
	v_pk_fma_f32 v[32:33], v[248:249], v[16:17], v[32:33]
	s_nop 0
	v_add_f32_e32 v17, v32, v33
	s_nop 1
	v_add_f32_dpp v17, v17, v17 quad_perm:[1,0,3,2] row_mask:0xf bank_mask:0xf bound_ctrl:1
	s_nop 1
	v_add_f32_dpp v17, v17, v17 quad_perm:[2,3,0,1] row_mask:0xf bank_mask:0xf bound_ctrl:1
	v_sub_f32_e32 v17, v156, v17
	v_cndmask_b32_e64 v17, 0, v17, s[86:87]
	v_pk_fma_f32 v[32:33], v[42:43], v[2:3], 0 op_sel_hi:[1,1,0]
	ds_read_b128 v[238:241], v56 offset:12032
	ds_read_b128 v[242:245], v56 offset:12048
	ds_read_b128 v[246:249], v56 offset:12064
	v_pk_fma_f32 v[32:33], v[44:45], v[4:5], v[32:33]
	s_nop 0
	v_pk_fma_f32 v[32:33], v[230:231], v[10:11], v[32:33]
	s_nop 0
	v_pk_fma_f32 v[32:33], v[232:233], v[12:13], v[32:33]
	s_nop 0
	v_pk_fma_f32 v[32:33], v[34:35], v[14:15], v[32:33]
	s_nop 0
	v_pk_fma_f32 v[32:33], v[36:37], v[16:17], v[32:33]
	s_nop 0
	v_add_f32_e32 v32, v32, v33
	s_nop 1
	v_add_f32_dpp v32, v32, v32 quad_perm:[1,0,3,2] row_mask:0xf bank_mask:0xf bound_ctrl:1
	s_nop 1
	v_add_f32_dpp v32, v32, v32 quad_perm:[2,3,0,1] row_mask:0xf bank_mask:0xf bound_ctrl:1
	v_sub_f32_e32 v32, v157, v32
	v_cndmask_b32_e64 v17, v17, v32, s[88:89]
	s_waitcnt lgkmcnt(5)
	v_pk_fma_f32 v[32:33], v[38:39], v[2:3], 0 op_sel_hi:[1,1,0]
	s_nop 0
	v_pk_fma_f32 v[32:33], v[40:41], v[4:5], v[32:33]
	s_waitcnt lgkmcnt(4)
	v_pk_fma_f32 v[32:33], v[46:47], v[10:11], v[32:33]
	s_nop 0
	v_pk_fma_f32 v[32:33], v[48:49], v[12:13], v[32:33]
	s_waitcnt lgkmcnt(3)
	v_pk_fma_f32 v[32:33], v[234:235], v[14:15], v[32:33]
	s_nop 0
	v_pk_fma_f32 v[32:33], v[236:237], v[16:17], v[32:33]
	s_nop 0
	v_add_f32_e32 v32, v32, v33
	s_nop 1
	v_add_f32_dpp v32, v32, v32 quad_perm:[1,0,3,2] row_mask:0xf bank_mask:0xf bound_ctrl:1
	s_nop 1
	v_add_f32_dpp v32, v32, v32 quad_perm:[2,3,0,1] row_mask:0xf bank_mask:0xf bound_ctrl:1
	v_sub_f32_e32 v32, v158, v32
	v_cndmask_b32_e64 v17, v17, v32, s[90:91]
	s_waitcnt lgkmcnt(2)
	v_pk_fma_f32 v[44:45], v[238:239], v[2:3], 0 op_sel_hi:[1,1,0]
	ds_read_b128 v[32:35], v56 offset:12288
	ds_read_b128 v[36:39], v56 offset:12304
	ds_read_b128 v[40:43], v56 offset:12320
	v_pk_fma_f32 v[44:45], v[240:241], v[4:5], v[44:45]
	s_waitcnt lgkmcnt(4)
	v_pk_fma_f32 v[44:45], v[242:243], v[10:11], v[44:45]
	s_nop 0
	v_pk_fma_f32 v[44:45], v[244:245], v[12:13], v[44:45]
	s_waitcnt lgkmcnt(3)
; #define SOLVE_LD(i_) do { _Pragma("unroll") for (int a4 = 0; a4 < ((i_) + 15) / 16; ++a4) lq[(i_) % 3][a4] = *(const LAS f32x4*)(LP + (i_) * 64 + 4 * a4); } while (0)
; __device__ __forceinline__ void gdn_prep_phase(LAS unsigned char* lds, const GdnPrepArgs& A, int bid, int G, const unsigned char* zero_page) {
;     ...
;         SOLVE_LD(0); SOLVE_LD(1);
; #pragma unroll
;         for (int i = 0; i < 64; ++i) {
;             if (i + 2 < 48) SOLVE_LD(i + 2);
;             else if (i + 1 >= 48 && i + 1 < 64) SOLVE_LD(i + 1);
;             float p0 = 0.f, p1 = 0.f;
; #pragma unroll
;             for (int a4 = 0; a4 < (i + 15) / 16; ++a4) { const f32x4 lv = lq[i % 3][a4];
;                 p0 = __builtin_fmaf(lv.x, t[4 * a4], p0); p1 = __builtin_fmaf(lv.y, t[4 * a4 + 1], p1); p0 = __builtin_fmaf(lv.z, t[4 * a4 + 2], p0); p1 = __builtin_fmaf(lv.w, t[4 * a4 + 3], p1); }
;             float p = quad_sum(p0 + p1);
;             const float ti = (i == j ? 1.f : 0.f) - p;
;             if (q == (i & 3)) t[i >> 2] = ti;
;             if ((i & 7) == 3 && !(pflg & 64)) {
;                 constexpr int kk = 0; const int k8 = i >> 3, b = w + 8 * (k8 & 1); v4u f; int off; (void)kk;
;                 if (k8 < 2)      { f = frag16_rm(lds + L_KN, QS_, b >> 2, b & 3, lane); off = B_KA + b * 1024; }
;                 else if (k8 < 4) { f = frag16_rm(lds + L_QN, QS_, b >> 2, b & 3, lane); off = B_QA + b * 1024; }
;                 else if (k8 < 6) { f = frag16_tr(lds + L_KN, QS_, b >> 1, b & 1, lane); off = B_KT + b * 1024; }
;                 else             { f = frag16_rm(lds + (k8 == 6 ? L_AF : L_AB), AS_, w >> 1, w & 1, lane); off = (k8 == 6 ? B_AF : B_AB) + w * 1024; }
;                 *(v4u*)(blob + off + lane * 16) = f; }
	v_pk_fma_f32 v[44:45], v[246:247], v[14:15], v[44:45]
	s_nop 0
	v_pk_fma_f32 v[44:45], v[248:249], v[16:17], v[44:45]
	s_nop 0
	v_add_f32_e32 v44, v44, v45
	s_nop 1
	v_add_f32_dpp v44, v44, v44 quad_perm:[1,0,3,2] row_mask:0xf bank_mask:0xf bound_ctrl:1
	s_nop 1
	v_add_f32_dpp v44, v44, v44 quad_perm:[2,3,0,1] row_mask:0xf bank_mask:0xf bound_ctrl:1
	v_sub_f32_e32 v44, v159, v44
	v_cndmask_b32_e64 v17, v17, v44, s[92:93]
	s_waitcnt lgkmcnt(2)
	v_pk_fma_f32 v[32:33], v[32:33], v[2:3], 0 op_sel_hi:[1,1,0]
	ds_read_b128 v[44:47], v56 offset:12544
	ds_read_b128 v[230:233], v56 offset:12560
	ds_read_b128 v[234:237], v56 offset:12576
	ds_read_b128 v[238:241], v56 offset:12592
	v_pk_fma_f32 v[32:33], v[34:35], v[4:5], v[32:33]
	s_waitcnt lgkmcnt(5)
	v_pk_fma_f32 v[32:33], v[36:37], v[10:11], v[32:33]
	s_nop 0
	v_pk_fma_f32 v[32:33], v[38:39], v[12:13], v[32:33]
	s_waitcnt lgkmcnt(4)
	v_pk_fma_f32 v[32:33], v[40:41], v[14:15], v[32:33]
	s_nop 0
	v_pk_fma_f32 v[32:33], v[42:43], v[16:17], v[32:33]
	s_nop 0
	v_add_f32_e32 v32, v32, v33
	s_nop 1
	v_add_f32_dpp v32, v32, v32 quad_perm:[1,0,3,2] row_mask:0xf bank_mask:0xf bound_ctrl:1
	s_nop 1
	v_add_f32_dpp v32, v32, v32 quad_perm:[2,3,0,1] row_mask:0xf bank_mask:0xf bound_ctrl:1
	v_sub_f32_e32 v32, v160, v32
	v_cndmask_b32_e64 v48, 0, v32, s[86:87]
	s_waitcnt lgkmcnt(3)
	v_pk_fma_f32 v[44:45], v[44:45], v[2:3], 0 op_sel_hi:[1,1,0]
	ds_read_b128 v[32:35], v56 offset:12800
	ds_read_b128 v[36:39], v56 offset:12816
	ds_read_b128 v[40:43], v56 offset:12832
	ds_read_b128 v[242:245], v56 offset:12848
	v_pk_fma_f32 v[44:45], v[46:47], v[4:5], v[44:45]
	v_mov_b32_e32 v49, v131
	s_waitcnt lgkmcnt(6)
	v_pk_fma_f32 v[44:45], v[230:231], v[10:11], v[44:45]
	s_nop 0
	v_pk_fma_f32 v[44:45], v[232:233], v[12:13], v[44:45]
	s_waitcnt lgkmcnt(5)
	v_pk_fma_f32 v[44:45], v[234:235], v[14:15], v[44:45]
	s_nop 0
	v_pk_fma_f32 v[44:45], v[236:237], v[16:17], v[44:45]
	s_waitcnt lgkmcnt(4)
	v_pk_fma_f32 v[44:45], v[238:239], v[48:49], v[44:45]
	s_nop 0
	v_pk_fma_f32 v[44:45], v[240:241], 0, v[44:45] op_sel_hi:[1,0,1]
	s_nop 0
	v_add_f32_e32 v44, v44, v45
	s_nop 1
	v_add_f32_dpp v44, v44, v44 quad_perm:[1,0,3,2] row_mask:0xf bank_mask:0xf bound_ctrl:1
	s_nop 1
	v_add_f32_dpp v44, v44, v44 quad_perm:[2,3,0,1] row_mask:0xf bank_mask:0xf bound_ctrl:1
	v_sub_f32_e32 v44, v161, v44
	v_cndmask_b32_e64 v48, v48, v44, s[88:89]
	s_waitcnt lgkmcnt(3)
	v_pk_fma_f32 v[32:33], v[32:33], v[2:3], 0 op_sel_hi:[1,1,0]
	ds_read_b128 v[44:47], v56 offset:13056
	ds_read_b128 v[230:233], v56 offset:13072
	ds_read_b128 v[234:237], v56 offset:13088
	ds_read_b128 v[238:241], v56 offset:13104
	v_pk_fma_f32 v[32:33], v[34:35], v[4:5], v[32:33]
	s_waitcnt lgkmcnt(6)
	v_pk_fma_f32 v[32:33], v[36:37], v[10:11], v[32:33]
	s_nop 0
	v_pk_fma_f32 v[32:33], v[38:39], v[12:13], v[32:33]
	s_waitcnt lgkmcnt(5)
	v_pk_fma_f32 v[32:33], v[40:41], v[14:15], v[32:33]
	s_nop 0
	v_pk_fma_f32 v[32:33], v[42:43], v[16:17], v[32:33]
	s_waitcnt lgkmcnt(4)
	v_pk_fma_f32 v[32:33], v[242:243], v[48:49], v[32:33]
	s_nop 0
	v_pk_fma_f32 v[32:33], v[244:245], 0, v[32:33] op_sel_hi:[1,0,1]
	s_nop 0
	v_add_f32_e32 v32, v32, v33
	s_nop 1
	v_add_f32_dpp v32, v32, v32 quad_perm:[1,0,3,2] row_mask:0xf bank_mask:0xf bound_ctrl:1
	s_nop 1
	v_add_f32_dpp v32, v32, v32 quad_perm:[2,3,0,1] row_mask:0xf bank_mask:0xf bound_ctrl:1
	v_sub_f32_e32 v32, v162, v32
	v_cndmask_b32_e64 v32, v48, v32, s[90:91]
	s_waitcnt lgkmcnt(3)
	v_pk_fma_f32 v[42:43], v[44:45], v[2:3], 0 op_sel_hi:[1,1,0]
	v_mov_b32_e32 v33, v131
	v_pk_fma_f32 v[42:43], v[46:47], v[4:5], v[42:43]
	ds_read_b128 v[34:37], v56 offset:13312
	ds_read_b128 v[38:41], v56 offset:13328
	ds_read_b128 v[242:245], v56 offset:13344
	ds_read_b128 v[246:249], v56 offset:13360
	s_waitcnt lgkmcnt(6)
	v_pk_fma_f32 v[42:43], v[230:231], v[10:11], v[42:43]
	s_mov_b32 s40, 0xe000
	v_pk_fma_f32 v[42:43], v[232:233], v[12:13], v[42:43]
	v_add_co_u32_e32 v46, vcc, s40, v8
	s_waitcnt lgkmcnt(5)
	v_pk_fma_f32 v[42:43], v[234:235], v[14:15], v[42:43]
	v_addc_co_u32_e32 v47, vcc, 0, v9, vcc
	v_pk_fma_f32 v[42:43], v[236:237], v[16:17], v[42:43]
	s_waitcnt lgkmcnt(4)
	v_pk_fma_f32 v[42:43], v[238:239], v[32:33], v[42:43]
	s_nop 0
	v_pk_fma_f32 v[42:43], v[240:241], 0, v[42:43] op_sel_hi:[1,0,1]
	s_nop 0
	v_add_f32_e32 v33, v42, v43
	ds_read_b64 v[42:43], v185
	ds_read_b64 v[44:45], v186
	v_add_f32_dpp v33, v33, v33 quad_perm:[1,0,3,2] row_mask:0xf bank_mask:0xf bound_ctrl:1
	s_waitcnt lgkmcnt(0)
	global_store_dwordx4 v[46:47], v[42:45], off offset:2048
	v_add_f32_dpp v33, v33, v33 quad_perm:[2,3,0,1] row_mask:0xf bank_mask:0xf bound_ctrl:1
	v_sub_f32_e32 v33, v163, v33
	v_cndmask_b32_e64 v32, v32, v33, s[92:93]
	v_pk_fma_f32 v[34:35], v[34:35], v[2:3], 0 op_sel_hi:[1,1,0]
	v_mov_b32_e32 v33, v131
	v_pk_fma_f32 v[34:35], v[36:37], v[4:5], v[34:35]
	ds_read_b128 v[42:45], v56 offset:13568
	ds_read_b128 v[46:49], v56 offset:13584
	ds_read_b128 v[230:233], v56 offset:13600
	ds_read_b128 v[234:237], v56 offset:13616
	v_pk_fma_f32 v[34:35], v[38:39], v[10:11], v[34:35]
	s_nop 0
	v_pk_fma_f32 v[34:35], v[40:41], v[12:13], v[34:35]
	s_nop 0
	v_pk_fma_f32 v[34:35], v[242:243], v[14:15], v[34:35]
	s_nop 0
	v_pk_fma_f32 v[34:35], v[244:245], v[16:17], v[34:35]
	s_nop 0
	v_pk_fma_f32 v[34:35], v[246:247], v[32:33], v[34:35]
	s_nop 0
	v_pk_fma_f32 v[34:35], v[248:249], 0, v[34:35] op_sel_hi:[1,0,1]
	s_nop 0
	v_add_f32_e32 v33, v34, v35
	s_nop 1
	v_add_f32_dpp v33, v33, v33 quad_perm:[1,0,3,2] row_mask:0xf bank_mask:0xf bound_ctrl:1
	s_nop 1
	v_add_f32_dpp v33, v33, v33 quad_perm:[2,3,0,1] row_mask:0xf bank_mask:0xf bound_ctrl:1
	v_sub_f32_e32 v33, v173, v33
	v_cndmask_b32_e64 v33, 0, v33, s[86:87]
	s_waitcnt lgkmcnt(3)
; #define SOLVE_LD(i_) do { _Pragma("unroll") for (int a4 = 0; a4 < ((i_) + 15) / 16; ++a4) lq[(i_) % 3][a4] = *(const LAS f32x4*)(LP + (i_) * 64 + 4 * a4); } while (0)
; __device__ __forceinline__ void gdn_prep_phase(LAS unsigned char* lds, const GdnPrepArgs& A, int bid, int G, const unsigned char* zero_page) {
;     ...
;         SOLVE_LD(0); SOLVE_LD(1);
; #pragma unroll
;         for (int i = 0; i < 64; ++i) {
;             if (i + 2 < 48) SOLVE_LD(i + 2);
;             else if (i + 1 >= 48 && i + 1 < 64) SOLVE_LD(i + 1);
;             float p0 = 0.f, p1 = 0.f;
; #pragma unroll
;             for (int a4 = 0; a4 < (i + 15) / 16; ++a4) { const f32x4 lv = lq[i % 3][a4];
;                 p0 = __builtin_fmaf(lv.x, t[4 * a4], p0); p1 = __builtin_fmaf(lv.y, t[4 * a4 + 1], p1); p0 = __builtin_fmaf(lv.z, t[4 * a4 + 2], p0); p1 = __builtin_fmaf(lv.w, t[4 * a4 + 3], p1); }
;             float p = quad_sum(p0 + p1);
;             const float ti = (i == j ? 1.f : 0.f) - p;
;             if (q == (i & 3)) t[i >> 2] = ti;
;             if ((i & 7) == 3 && !(pflg & 64)) {
;                 constexpr int kk = 0; const int k8 = i >> 3, b = w + 8 * (k8 & 1); v4u f; int off; (void)kk;
;                 if (k8 < 2)      { f = frag16_rm(lds + L_KN, QS_, b >> 2, b & 3, lane); off = B_KA + b * 1024; }
;                 else if (k8 < 4) { f = frag16_rm(lds + L_QN, QS_, b >> 2, b & 3, lane); off = B_QA + b * 1024; }
;                 else if (k8 < 6) { f = frag16_tr(lds + L_KN, QS_, b >> 1, b & 1, lane); off = B_KT + b * 1024; }
;                 else             { f = frag16_rm(lds + (k8 == 6 ? L_AF : L_AB), AS_, w >> 1, w & 1, lane); off = (k8 == 6 ? B_AF : B_AB) + w * 1024; }
;                 *(v4u*)(blob + off + lane * 16) = f; }
	v_pk_fma_f32 v[42:43], v[42:43], v[2:3], 0 op_sel_hi:[1,1,0]
	ds_read_b128 v[34:37], v56 offset:13824
	ds_read_b128 v[38:41], v56 offset:13840
	ds_read_b128 v[238:241], v56 offset:13856
	ds_read_b128 v[242:245], v56 offset:13872
	v_pk_fma_f32 v[42:43], v[44:45], v[4:5], v[42:43]
	s_waitcnt lgkmcnt(6)
	v_pk_fma_f32 v[42:43], v[46:47], v[10:11], v[42:43]
	s_nop 0
	v_pk_fma_f32 v[42:43], v[48:49], v[12:13], v[42:43]
	s_waitcnt lgkmcnt(5)
	v_pk_fma_f32 v[42:43], v[230:231], v[14:15], v[42:43]
	s_nop 0
	v_pk_fma_f32 v[42:43], v[232:233], v[16:17], v[42:43]
	s_waitcnt lgkmcnt(4)
	v_pk_fma_f32 v[42:43], v[234:235], v[32:33], v[42:43]
	s_nop 0
	v_pk_fma_f32 v[42:43], v[236:237], 0, v[42:43] op_sel_hi:[1,0,1]
	s_nop 0
	v_add_f32_e32 v42, v42, v43
	s_nop 1
	v_add_f32_dpp v42, v42, v42 quad_perm:[1,0,3,2] row_mask:0xf bank_mask:0xf bound_ctrl:1
	s_nop 1
	v_add_f32_dpp v42, v42, v42 quad_perm:[2,3,0,1] row_mask:0xf bank_mask:0xf bound_ctrl:1
	v_sub_f32_e32 v42, v174, v42
	v_cndmask_b32_e64 v33, v33, v42, s[88:89]
	s_waitcnt lgkmcnt(3)
	v_pk_fma_f32 v[34:35], v[34:35], v[2:3], 0 op_sel_hi:[1,1,0]
	ds_read_b128 v[42:45], v56 offset:14080
	ds_read_b128 v[46:49], v56 offset:14096
	ds_read_b128 v[230:233], v56 offset:14112
	ds_read_b128 v[234:237], v56 offset:14128
	v_pk_fma_f32 v[34:35], v[36:37], v[4:5], v[34:35]
	s_waitcnt lgkmcnt(6)
	v_pk_fma_f32 v[34:35], v[38:39], v[10:11], v[34:35]
	s_nop 0
	v_pk_fma_f32 v[34:35], v[40:41], v[12:13], v[34:35]
	s_waitcnt lgkmcnt(5)
	v_pk_fma_f32 v[34:35], v[238:239], v[14:15], v[34:35]
	s_nop 0
	v_pk_fma_f32 v[34:35], v[240:241], v[16:17], v[34:35]
	s_waitcnt lgkmcnt(4)
	v_pk_fma_f32 v[34:35], v[242:243], v[32:33], v[34:35]
	s_nop 0
	v_pk_fma_f32 v[34:35], v[244:245], 0, v[34:35] op_sel_hi:[1,0,1]
	s_nop 0
	v_add_f32_e32 v34, v34, v35
	s_nop 1
	v_add_f32_dpp v34, v34, v34 quad_perm:[1,0,3,2] row_mask:0xf bank_mask:0xf bound_ctrl:1
	s_nop 1
	v_add_f32_dpp v34, v34, v34 quad_perm:[2,3,0,1] row_mask:0xf bank_mask:0xf bound_ctrl:1
	v_sub_f32_e32 v34, v175, v34
	v_cndmask_b32_e64 v33, v33, v34, s[90:91]
	s_waitcnt lgkmcnt(3)
	v_pk_fma_f32 v[42:43], v[42:43], v[2:3], 0 op_sel_hi:[1,1,0]
	ds_read_b128 v[34:37], v56 offset:14336
	ds_read_b128 v[38:41], v56 offset:14352
	ds_read_b128 v[238:241], v56 offset:14368
	ds_read_b128 v[242:245], v56 offset:14384
	v_pk_fma_f32 v[42:43], v[44:45], v[4:5], v[42:43]
	s_waitcnt lgkmcnt(6)
	v_pk_fma_f32 v[42:43], v[46:47], v[10:11], v[42:43]
	s_nop 0
	v_pk_fma_f32 v[42:43], v[48:49], v[12:13], v[42:43]
	s_waitcnt lgkmcnt(5)
	v_pk_fma_f32 v[42:43], v[230:231], v[14:15], v[42:43]
	s_nop 0
	v_pk_fma_f32 v[42:43], v[232:233], v[16:17], v[42:43]
	s_waitcnt lgkmcnt(4)
	v_pk_fma_f32 v[42:43], v[234:235], v[32:33], v[42:43]
	s_nop 0
	v_pk_fma_f32 v[42:43], v[236:237], 0, v[42:43] op_sel_hi:[1,0,1]
	s_nop 0
	v_add_f32_e32 v42, v42, v43
	s_nop 1
	v_add_f32_dpp v42, v42, v42 quad_perm:[1,0,3,2] row_mask:0xf bank_mask:0xf bound_ctrl:1
	s_nop 1
	v_add_f32_dpp v42, v42, v42 quad_perm:[2,3,0,1] row_mask:0xf bank_mask:0xf bound_ctrl:1
	v_sub_f32_e32 v42, v176, v42
	v_cndmask_b32_e64 v33, v33, v42, s[92:93]
	s_waitcnt lgkmcnt(3)
	v_pk_fma_f32 v[34:35], v[34:35], v[2:3], 0 op_sel_hi:[1,1,0]
	ds_read_b128 v[42:45], v56 offset:14592
	ds_read_b128 v[46:49], v56 offset:14608
	ds_read_b128 v[230:233], v56 offset:14624
	ds_read_b128 v[234:237], v56 offset:14640
	v_pk_fma_f32 v[34:35], v[36:37], v[4:5], v[34:35]
	s_waitcnt lgkmcnt(6)
	v_pk_fma_f32 v[34:35], v[38:39], v[10:11], v[34:35]
	s_nop 0
	v_pk_fma_f32 v[34:35], v[40:41], v[12:13], v[34:35]
	s_waitcnt lgkmcnt(5)
	v_pk_fma_f32 v[34:35], v[238:239], v[14:15], v[34:35]
	s_nop 0
	v_pk_fma_f32 v[34:35], v[240:241], v[16:17], v[34:35]
	s_waitcnt lgkmcnt(4)
	v_pk_fma_f32 v[34:35], v[242:243], v[32:33], v[34:35]
	s_nop 0
	v_pk_fma_f32 v[34:35], v[244:245], 0, v[34:35] op_sel_hi:[1,0,1]
	s_nop 0
	v_add_f32_e32 v34, v34, v35
	s_nop 1
	v_add_f32_dpp v34, v34, v34 quad_perm:[1,0,3,2] row_mask:0xf bank_mask:0xf bound_ctrl:1
	s_nop 1
	v_add_f32_dpp v34, v34, v34 quad_perm:[2,3,0,1] row_mask:0xf bank_mask:0xf bound_ctrl:1
	v_sub_f32_e32 v34, v177, v34
	v_cndmask_b32_e64 v246, 0, v34, s[86:87]
	s_waitcnt lgkmcnt(3)
	v_pk_fma_f32 v[42:43], v[42:43], v[2:3], 0 op_sel_hi:[1,1,0]
	ds_read_b128 v[34:37], v56 offset:14848
	ds_read_b128 v[38:41], v56 offset:14864
	ds_read_b128 v[238:241], v56 offset:14880
	ds_read_b128 v[242:245], v56 offset:14896
	v_pk_fma_f32 v[42:43], v[44:45], v[4:5], v[42:43]
	v_mov_b32_e32 v247, v131
	s_waitcnt lgkmcnt(6)
	v_pk_fma_f32 v[42:43], v[46:47], v[10:11], v[42:43]
	s_nop 0
	v_pk_fma_f32 v[42:43], v[48:49], v[12:13], v[42:43]
	s_waitcnt lgkmcnt(5)
	v_pk_fma_f32 v[42:43], v[230:231], v[14:15], v[42:43]
	s_nop 0
	v_pk_fma_f32 v[42:43], v[232:233], v[16:17], v[42:43]
	s_waitcnt lgkmcnt(4)
	v_pk_fma_f32 v[42:43], v[234:235], v[32:33], v[42:43]
	s_nop 0
	v_pk_fma_f32 v[42:43], v[236:237], v[246:247], v[42:43]
	s_nop 0
	v_add_f32_e32 v42, v42, v43
	s_nop 1
	v_add_f32_dpp v42, v42, v42 quad_perm:[1,0,3,2] row_mask:0xf bank_mask:0xf bound_ctrl:1
	s_nop 1
	v_add_f32_dpp v42, v42, v42 quad_perm:[2,3,0,1] row_mask:0xf bank_mask:0xf bound_ctrl:1
	v_sub_f32_e32 v42, v178, v42
	v_cndmask_b32_e64 v246, v246, v42, s[88:89]
	s_waitcnt lgkmcnt(3)
	v_pk_fma_f32 v[34:35], v[34:35], v[2:3], 0 op_sel_hi:[1,1,0]
	ds_read_b128 v[42:45], v56 offset:15104
	ds_read_b128 v[46:49], v56 offset:15120
	ds_read_b128 v[230:233], v56 offset:15136
	ds_read_b128 v[234:237], v56 offset:15152
	v_pk_fma_f32 v[34:35], v[36:37], v[4:5], v[34:35]
	s_waitcnt lgkmcnt(6)
	v_pk_fma_f32 v[34:35], v[38:39], v[10:11], v[34:35]
	s_nop 0
	v_pk_fma_f32 v[34:35], v[40:41], v[12:13], v[34:35]
	s_waitcnt lgkmcnt(5)
; #define SOLVE_LD(i_) do { _Pragma("unroll") for (int a4 = 0; a4 < ((i_) + 15) / 16; ++a4) lq[(i_) % 3][a4] = *(const LAS f32x4*)(LP + (i_) * 64 + 4 * a4); } while (0)
; __device__ __forceinline__ void gdn_prep_phase(LAS unsigned char* lds, const GdnPrepArgs& A, int bid, int G, const unsigned char* zero_page) {
;     ...
;         SOLVE_LD(0); SOLVE_LD(1);
; #pragma unroll
;         for (int i = 0; i < 64; ++i) {
;             if (i + 2 < 48) SOLVE_LD(i + 2);
;             else if (i + 1 >= 48 && i + 1 < 64) SOLVE_LD(i + 1);
;             float p0 = 0.f, p1 = 0.f;
; #pragma unroll
;             for (int a4 = 0; a4 < (i + 15) / 16; ++a4) { const f32x4 lv = lq[i % 3][a4];
;                 p0 = __builtin_fmaf(lv.x, t[4 * a4], p0); p1 = __builtin_fmaf(lv.y, t[4 * a4 + 1], p1); p0 = __builtin_fmaf(lv.z, t[4 * a4 + 2], p0); p1 = __builtin_fmaf(lv.w, t[4 * a4 + 3], p1); }
;             float p = quad_sum(p0 + p1);
;             const float ti = (i == j ? 1.f : 0.f) - p;
;             if (q == (i & 3)) t[i >> 2] = ti;
;             if ((i & 7) == 3 && !(pflg & 64)) {
;                 constexpr int kk = 0; const int k8 = i >> 3, b = w + 8 * (k8 & 1); v4u f; int off; (void)kk;
;                 if (k8 < 2)      { f = frag16_rm(lds + L_KN, QS_, b >> 2, b & 3, lane); off = B_KA + b * 1024; }
;                 else if (k8 < 4) { f = frag16_rm(lds + L_QN, QS_, b >> 2, b & 3, lane); off = B_QA + b * 1024; }
;                 else if (k8 < 6) { f = frag16_tr(lds + L_KN, QS_, b >> 1, b & 1, lane); off = B_KT + b * 1024; }
;                 else             { f = frag16_rm(lds + (k8 == 6 ? L_AF : L_AB), AS_, w >> 1, w & 1, lane); off = (k8 == 6 ? B_AF : B_AB) + w * 1024; }
;                 *(v4u*)(blob + off + lane * 16) = f; }
	v_pk_fma_f32 v[34:35], v[238:239], v[14:15], v[34:35]
	s_nop 0
	v_pk_fma_f32 v[34:35], v[240:241], v[16:17], v[34:35]
	s_waitcnt lgkmcnt(4)
	v_pk_fma_f32 v[34:35], v[242:243], v[32:33], v[34:35]
	s_nop 0
	v_pk_fma_f32 v[34:35], v[244:245], v[246:247], v[34:35]
	s_nop 0
	v_add_f32_e32 v34, v34, v35
	s_nop 1
	v_add_f32_dpp v34, v34, v34 quad_perm:[1,0,3,2] row_mask:0xf bank_mask:0xf bound_ctrl:1
	s_nop 1
	v_add_f32_dpp v34, v34, v34 quad_perm:[2,3,0,1] row_mask:0xf bank_mask:0xf bound_ctrl:1
	v_sub_f32_e32 v34, v179, v34
	v_cndmask_b32_e64 v34, v246, v34, s[90:91]
	s_waitcnt lgkmcnt(3)
	v_pk_fma_f32 v[40:41], v[42:43], v[2:3], 0 op_sel_hi:[1,1,0]
	ds_read_b128 v[36:39], v56 offset:15360
	ds_read_b128 v[238:241], v56 offset:15376
	ds_read_b128 v[242:245], v56 offset:15392
	ds_read_b128 v[246:249], v56 offset:15408
	v_pk_fma_f32 v[40:41], v[44:45], v[4:5], v[40:41]
	v_mov_b32_e32 v35, v131
	s_waitcnt lgkmcnt(6)
	v_pk_fma_f32 v[40:41], v[46:47], v[10:11], v[40:41]
	s_mov_b32 s40, 0x12000
	v_pk_fma_f32 v[40:41], v[48:49], v[12:13], v[40:41]
	v_add_co_u32_e32 v8, vcc, s40, v8
	s_waitcnt lgkmcnt(5)
	v_pk_fma_f32 v[40:41], v[230:231], v[14:15], v[40:41]
	v_addc_co_u32_e32 v9, vcc, 0, v9, vcc
	v_pk_fma_f32 v[40:41], v[232:233], v[16:17], v[40:41]
	s_waitcnt lgkmcnt(4)
	v_pk_fma_f32 v[40:41], v[234:235], v[32:33], v[40:41]
	s_nop 0
	v_pk_fma_f32 v[40:41], v[236:237], v[34:35], v[40:41]
	s_nop 0
	v_add_f32_e32 v35, v40, v41
	ds_read_b64 v[40:41], v187
	ds_read_b64 v[42:43], v188
	v_add_f32_dpp v35, v35, v35 quad_perm:[1,0,3,2] row_mask:0xf bank_mask:0xf bound_ctrl:1
	s_waitcnt lgkmcnt(0)
	global_store_dwordx4 v[8:9], v[40:43], off offset:2048
	v_add_f32_dpp v35, v35, v35 quad_perm:[2,3,0,1] row_mask:0xf bank_mask:0xf bound_ctrl:1
	v_sub_f32_e32 v35, v180, v35
	v_cndmask_b32_e64 v34, v34, v35, s[92:93]
	v_pk_fma_f32 v[8:9], v[36:37], v[2:3], 0 op_sel_hi:[1,1,0]
	ds_read_b128 v[40:43], v56 offset:15616
	ds_read_b128 v[44:47], v56 offset:15632
	ds_read_b128 v[230:233], v56 offset:15648
	ds_read_b128 v[234:237], v56 offset:15664
	v_pk_fma_f32 v[8:9], v[38:39], v[4:5], v[8:9]
	v_mov_b32_e32 v35, v131
	v_pk_fma_f32 v[8:9], v[238:239], v[10:11], v[8:9]
	s_nop 0
	v_pk_fma_f32 v[8:9], v[240:241], v[12:13], v[8:9]
	s_nop 0
	v_pk_fma_f32 v[8:9], v[242:243], v[14:15], v[8:9]
	s_nop 0
	v_pk_fma_f32 v[8:9], v[244:245], v[16:17], v[8:9]
	s_nop 0
	v_pk_fma_f32 v[8:9], v[246:247], v[32:33], v[8:9]
	s_nop 0
	v_pk_fma_f32 v[8:9], v[248:249], v[34:35], v[8:9]
	s_nop 0
	v_add_f32_e32 v8, v8, v9
	s_nop 1
	v_add_f32_dpp v8, v8, v8 quad_perm:[1,0,3,2] row_mask:0xf bank_mask:0xf bound_ctrl:1
	s_nop 1
	v_add_f32_dpp v8, v8, v8 quad_perm:[2,3,0,1] row_mask:0xf bank_mask:0xf bound_ctrl:1
	v_sub_f32_e32 v8, v181, v8
	v_cndmask_b32_e64 v35, 0, v8, s[86:87]
	s_waitcnt lgkmcnt(3)
	v_pk_fma_f32 v[8:9], v[40:41], v[2:3], 0 op_sel_hi:[1,1,0]
	ds_read_b128 v[36:39], v56 offset:15872
	ds_read_b128 v[238:241], v56 offset:15888
	ds_read_b128 v[242:245], v56 offset:15904
	ds_read_b128 v[246:249], v56 offset:15920
	v_pk_fma_f32 v[8:9], v[42:43], v[4:5], v[8:9]
	s_waitcnt lgkmcnt(6)
	v_pk_fma_f32 v[8:9], v[44:45], v[10:11], v[8:9]
	s_nop 0
	v_pk_fma_f32 v[8:9], v[46:47], v[12:13], v[8:9]
	s_waitcnt lgkmcnt(5)
	v_pk_fma_f32 v[8:9], v[230:231], v[14:15], v[8:9]
	s_nop 0
	v_pk_fma_f32 v[8:9], v[232:233], v[16:17], v[8:9]
	s_waitcnt lgkmcnt(4)
	v_pk_fma_f32 v[8:9], v[234:235], v[32:33], v[8:9]
	s_nop 0
	v_pk_fma_f32 v[8:9], v[236:237], v[34:35], v[8:9]
	s_nop 0
	v_add_f32_e32 v8, v8, v9
	s_nop 1
	v_add_f32_dpp v8, v8, v8 quad_perm:[1,0,3,2] row_mask:0xf bank_mask:0xf bound_ctrl:1
	s_nop 1
	v_add_f32_dpp v8, v8, v8 quad_perm:[2,3,0,1] row_mask:0xf bank_mask:0xf bound_ctrl:1
	v_sub_f32_e32 v8, v182, v8
	v_cndmask_b32_e64 v35, v35, v8, s[88:89]
	s_waitcnt lgkmcnt(3)
	v_pk_fma_f32 v[8:9], v[36:37], v[2:3], 0 op_sel_hi:[1,1,0]
	ds_read_b128 v[40:43], v56 offset:16128
	ds_read_b128 v[44:47], v56 offset:16144
	ds_read_b128 v[230:233], v56 offset:16160
	ds_read_b128 v[234:237], v56 offset:16176
	v_pk_fma_f32 v[8:9], v[38:39], v[4:5], v[8:9]
	s_waitcnt lgkmcnt(6)
	v_pk_fma_f32 v[8:9], v[238:239], v[10:11], v[8:9]
	s_nop 0
	v_pk_fma_f32 v[8:9], v[240:241], v[12:13], v[8:9]
	s_waitcnt lgkmcnt(5)
	v_pk_fma_f32 v[8:9], v[242:243], v[14:15], v[8:9]
	s_nop 0
	v_pk_fma_f32 v[8:9], v[244:245], v[16:17], v[8:9]
	s_waitcnt lgkmcnt(4)
	v_pk_fma_f32 v[8:9], v[246:247], v[32:33], v[8:9]
	s_nop 0
	v_pk_fma_f32 v[8:9], v[248:249], v[34:35], v[8:9]
	s_nop 0
	v_add_f32_e32 v8, v8, v9
	s_nop 1
	v_add_f32_dpp v8, v8, v8 quad_perm:[1,0,3,2] row_mask:0xf bank_mask:0xf bound_ctrl:1
	s_nop 1
	v_add_f32_dpp v8, v8, v8 quad_perm:[2,3,0,1] row_mask:0xf bank_mask:0xf bound_ctrl:1
	v_sub_f32_e32 v8, v183, v8
	v_cndmask_b32_e64 v35, v35, v8, s[90:91]
	s_waitcnt lgkmcnt(3)
	v_pk_fma_f32 v[8:9], v[40:41], v[2:3], 0 op_sel_hi:[1,1,0]
	s_nop 0
	v_pk_fma_f32 v[8:9], v[42:43], v[4:5], v[8:9]
	s_waitcnt lgkmcnt(2)
	v_pk_fma_f32 v[8:9], v[44:45], v[10:11], v[8:9]
	s_nop 0
	v_pk_fma_f32 v[8:9], v[46:47], v[12:13], v[8:9]
	s_waitcnt lgkmcnt(1)
	v_pk_fma_f32 v[8:9], v[230:231], v[14:15], v[8:9]
	s_nop 0
	v_pk_fma_f32 v[8:9], v[232:233], v[16:17], v[8:9]
	s_waitcnt lgkmcnt(0)
	v_pk_fma_f32 v[8:9], v[234:235], v[32:33], v[8:9]
	s_nop 0
	v_pk_fma_f32 v[8:9], v[236:237], v[34:35], v[8:9]
	s_nop 0
	v_add_f32_e32 v2, v8, v9
	s_nop 1
	v_add_f32_dpp v2, v2, v2 quad_perm:[1,0,3,2] row_mask:0xf bank_mask:0xf bound_ctrl:1
	s_nop 1
	v_add_f32_dpp v2, v2, v2 quad_perm:[2,3,0,1] row_mask:0xf bank_mask:0xf bound_ctrl:1
	v_sub_f32_e32 v2, v184, v2
	v_cndmask_b32_e64 v2, v35, v2, s[92:93]
	s_branch .Ls4join
; #define SOLVE_LD(i_) do { _Pragma("unroll") for (int a4 = 0; a4 < ((i_) + 15) / 16; ++a4) lq[(i_) % 3][a4] = *(const LAS f32x4*)(LP + (i_) * 64 + 4 * a4); } while (0)
; __device__ __forceinline__ void gdn_prep_phase(LAS unsigned char* lds, const GdnPrepArgs& A, int bid, int G, const unsigned char* zero_page) {
;     ...
;         SOLVE_LD(0); SOLVE_LD(1);
; #pragma unroll
;         for (int i = 0; i < 64; ++i) {
;             if (i + 2 < 48) SOLVE_LD(i + 2);
;             else if (i + 1 >= 48 && i + 1 < 64) SOLVE_LD(i + 1);
;             float p0 = 0.f, p1 = 0.f;
; #pragma unroll
;             for (int a4 = 0; a4 < (i + 15) / 16; ++a4) { const f32x4 lv = lq[i % 3][a4];
;                 p0 = __builtin_fmaf(lv.x, t[4 * a4], p0); p1 = __builtin_fmaf(lv.y, t[4 * a4 + 1], p1); p0 = __builtin_fmaf(lv.z, t[4 * a4 + 2], p0); p1 = __builtin_fmaf(lv.w, t[4 * a4 + 3], p1); }
;             float p = quad_sum(p0 + p1);
;             const float ti = (i == j ? 1.f : 0.f) - p;
;             if (q == (i & 3)) t[i >> 2] = ti;
;             if ((i & 7) == 3 && !(pflg & 64)) {
;                 constexpr int kk = 0; const int k8 = i >> 3, b = w + 8 * (k8 & 1); v4u f; int off; (void)kk;
;                 if (k8 < 2)      { f = frag16_rm(lds + L_KN, QS_, b >> 2, b & 3, lane); off = B_KA + b * 1024; }
;                 else if (k8 < 4) { f = frag16_rm(lds + L_QN, QS_, b >> 2, b & 3, lane); off = B_QA + b * 1024; }
;                 else if (k8 < 6) { f = frag16_tr(lds + L_KN, QS_, b >> 1, b & 1, lane); off = B_KT + b * 1024; }
;                 else             { f = frag16_rm(lds + (k8 == 6 ? L_AF : L_AB), AS_, w >> 1, w & 1, lane); off = (k8 == 6 ? B_AF : B_AB) + w * 1024; }
;                 *(v4u*)(blob + off + lane * 16) = f; }
.Ls4v1:
	v_lshl_add_u64 v[6:7], s[40:41], 0, v[22:23]
	s_nop 0
	s_nop 0
	s_nop 1
	s_nop 1
	s_nop 0
	s_nop 1
	s_nop 1
	v_readlane_b32 s2, v255, 48
	v_add_u32_e32 v9, v63, v108
	ds_read2_b64 v[10:13], v9 offset1:4
	v_readlane_b32 s3, v255, 49
	s_nop 0
	v_lshl_add_u64 v[8:9], v[6:7], 0, s[2:3]
	s_waitcnt lgkmcnt(0)
	global_store_dwordx4 v[8:9], v[10:13], off
	s_nop 0
	s_nop 1
	s_nop 1
	s_nop 0
	s_nop 1
	s_nop 1
	s_nop 0
	s_nop 1
	s_nop 1
	s_nop 0
	s_nop 1
	s_nop 1
	s_nop 0
	s_nop 1
	s_nop 1
	v_mov_b32_e32 v5, v131
	s_nop 1
	s_nop 1
	v_mov_b32_e32 v5, v131
	s_nop 1
	s_nop 1
	v_mov_b32_e32 v5, v131
	v_add_u32_e32 v14, v63, v117
	ds_read2_b64 v[14:17], v14 offset1:4
	v_lshl_add_u64 v[32:33], v[6:7], 0, s[38:39]
	s_waitcnt lgkmcnt(0)
	global_store_dwordx4 v[32:33], v[14:17], off
	v_mov_b32_e32 v5, v131
	s_nop 1
	s_nop 1
	s_nop 0
	s_nop 1
	s_nop 1
	s_nop 0
	s_nop 1
	s_nop 1
	ds_read_b128 v[38:41], v56 offset:4368
	s_nop 0
	s_nop 1
	s_nop 1
	v_mov_b32_e32 v130, 0
	v_mov_b32_e32 v3, 0
	v_mov_b32_e32 v2, 0
	v_mov_b32_e32 v4, 0
	v_mov_b32_e32 v5, 0
	ds_read_b128 v[42:45], v56 offset:4624
	s_nop 0
	v_mov_b32_e32 v34, 0
	s_nop 1
	v_add_f32_dpp v34, v34, v34 quad_perm:[1,0,3,2] row_mask:0xf bank_mask:0xf bound_ctrl:1
	s_nop 1
	v_add_f32_dpp v34, v34, v34 quad_perm:[2,3,0,1] row_mask:0xf bank_mask:0xf bound_ctrl:1
	v_sub_f32_e32 v34, v122, v34
	v_cndmask_b32_e64 v230, 0, v34, s[86:87]
	v_mov_b32_e32 v231, v131
	ds_read_b128 v[46:49], v56 offset:4880
	s_waitcnt lgkmcnt(2)
	v_pk_fma_f32 v[14:15], v[38:39], v[230:231], 0 op_sel_hi:[1,1,0]
	s_nop 0
	v_pk_fma_f32 v[14:15], v[40:41], 0, v[14:15] op_sel_hi:[1,0,1]
	s_nop 0
	v_add_f32_e32 v14, v14, v15
	s_nop 1
	v_add_f32_dpp v14, v14, v14 quad_perm:[1,0,3,2] row_mask:0xf bank_mask:0xf bound_ctrl:1
	s_nop 1
	v_add_f32_dpp v14, v14, v14 quad_perm:[2,3,0,1] row_mask:0xf bank_mask:0xf bound_ctrl:1
	v_sub_f32_e32 v14, v123, v14
	v_cndmask_b32_e64 v230, v230, v14, s[88:89]
	ds_read_b128 v[38:41], v56 offset:5136
	s_waitcnt lgkmcnt(2)
	v_pk_fma_f32 v[10:11], v[42:43], v[230:231], 0 op_sel_hi:[1,1,0]
	s_nop 0
	v_pk_fma_f32 v[10:11], v[44:45], 0, v[10:11] op_sel_hi:[1,0,1]
	s_nop 0
	v_add_f32_e32 v10, v10, v11
	s_nop 1
	v_add_f32_dpp v10, v10, v10 quad_perm:[1,0,3,2] row_mask:0xf bank_mask:0xf bound_ctrl:1
	s_nop 1
	v_add_f32_dpp v10, v10, v10 quad_perm:[2,3,0,1] row_mask:0xf bank_mask:0xf bound_ctrl:1
	v_sub_f32_e32 v10, v124, v10
	v_cndmask_b32_e64 v10, v230, v10, s[90:91]
	v_mov_b32_e32 v11, v131
	ds_read_b128 v[230:233], v56 offset:5392
	s_waitcnt lgkmcnt(2)
	v_pk_fma_f32 v[12:13], v[46:47], v[10:11], 0 op_sel_hi:[1,1,0]
	s_movk_i32 s40, 0x4000
	v_pk_fma_f32 v[12:13], v[48:49], 0, v[12:13] op_sel_hi:[1,0,1]
	s_nop 0
	v_add_f32_e32 v11, v12, v13
	v_add_co_u32_e32 v12, vcc, s40, v8
	s_nop 0
	v_add_f32_dpp v11, v11, v11 quad_perm:[1,0,3,2] row_mask:0xf bank_mask:0xf bound_ctrl:1
	v_addc_co_u32_e32 v13, vcc, 0, v9, vcc
	s_nop 0
	v_add_f32_dpp v11, v11, v11 quad_perm:[2,3,0,1] row_mask:0xf bank_mask:0xf bound_ctrl:1
	v_sub_f32_e32 v11, v125, v11
	v_cndmask_b32_e64 v10, v10, v11, s[92:93]
	v_add_u32_e32 v11, v62, v108
	v_add_u32_e32 v11, 0xc800, v11
	ds_read2_b64 v[34:37], v11 offset0:128 offset1:132
	s_waitcnt lgkmcnt(0)
	global_store_dwordx4 v[12:13], v[34:37], off
	v_mov_b32_e32 v11, v131
	ds_read_b128 v[46:49], v56 offset:5648
	v_pk_fma_f32 v[12:13], v[38:39], v[10:11], 0 op_sel_hi:[1,1,0]
	s_nop 0
	v_pk_fma_f32 v[12:13], v[40:41], 0, v[12:13] op_sel_hi:[1,0,1]
	s_nop 0
	v_add_f32_e32 v11, v12, v13
	s_nop 1
	v_add_f32_dpp v11, v11, v11 quad_perm:[1,0,3,2] row_mask:0xf bank_mask:0xf bound_ctrl:1
	s_nop 1
	v_add_f32_dpp v11, v11, v11 quad_perm:[2,3,0,1] row_mask:0xf bank_mask:0xf bound_ctrl:1
	v_sub_f32_e32 v11, v126, v11
	v_cndmask_b32_e64 v11, 0, v11, s[86:87]
	ds_read_b128 v[38:41], v56 offset:5904
	s_nop 0
	v_pk_fma_f32 v[16:17], v[230:231], v[10:11], 0 op_sel_hi:[1,1,0]
	s_nop 0
	v_pk_fma_f32 v[16:17], v[232:233], 0, v[16:17] op_sel_hi:[1,0,1]
	s_nop 0
	v_add_f32_e32 v16, v16, v17
	s_nop 1
	v_add_f32_dpp v16, v16, v16 quad_perm:[1,0,3,2] row_mask:0xf bank_mask:0xf bound_ctrl:1
	s_nop 1
	v_add_f32_dpp v16, v16, v16 quad_perm:[2,3,0,1] row_mask:0xf bank_mask:0xf bound_ctrl:1
	v_sub_f32_e32 v16, v127, v16
	v_cndmask_b32_e64 v11, v11, v16, s[88:89]
	ds_read_b128 v[230:233], v56 offset:6160
	s_waitcnt lgkmcnt(2)
	v_pk_fma_f32 v[16:17], v[46:47], v[10:11], 0 op_sel_hi:[1,1,0]
	s_nop 0
	v_pk_fma_f32 v[16:17], v[48:49], 0, v[16:17] op_sel_hi:[1,0,1]
	s_nop 0
	v_add_f32_e32 v16, v16, v17
	s_nop 1
	v_add_f32_dpp v16, v16, v16 quad_perm:[1,0,3,2] row_mask:0xf bank_mask:0xf bound_ctrl:1
	s_nop 1
	v_add_f32_dpp v16, v16, v16 quad_perm:[2,3,0,1] row_mask:0xf bank_mask:0xf bound_ctrl:1
	v_sub_f32_e32 v16, v128, v16
	v_cndmask_b32_e64 v11, v11, v16, s[90:91]
	ds_read_b128 v[46:49], v56 offset:6416
	s_waitcnt lgkmcnt(2)
	v_pk_fma_f32 v[12:13], v[38:39], v[10:11], 0 op_sel_hi:[1,1,0]
	s_nop 0
	v_pk_fma_f32 v[12:13], v[40:41], 0, v[12:13] op_sel_hi:[1,0,1]
	s_nop 0
	v_add_f32_e32 v12, v12, v13
	s_nop 1
	v_add_f32_dpp v12, v12, v12 quad_perm:[1,0,3,2] row_mask:0xf bank_mask:0xf bound_ctrl:1
	s_nop 1
	v_add_f32_dpp v12, v12, v12 quad_perm:[2,3,0,1] row_mask:0xf bank_mask:0xf bound_ctrl:1
	v_sub_f32_e32 v12, v129, v12
	v_cndmask_b32_e64 v11, v11, v12, s[92:93]
	ds_read_b128 v[38:41], v56 offset:6672
	s_waitcnt lgkmcnt(2)
	v_pk_fma_f32 v[16:17], v[230:231], v[10:11], 0 op_sel_hi:[1,1,0]
	s_nop 0
	v_pk_fma_f32 v[16:17], v[232:233], 0, v[16:17] op_sel_hi:[1,0,1]
	s_nop 0
	v_add_f32_e32 v16, v16, v17
	s_nop 1
	v_add_f32_dpp v16, v16, v16 quad_perm:[1,0,3,2] row_mask:0xf bank_mask:0xf bound_ctrl:1
	s_nop 1
	v_add_f32_dpp v16, v16, v16 quad_perm:[2,3,0,1] row_mask:0xf bank_mask:0xf bound_ctrl:1
	v_sub_f32_e32 v16, v136, v16
	v_cndmask_b32_e64 v16, 0, v16, s[86:87]
	v_mov_b32_e32 v17, v131
	ds_read_b128 v[230:233], v56 offset:6928
	s_waitcnt lgkmcnt(2)
; #define SOLVE_LD(i_) do { _Pragma("unroll") for (int a4 = 0; a4 < ((i_) + 15) / 16; ++a4) lq[(i_) % 3][a4] = *(const LAS f32x4*)(LP + (i_) * 64 + 4 * a4); } while (0)
; __device__ __forceinline__ void gdn_prep_phase(LAS unsigned char* lds, const GdnPrepArgs& A, int bid, int G, const unsigned char* zero_page) {
;     ...
;         for (int i = 0; i < 64; ++i) {
;             if (i + 2 < 48) SOLVE_LD(i + 2);
;             else if (i + 1 >= 48 && i + 1 < 64) SOLVE_LD(i + 1);
;             float p0 = 0.f, p1 = 0.f;
; #pragma unroll
;             for (int a4 = 0; a4 < (i + 15) / 16; ++a4) { const f32x4 lv = lq[i % 3][a4];
;                 p0 = __builtin_fmaf(lv.x, t[4 * a4], p0); p1 = __builtin_fmaf(lv.y, t[4 * a4 + 1], p1); p0 = __builtin_fmaf(lv.z, t[4 * a4 + 2], p0); p1 = __builtin_fmaf(lv.w, t[4 * a4 + 3], p1); }
;             float p = quad_sum(p0 + p1);
;             const float ti = (i == j ? 1.f : 0.f) - p;
;             if (q == (i & 3)) t[i >> 2] = ti;
;             if ((i & 7) == 3 && !(pflg & 64)) {
;                 constexpr int kk = 0; const int k8 = i >> 3, b = w + 8 * (k8 & 1); v4u f; int off; (void)kk;
;                 if (k8 < 2)      { f = frag16_rm(lds + L_KN, QS_, b >> 2, b & 3, lane); off = B_KA + b * 1024; }
;                 else if (k8 < 4) { f = frag16_rm(lds + L_QN, QS_, b >> 2, b & 3, lane); off = B_QA + b * 1024; }
;                 else if (k8 < 6) { f = frag16_tr(lds + L_KN, QS_, b >> 1, b & 1, lane); off = B_KT + b * 1024; }
;                 else             { f = frag16_rm(lds + (k8 == 6 ? L_AF : L_AB), AS_, w >> 1, w & 1, lane); off = (k8 == 6 ? B_AF : B_AB) + w * 1024; }
;                 *(v4u*)(blob + off + lane * 16) = f; }
;             __builtin_amdgcn_sched_barrier(0);
;         }
	v_pk_fma_f32 v[34:35], v[46:47], v[10:11], 0 op_sel_hi:[1,1,0]
	s_nop 0
	v_pk_fma_f32 v[34:35], v[48:49], v[16:17], v[34:35]
	s_nop 0
	v_add_f32_e32 v17, v34, v35
	s_nop 1
	v_add_f32_dpp v17, v17, v17 quad_perm:[1,0,3,2] row_mask:0xf bank_mask:0xf bound_ctrl:1
	s_nop 1
	v_add_f32_dpp v17, v17, v17 quad_perm:[2,3,0,1] row_mask:0xf bank_mask:0xf bound_ctrl:1
	v_sub_f32_e32 v17, v137, v17
	v_cndmask_b32_e64 v16, v16, v17, s[88:89]
	v_mov_b32_e32 v17, v131
	ds_read_b128 v[46:49], v56 offset:7184
	s_waitcnt lgkmcnt(2)
	v_pk_fma_f32 v[12:13], v[38:39], v[10:11], 0 op_sel_hi:[1,1,0]
	s_nop 0
	v_pk_fma_f32 v[12:13], v[40:41], v[16:17], v[12:13]
	s_nop 0
	v_add_f32_e32 v12, v12, v13
	s_nop 1
	v_add_f32_dpp v12, v12, v12 quad_perm:[1,0,3,2] row_mask:0xf bank_mask:0xf bound_ctrl:1
	s_nop 1
	v_add_f32_dpp v12, v12, v12 quad_perm:[2,3,0,1] row_mask:0xf bank_mask:0xf bound_ctrl:1
	v_sub_f32_e32 v12, v138, v12
	v_cndmask_b32_e64 v12, v16, v12, s[90:91]
	v_mov_b32_e32 v13, v131
	ds_read_b128 v[38:41], v56 offset:7440
	s_waitcnt lgkmcnt(2)
	v_pk_fma_f32 v[42:43], v[230:231], v[10:11], 0 op_sel_hi:[1,1,0]
	v_add_co_u32_e32 v230, vcc, s40, v32
	v_pk_fma_f32 v[42:43], v[232:233], v[12:13], v[42:43]
	s_nop 0
	v_addc_co_u32_e32 v231, vcc, 0, v33, vcc
	v_add_f32_e32 v13, v42, v43
	s_nop 1
	v_add_f32_dpp v13, v13, v13 quad_perm:[1,0,3,2] row_mask:0xf bank_mask:0xf bound_ctrl:1
	s_nop 1
	v_add_f32_dpp v13, v13, v13 quad_perm:[2,3,0,1] row_mask:0xf bank_mask:0xf bound_ctrl:1
	v_sub_f32_e32 v13, v139, v13
	v_cndmask_b32_e64 v12, v12, v13, s[92:93]
	v_add_u32_e32 v13, v62, v117
	v_add_u32_e32 v13, 0xc800, v13
	ds_read2_b64 v[42:45], v13 offset0:128 offset1:132
	s_waitcnt lgkmcnt(0)
	global_store_dwordx4 v[230:231], v[42:45], off
	v_mov_b32_e32 v13, v131
	ds_read_b128 v[230:233], v56 offset:7696
	v_pk_fma_f32 v[34:35], v[46:47], v[10:11], 0 op_sel_hi:[1,1,0]
	s_nop 0
	v_pk_fma_f32 v[34:35], v[48:49], v[12:13], v[34:35]
	s_nop 0
	v_add_f32_e32 v13, v34, v35
	s_nop 1
	v_add_f32_dpp v13, v13, v13 quad_perm:[1,0,3,2] row_mask:0xf bank_mask:0xf bound_ctrl:1
	s_nop 1
	v_add_f32_dpp v13, v13, v13 quad_perm:[2,3,0,1] row_mask:0xf bank_mask:0xf bound_ctrl:1
	v_sub_f32_e32 v13, v140, v13
	v_cndmask_b32_e64 v13, 0, v13, s[86:87]
	ds_read_b128 v[46:49], v56 offset:7952
	s_nop 0
	v_pk_fma_f32 v[14:15], v[38:39], v[10:11], 0 op_sel_hi:[1,1,0]
	s_nop 0
	v_pk_fma_f32 v[14:15], v[40:41], v[12:13], v[14:15]
	s_nop 0
	v_add_f32_e32 v14, v14, v15
	s_nop 1
	v_add_f32_dpp v14, v14, v14 quad_perm:[1,0,3,2] row_mask:0xf bank_mask:0xf bound_ctrl:1
	s_nop 1
	v_add_f32_dpp v14, v14, v14 quad_perm:[2,3,0,1] row_mask:0xf bank_mask:0xf bound_ctrl:1
	v_sub_f32_e32 v14, v141, v14
	v_cndmask_b32_e64 v13, v13, v14, s[88:89]
	ds_read_b128 v[38:41], v56 offset:8208
	s_waitcnt lgkmcnt(2)
	v_pk_fma_f32 v[42:43], v[230:231], v[10:11], 0 op_sel_hi:[1,1,0]
	s_nop 0
	v_pk_fma_f32 v[42:43], v[232:233], v[12:13], v[42:43]
	s_nop 0
	v_add_f32_e32 v42, v42, v43
	s_nop 1
	v_add_f32_dpp v42, v42, v42 quad_perm:[1,0,3,2] row_mask:0xf bank_mask:0xf bound_ctrl:1
	s_nop 1
	v_add_f32_dpp v42, v42, v42 quad_perm:[2,3,0,1] row_mask:0xf bank_mask:0xf bound_ctrl:1
	v_sub_f32_e32 v42, v142, v42
	v_cndmask_b32_e64 v13, v13, v42, s[90:91]
	ds_read_b128 v[230:233], v56 offset:8464
	ds_read_b128 v[234:237], v56 offset:8480
	s_waitcnt lgkmcnt(3)
	v_pk_fma_f32 v[34:35], v[46:47], v[10:11], 0 op_sel_hi:[1,1,0]
	s_nop 0
	v_pk_fma_f32 v[34:35], v[48:49], v[12:13], v[34:35]
	s_nop 0
	v_add_f32_e32 v34, v34, v35
	s_nop 1
	v_add_f32_dpp v34, v34, v34 quad_perm:[1,0,3,2] row_mask:0xf bank_mask:0xf bound_ctrl:1
	s_nop 1
	v_add_f32_dpp v34, v34, v34 quad_perm:[2,3,0,1] row_mask:0xf bank_mask:0xf bound_ctrl:1
	v_sub_f32_e32 v34, v143, v34
	v_cndmask_b32_e64 v13, v13, v34, s[92:93]
	ds_read_b128 v[46:49], v56 offset:8720
	ds_read_b128 v[238:241], v56 offset:8736
	s_waitcnt lgkmcnt(4)
	v_pk_fma_f32 v[14:15], v[38:39], v[10:11], 0 op_sel_hi:[1,1,0]
	s_nop 0
	v_pk_fma_f32 v[14:15], v[40:41], v[12:13], v[14:15]
	s_nop 0
	v_add_f32_e32 v14, v14, v15
	s_nop 1
	v_add_f32_dpp v14, v14, v14 quad_perm:[1,0,3,2] row_mask:0xf bank_mask:0xf bound_ctrl:1
	s_nop 1
	v_add_f32_dpp v14, v14, v14 quad_perm:[2,3,0,1] row_mask:0xf bank_mask:0xf bound_ctrl:1
	v_sub_f32_e32 v14, v144, v14
	v_cndmask_b32_e64 v246, 0, v14, s[86:87]
	v_mov_b32_e32 v247, v131
	ds_read_b128 v[38:41], v56 offset:8976
	ds_read_b128 v[242:245], v56 offset:8992
	s_waitcnt lgkmcnt(5)
	v_pk_fma_f32 v[42:43], v[230:231], v[10:11], 0 op_sel_hi:[1,1,0]
	s_nop 0
	v_pk_fma_f32 v[42:43], v[232:233], v[12:13], v[42:43]
	s_waitcnt lgkmcnt(4)
	v_pk_fma_f32 v[42:43], v[234:235], v[246:247], v[42:43]
	s_nop 0
	v_pk_fma_f32 v[42:43], v[236:237], 0, v[42:43] op_sel_hi:[1,0,1]
	s_nop 0
	v_add_f32_e32 v42, v42, v43
	s_nop 1
	v_add_f32_dpp v42, v42, v42 quad_perm:[1,0,3,2] row_mask:0xf bank_mask:0xf bound_ctrl:1
	s_nop 1
	v_add_f32_dpp v42, v42, v42 quad_perm:[2,3,0,1] row_mask:0xf bank_mask:0xf bound_ctrl:1
	v_sub_f32_e32 v42, v145, v42
	v_cndmask_b32_e64 v246, v246, v42, s[88:89]
	ds_read_b128 v[230:233], v56 offset:9232
	ds_read_b128 v[234:237], v56 offset:9248
	s_waitcnt lgkmcnt(5)
	v_pk_fma_f32 v[34:35], v[46:47], v[10:11], 0 op_sel_hi:[1,1,0]
	s_nop 0
	v_pk_fma_f32 v[34:35], v[48:49], v[12:13], v[34:35]
	s_waitcnt lgkmcnt(4)
	v_pk_fma_f32 v[34:35], v[238:239], v[246:247], v[34:35]
	s_nop 0
	v_pk_fma_f32 v[34:35], v[240:241], 0, v[34:35] op_sel_hi:[1,0,1]
	s_nop 0
	v_add_f32_e32 v34, v34, v35
	s_nop 1
	v_add_f32_dpp v34, v34, v34 quad_perm:[1,0,3,2] row_mask:0xf bank_mask:0xf bound_ctrl:1
	s_nop 1
	v_add_f32_dpp v34, v34, v34 quad_perm:[2,3,0,1] row_mask:0xf bank_mask:0xf bound_ctrl:1
	v_sub_f32_e32 v34, v146, v34
	v_cndmask_b32_e64 v238, v246, v34, s[90:91]
	v_mov_b32_e32 v239, v131
	ds_read_b128 v[46:49], v56 offset:9488
	s_waitcnt lgkmcnt(4)
; #define SOLVE_LD(i_) do { _Pragma("unroll") for (int a4 = 0; a4 < ((i_) + 15) / 16; ++a4) lq[(i_) % 3][a4] = *(const LAS f32x4*)(LP + (i_) * 64 + 4 * a4); } while (0)
; __device__ __forceinline__ void gdn_prep_phase(LAS unsigned char* lds, const GdnPrepArgs& A, int bid, int G, const unsigned char* zero_page) {
;     ...
;         for (int i = 0; i < 64; ++i) {
;             if (i + 2 < 48) SOLVE_LD(i + 2);
;             else if (i + 1 >= 48 && i + 1 < 64) SOLVE_LD(i + 1);
;             float p0 = 0.f, p1 = 0.f;
; #pragma unroll
;             for (int a4 = 0; a4 < (i + 15) / 16; ++a4) { const f32x4 lv = lq[i % 3][a4];
;                 p0 = __builtin_fmaf(lv.x, t[4 * a4], p0); p1 = __builtin_fmaf(lv.y, t[4 * a4 + 1], p1); p0 = __builtin_fmaf(lv.z, t[4 * a4 + 2], p0); p1 = __builtin_fmaf(lv.w, t[4 * a4 + 3], p1); }
;             float p = quad_sum(p0 + p1);
;             const float ti = (i == j ? 1.f : 0.f) - p;
;             if (q == (i & 3)) t[i >> 2] = ti;
;             if ((i & 7) == 3 && !(pflg & 64)) {
;                 constexpr int kk = 0; const int k8 = i >> 3, b = w + 8 * (k8 & 1); v4u f; int off; (void)kk;
;                 if (k8 < 2)      { f = frag16_rm(lds + L_KN, QS_, b >> 2, b & 3, lane); off = B_KA + b * 1024; }
;                 else if (k8 < 4) { f = frag16_rm(lds + L_QN, QS_, b >> 2, b & 3, lane); off = B_QA + b * 1024; }
;                 else if (k8 < 6) { f = frag16_tr(lds + L_KN, QS_, b >> 1, b & 1, lane); off = B_KT + b * 1024; }
;                 else             { f = frag16_rm(lds + (k8 == 6 ? L_AF : L_AB), AS_, w >> 1, w & 1, lane); off = (k8 == 6 ? B_AF : B_AB) + w * 1024; }
;                 *(v4u*)(blob + off + lane * 16) = f; }
;             __builtin_amdgcn_sched_barrier(0);
;         }
	v_pk_fma_f32 v[14:15], v[38:39], v[10:11], 0 op_sel_hi:[1,1,0]
	s_mov_b32 s40, 0x8000
	v_pk_fma_f32 v[14:15], v[40:41], v[12:13], v[14:15]
	s_waitcnt lgkmcnt(3)
	v_pk_fma_f32 v[14:15], v[242:243], v[238:239], v[14:15]
	s_nop 0
	v_pk_fma_f32 v[14:15], v[244:245], 0, v[14:15] op_sel_hi:[1,0,1]
	s_nop 0
	v_add_f32_e32 v14, v14, v15
	v_add_u32_e32 v15, s71, v61
	ds_read_u16 v16, v15 offset:816
	ds_read_u16 v17, v15 offset:4352
	ds_read_u16 v239, v15 offset:4624
	ds_read_u16 v240, v15 offset:4896
	ds_read_u16 v241, v15 offset:5168
	ds_read_b128 v[38:41], v56 offset:9504
	ds_read_u16 v242, v15
	ds_read_u16 v243, v15 offset:272
	ds_read_u16 v15, v15 offset:544
	v_add_f32_dpp v14, v14, v14 quad_perm:[1,0,3,2] row_mask:0xf bank_mask:0xf bound_ctrl:1
	s_waitcnt lgkmcnt(4)
	v_perm_b32 v241, v241, v240, s33
	v_perm_b32 v240, v239, v17, s33
	v_add_f32_dpp v14, v14, v14 quad_perm:[2,3,0,1] row_mask:0xf bank_mask:0xf bound_ctrl:1
	v_sub_f32_e32 v14, v147, v14
	s_waitcnt lgkmcnt(0)
	v_perm_b32 v239, v16, v15, s33
	v_add_co_u32_e32 v16, vcc, s40, v8
	v_cndmask_b32_e64 v14, v238, v14, s[92:93]
	v_perm_b32 v238, v243, v242, s33
	v_addc_co_u32_e32 v17, vcc, 0, v9, vcc
	global_store_dwordx4 v[16:17], v[238:241], off offset:2048
	v_mov_b32_e32 v15, v131
	ds_read_b128 v[242:245], v56 offset:9744
	ds_read_b128 v[246:249], v56 offset:9760
	v_pk_fma_f32 v[16:17], v[230:231], v[10:11], 0 op_sel_hi:[1,1,0]
	s_nop 0
	v_pk_fma_f32 v[16:17], v[232:233], v[12:13], v[16:17]
	s_nop 0
	v_pk_fma_f32 v[16:17], v[234:235], v[14:15], v[16:17]
	s_nop 0
	v_pk_fma_f32 v[16:17], v[236:237], 0, v[16:17] op_sel_hi:[1,0,1]
	s_nop 0
	v_add_f32_e32 v15, v16, v17
	s_nop 1
	v_add_f32_dpp v15, v15, v15 quad_perm:[1,0,3,2] row_mask:0xf bank_mask:0xf bound_ctrl:1
	s_nop 1
	v_add_f32_dpp v15, v15, v15 quad_perm:[2,3,0,1] row_mask:0xf bank_mask:0xf bound_ctrl:1
	v_sub_f32_e32 v15, v148, v15
	v_cndmask_b32_e64 v15, 0, v15, s[86:87]
	ds_read_b128 v[230:233], v56 offset:10000
	ds_read_b128 v[234:237], v56 offset:10016
	s_nop 0
	v_pk_fma_f32 v[16:17], v[46:47], v[10:11], 0 op_sel_hi:[1,1,0]
	s_nop 0
	v_pk_fma_f32 v[16:17], v[48:49], v[12:13], v[16:17]
	s_nop 0
	v_pk_fma_f32 v[16:17], v[38:39], v[14:15], v[16:17]
	s_nop 0
	v_pk_fma_f32 v[16:17], v[40:41], 0, v[16:17] op_sel_hi:[1,0,1]
	s_nop 0
	v_add_f32_e32 v16, v16, v17
	s_nop 1
	v_add_f32_dpp v16, v16, v16 quad_perm:[1,0,3,2] row_mask:0xf bank_mask:0xf bound_ctrl:1
	s_nop 1
	v_add_f32_dpp v16, v16, v16 quad_perm:[2,3,0,1] row_mask:0xf bank_mask:0xf bound_ctrl:1
	v_sub_f32_e32 v16, v149, v16
	v_cndmask_b32_e64 v15, v15, v16, s[88:89]
	ds_read_b128 v[38:41], v56 offset:10256
	ds_read_b128 v[46:49], v56 offset:10272
	s_waitcnt lgkmcnt(5)
	v_pk_fma_f32 v[16:17], v[242:243], v[10:11], 0 op_sel_hi:[1,1,0]
	s_nop 0
	v_pk_fma_f32 v[16:17], v[244:245], v[12:13], v[16:17]
	s_waitcnt lgkmcnt(4)
	v_pk_fma_f32 v[16:17], v[246:247], v[14:15], v[16:17]
	s_nop 0
	v_pk_fma_f32 v[16:17], v[248:249], 0, v[16:17] op_sel_hi:[1,0,1]
	s_nop 0
	v_add_f32_e32 v16, v16, v17
	s_nop 1
	v_add_f32_dpp v16, v16, v16 quad_perm:[1,0,3,2] row_mask:0xf bank_mask:0xf bound_ctrl:1
	s_nop 1
	v_add_f32_dpp v16, v16, v16 quad_perm:[2,3,0,1] row_mask:0xf bank_mask:0xf bound_ctrl:1
	v_sub_f32_e32 v16, v150, v16
	v_cndmask_b32_e64 v15, v15, v16, s[90:91]
	ds_read_b128 v[242:245], v56 offset:10512
	ds_read_b128 v[246:249], v56 offset:10528
	s_waitcnt lgkmcnt(5)
	v_pk_fma_f32 v[16:17], v[230:231], v[10:11], 0 op_sel_hi:[1,1,0]
	s_nop 0
	v_pk_fma_f32 v[16:17], v[232:233], v[12:13], v[16:17]
	s_waitcnt lgkmcnt(4)
	v_pk_fma_f32 v[16:17], v[234:235], v[14:15], v[16:17]
	s_nop 0
	v_pk_fma_f32 v[16:17], v[236:237], 0, v[16:17] op_sel_hi:[1,0,1]
	s_nop 0
	v_add_f32_e32 v16, v16, v17
	s_nop 1
	v_add_f32_dpp v16, v16, v16 quad_perm:[1,0,3,2] row_mask:0xf bank_mask:0xf bound_ctrl:1
	s_nop 1
	v_add_f32_dpp v16, v16, v16 quad_perm:[2,3,0,1] row_mask:0xf bank_mask:0xf bound_ctrl:1
	v_sub_f32_e32 v16, v151, v16
	v_cndmask_b32_e64 v15, v15, v16, s[92:93]
	ds_read_b128 v[230:233], v56 offset:10768
	ds_read_b128 v[234:237], v56 offset:10784
	s_waitcnt lgkmcnt(5)
	v_pk_fma_f32 v[16:17], v[38:39], v[10:11], 0 op_sel_hi:[1,1,0]
	s_nop 0
	v_pk_fma_f32 v[16:17], v[40:41], v[12:13], v[16:17]
	s_waitcnt lgkmcnt(4)
	v_pk_fma_f32 v[16:17], v[46:47], v[14:15], v[16:17]
	s_nop 0
	v_pk_fma_f32 v[16:17], v[48:49], 0, v[16:17] op_sel_hi:[1,0,1]
	s_nop 0
	v_add_f32_e32 v16, v16, v17
	s_nop 1
	v_add_f32_dpp v16, v16, v16 quad_perm:[1,0,3,2] row_mask:0xf bank_mask:0xf bound_ctrl:1
	s_nop 1
	v_add_f32_dpp v16, v16, v16 quad_perm:[2,3,0,1] row_mask:0xf bank_mask:0xf bound_ctrl:1
	v_sub_f32_e32 v16, v152, v16
	v_cndmask_b32_e64 v16, 0, v16, s[86:87]
	v_mov_b32_e32 v17, v131
	ds_read_b128 v[38:41], v56 offset:11024
	ds_read_b128 v[46:49], v56 offset:11040
	s_waitcnt lgkmcnt(5)
	v_pk_fma_f32 v[238:239], v[242:243], v[10:11], 0 op_sel_hi:[1,1,0]
	s_nop 0
	v_pk_fma_f32 v[238:239], v[244:245], v[12:13], v[238:239]
	s_waitcnt lgkmcnt(4)
	v_pk_fma_f32 v[238:239], v[246:247], v[14:15], v[238:239]
	s_nop 0
	v_pk_fma_f32 v[238:239], v[248:249], v[16:17], v[238:239]
	s_nop 0
	v_add_f32_e32 v17, v238, v239
	s_nop 1
	v_add_f32_dpp v17, v17, v17 quad_perm:[1,0,3,2] row_mask:0xf bank_mask:0xf bound_ctrl:1
	s_nop 1
	v_add_f32_dpp v17, v17, v17 quad_perm:[2,3,0,1] row_mask:0xf bank_mask:0xf bound_ctrl:1
	v_sub_f32_e32 v17, v153, v17
	v_cndmask_b32_e64 v16, v16, v17, s[88:89]
	v_mov_b32_e32 v17, v131
	ds_read_b128 v[242:245], v56 offset:11280
	ds_read_b128 v[246:249], v56 offset:11296
	s_waitcnt lgkmcnt(5)
	v_pk_fma_f32 v[42:43], v[230:231], v[10:11], 0 op_sel_hi:[1,1,0]
	s_nop 0
	v_pk_fma_f32 v[42:43], v[232:233], v[12:13], v[42:43]
	s_waitcnt lgkmcnt(4)
; #define SOLVE_LD(i_) do { _Pragma("unroll") for (int a4 = 0; a4 < ((i_) + 15) / 16; ++a4) lq[(i_) % 3][a4] = *(const LAS f32x4*)(LP + (i_) * 64 + 4 * a4); } while (0)
; __device__ __forceinline__ void gdn_prep_phase(LAS unsigned char* lds, const GdnPrepArgs& A, int bid, int G, const unsigned char* zero_page) {
;     ...
;         for (int i = 0; i < 64; ++i) {
;             if (i + 2 < 48) SOLVE_LD(i + 2);
;             else if (i + 1 >= 48 && i + 1 < 64) SOLVE_LD(i + 1);
;             float p0 = 0.f, p1 = 0.f;
; #pragma unroll
;             for (int a4 = 0; a4 < (i + 15) / 16; ++a4) { const f32x4 lv = lq[i % 3][a4];
;                 p0 = __builtin_fmaf(lv.x, t[4 * a4], p0); p1 = __builtin_fmaf(lv.y, t[4 * a4 + 1], p1); p0 = __builtin_fmaf(lv.z, t[4 * a4 + 2], p0); p1 = __builtin_fmaf(lv.w, t[4 * a4 + 3], p1); }
;             float p = quad_sum(p0 + p1);
;             const float ti = (i == j ? 1.f : 0.f) - p;
;             if (q == (i & 3)) t[i >> 2] = ti;
;             if ((i & 7) == 3 && !(pflg & 64)) {
;                 constexpr int kk = 0; const int k8 = i >> 3, b = w + 8 * (k8 & 1); v4u f; int off; (void)kk;
;                 if (k8 < 2)      { f = frag16_rm(lds + L_KN, QS_, b >> 2, b & 3, lane); off = B_KA + b * 1024; }
;                 else if (k8 < 4) { f = frag16_rm(lds + L_QN, QS_, b >> 2, b & 3, lane); off = B_QA + b * 1024; }
;                 else if (k8 < 6) { f = frag16_tr(lds + L_KN, QS_, b >> 1, b & 1, lane); off = B_KT + b * 1024; }
;                 else             { f = frag16_rm(lds + (k8 == 6 ? L_AF : L_AB), AS_, w >> 1, w & 1, lane); off = (k8 == 6 ? B_AF : B_AB) + w * 1024; }
;                 *(v4u*)(blob + off + lane * 16) = f; }
;             __builtin_amdgcn_sched_barrier(0);
;         }
	v_pk_fma_f32 v[42:43], v[234:235], v[14:15], v[42:43]
	s_nop 0
	v_pk_fma_f32 v[42:43], v[236:237], v[16:17], v[42:43]
	s_nop 0
	v_add_f32_e32 v17, v42, v43
	s_nop 1
	v_add_f32_dpp v17, v17, v17 quad_perm:[1,0,3,2] row_mask:0xf bank_mask:0xf bound_ctrl:1
	s_nop 1
	v_add_f32_dpp v17, v17, v17 quad_perm:[2,3,0,1] row_mask:0xf bank_mask:0xf bound_ctrl:1
	v_sub_f32_e32 v17, v154, v17
	v_cndmask_b32_e64 v16, v16, v17, s[90:91]
	v_mov_b32_e32 v17, v131
	ds_read_b128 v[230:233], v56 offset:11536
	s_waitcnt lgkmcnt(4)
	v_pk_fma_f32 v[34:35], v[38:39], v[10:11], 0 op_sel_hi:[1,1,0]
	v_add_u32_e32 v38, s72, v61
	v_pk_fma_f32 v[34:35], v[40:41], v[12:13], v[34:35]
	v_add_co_u32_e32 v32, vcc, s40, v32
	s_waitcnt lgkmcnt(3)
	v_pk_fma_f32 v[34:35], v[46:47], v[14:15], v[34:35]
	v_addc_co_u32_e32 v33, vcc, 0, v33, vcc
	v_pk_fma_f32 v[34:35], v[48:49], v[16:17], v[34:35]
	s_nop 0
	v_add_f32_e32 v17, v34, v35
	ds_read_u16 v39, v38 offset:816
	ds_read_u16 v40, v38 offset:4352
	ds_read_u16 v46, v38 offset:4624
	ds_read_u16 v41, v38 offset:4896
	ds_read_u16 v47, v38 offset:5168
	ds_read_b128 v[34:37], v56 offset:11552
	ds_read_u16 v48, v38
	ds_read_u16 v49, v38 offset:272
	ds_read_u16 v38, v38 offset:544
	v_add_f32_dpp v17, v17, v17 quad_perm:[1,0,3,2] row_mask:0xf bank_mask:0xf bound_ctrl:1
	s_waitcnt lgkmcnt(4)
	v_perm_b32 v41, v47, v41, s33
	v_perm_b32 v40, v46, v40, s33
	v_add_f32_dpp v17, v17, v17 quad_perm:[2,3,0,1] row_mask:0xf bank_mask:0xf bound_ctrl:1
	v_sub_f32_e32 v17, v155, v17
	v_cndmask_b32_e64 v16, v16, v17, s[92:93]
	s_waitcnt lgkmcnt(0)
	v_perm_b32 v39, v39, v38, s33
	v_perm_b32 v38, v49, v48, s33
	global_store_dwordx4 v[32:33], v[38:41], off offset:2048
	v_mov_b32_e32 v17, v131
	ds_read_b128 v[46:49], v56 offset:11792
	ds_read_b128 v[234:237], v56 offset:11808
	v_pk_fma_f32 v[32:33], v[242:243], v[10:11], 0 op_sel_hi:[1,1,0]
	s_nop 0
	v_pk_fma_f32 v[32:33], v[244:245], v[12:13], v[32:33]
	s_nop 0
	v_pk_fma_f32 v[32:33], v[246:247], v[14:15], v[32:33]
	s_nop 0
	v_pk_fma_f32 v[32:33], v[248:249], v[16:17], v[32:33]
	s_nop 0
	v_add_f32_e32 v17, v32, v33
	s_nop 1
	v_add_f32_dpp v17, v17, v17 quad_perm:[1,0,3,2] row_mask:0xf bank_mask:0xf bound_ctrl:1
	s_nop 1
	v_add_f32_dpp v17, v17, v17 quad_perm:[2,3,0,1] row_mask:0xf bank_mask:0xf bound_ctrl:1
	v_sub_f32_e32 v17, v156, v17
	v_cndmask_b32_e64 v17, 0, v17, s[86:87]
	ds_read_b128 v[242:245], v56 offset:12048
	ds_read_b128 v[246:249], v56 offset:12064
	s_nop 0
	v_pk_fma_f32 v[32:33], v[230:231], v[10:11], 0 op_sel_hi:[1,1,0]
	s_nop 0
	v_pk_fma_f32 v[32:33], v[232:233], v[12:13], v[32:33]
	s_nop 0
	v_pk_fma_f32 v[32:33], v[34:35], v[14:15], v[32:33]
	s_nop 0
	v_pk_fma_f32 v[32:33], v[36:37], v[16:17], v[32:33]
	s_nop 0
	v_add_f32_e32 v32, v32, v33
	s_nop 1
	v_add_f32_dpp v32, v32, v32 quad_perm:[1,0,3,2] row_mask:0xf bank_mask:0xf bound_ctrl:1
	s_nop 1
	v_add_f32_dpp v32, v32, v32 quad_perm:[2,3,0,1] row_mask:0xf bank_mask:0xf bound_ctrl:1
	v_sub_f32_e32 v32, v157, v32
	v_cndmask_b32_e64 v17, v17, v32, s[88:89]
	s_nop 0
	s_waitcnt lgkmcnt(3)
	v_pk_fma_f32 v[32:33], v[46:47], v[10:11], 0 op_sel_hi:[1,1,0]
	s_nop 0
	v_pk_fma_f32 v[32:33], v[48:49], v[12:13], v[32:33]
	s_waitcnt lgkmcnt(2)
	v_pk_fma_f32 v[32:33], v[234:235], v[14:15], v[32:33]
	s_nop 0
	v_pk_fma_f32 v[32:33], v[236:237], v[16:17], v[32:33]
	s_nop 0
	v_add_f32_e32 v32, v32, v33
	s_nop 1
	v_add_f32_dpp v32, v32, v32 quad_perm:[1,0,3,2] row_mask:0xf bank_mask:0xf bound_ctrl:1
	s_nop 1
	v_add_f32_dpp v32, v32, v32 quad_perm:[2,3,0,1] row_mask:0xf bank_mask:0xf bound_ctrl:1
	v_sub_f32_e32 v32, v158, v32
	v_cndmask_b32_e64 v17, v17, v32, s[90:91]
	ds_read_b128 v[36:39], v56 offset:12304
	ds_read_b128 v[40:43], v56 offset:12320
	s_waitcnt lgkmcnt(3)
	v_pk_fma_f32 v[44:45], v[242:243], v[10:11], 0 op_sel_hi:[1,1,0]
	s_nop 0
	v_pk_fma_f32 v[44:45], v[244:245], v[12:13], v[44:45]
	s_waitcnt lgkmcnt(2)
	v_pk_fma_f32 v[44:45], v[246:247], v[14:15], v[44:45]
	s_nop 0
	v_pk_fma_f32 v[44:45], v[248:249], v[16:17], v[44:45]
	s_nop 0
	v_add_f32_e32 v44, v44, v45
	s_nop 1
	v_add_f32_dpp v44, v44, v44 quad_perm:[1,0,3,2] row_mask:0xf bank_mask:0xf bound_ctrl:1
	s_nop 1
	v_add_f32_dpp v44, v44, v44 quad_perm:[2,3,0,1] row_mask:0xf bank_mask:0xf bound_ctrl:1
	v_sub_f32_e32 v44, v159, v44
	v_cndmask_b32_e64 v17, v17, v44, s[92:93]
	ds_read_b128 v[230:233], v56 offset:12560
	ds_read_b128 v[234:237], v56 offset:12576
	ds_read_b128 v[238:241], v56 offset:12592
	s_waitcnt lgkmcnt(4)
	v_pk_fma_f32 v[32:33], v[36:37], v[10:11], 0 op_sel_hi:[1,1,0]
	s_nop 0
	v_pk_fma_f32 v[32:33], v[38:39], v[12:13], v[32:33]
	s_waitcnt lgkmcnt(3)
	v_pk_fma_f32 v[32:33], v[40:41], v[14:15], v[32:33]
	s_nop 0
	v_pk_fma_f32 v[32:33], v[42:43], v[16:17], v[32:33]
	s_nop 0
	v_add_f32_e32 v32, v32, v33
	s_nop 1
	v_add_f32_dpp v32, v32, v32 quad_perm:[1,0,3,2] row_mask:0xf bank_mask:0xf bound_ctrl:1
	s_nop 1
	v_add_f32_dpp v32, v32, v32 quad_perm:[2,3,0,1] row_mask:0xf bank_mask:0xf bound_ctrl:1
	v_sub_f32_e32 v32, v160, v32
	v_cndmask_b32_e64 v48, 0, v32, s[86:87]
	ds_read_b128 v[36:39], v56 offset:12816
	ds_read_b128 v[40:43], v56 offset:12832
	ds_read_b128 v[242:245], v56 offset:12848
	v_mov_b32_e32 v49, v131
	s_waitcnt lgkmcnt(5)
	v_pk_fma_f32 v[44:45], v[230:231], v[10:11], 0 op_sel_hi:[1,1,0]
	s_nop 0
	v_pk_fma_f32 v[44:45], v[232:233], v[12:13], v[44:45]
	s_waitcnt lgkmcnt(4)
	v_pk_fma_f32 v[44:45], v[234:235], v[14:15], v[44:45]
	s_nop 0
	v_pk_fma_f32 v[44:45], v[236:237], v[16:17], v[44:45]
	s_waitcnt lgkmcnt(3)
; #define SOLVE_LD(i_) do { _Pragma("unroll") for (int a4 = 0; a4 < ((i_) + 15) / 16; ++a4) lq[(i_) % 3][a4] = *(const LAS f32x4*)(LP + (i_) * 64 + 4 * a4); } while (0)
; __device__ __forceinline__ void gdn_prep_phase(LAS unsigned char* lds, const GdnPrepArgs& A, int bid, int G, const unsigned char* zero_page) {
;     ...
;         for (int i = 0; i < 64; ++i) {
;             if (i + 2 < 48) SOLVE_LD(i + 2);
;             else if (i + 1 >= 48 && i + 1 < 64) SOLVE_LD(i + 1);
;             float p0 = 0.f, p1 = 0.f;
; #pragma unroll
;             for (int a4 = 0; a4 < (i + 15) / 16; ++a4) { const f32x4 lv = lq[i % 3][a4];
;                 p0 = __builtin_fmaf(lv.x, t[4 * a4], p0); p1 = __builtin_fmaf(lv.y, t[4 * a4 + 1], p1); p0 = __builtin_fmaf(lv.z, t[4 * a4 + 2], p0); p1 = __builtin_fmaf(lv.w, t[4 * a4 + 3], p1); }
;             float p = quad_sum(p0 + p1);
;             const float ti = (i == j ? 1.f : 0.f) - p;
;             if (q == (i & 3)) t[i >> 2] = ti;
;             if ((i & 7) == 3 && !(pflg & 64)) {
;                 constexpr int kk = 0; const int k8 = i >> 3, b = w + 8 * (k8 & 1); v4u f; int off; (void)kk;
;                 if (k8 < 2)      { f = frag16_rm(lds + L_KN, QS_, b >> 2, b & 3, lane); off = B_KA + b * 1024; }
;                 else if (k8 < 4) { f = frag16_rm(lds + L_QN, QS_, b >> 2, b & 3, lane); off = B_QA + b * 1024; }
;                 else if (k8 < 6) { f = frag16_tr(lds + L_KN, QS_, b >> 1, b & 1, lane); off = B_KT + b * 1024; }
;                 else             { f = frag16_rm(lds + (k8 == 6 ? L_AF : L_AB), AS_, w >> 1, w & 1, lane); off = (k8 == 6 ? B_AF : B_AB) + w * 1024; }
;                 *(v4u*)(blob + off + lane * 16) = f; }
;             __builtin_amdgcn_sched_barrier(0);
;         }
	v_pk_fma_f32 v[44:45], v[238:239], v[48:49], v[44:45]
	s_nop 0
	v_pk_fma_f32 v[44:45], v[240:241], 0, v[44:45] op_sel_hi:[1,0,1]
	s_nop 0
	v_add_f32_e32 v44, v44, v45
	s_nop 1
	v_add_f32_dpp v44, v44, v44 quad_perm:[1,0,3,2] row_mask:0xf bank_mask:0xf bound_ctrl:1
	s_nop 1
	v_add_f32_dpp v44, v44, v44 quad_perm:[2,3,0,1] row_mask:0xf bank_mask:0xf bound_ctrl:1
	v_sub_f32_e32 v44, v161, v44
	v_cndmask_b32_e64 v48, v48, v44, s[88:89]
	ds_read_b128 v[230:233], v56 offset:13072
	ds_read_b128 v[234:237], v56 offset:13088
	ds_read_b128 v[238:241], v56 offset:13104
	s_waitcnt lgkmcnt(5)
	v_pk_fma_f32 v[32:33], v[36:37], v[10:11], 0 op_sel_hi:[1,1,0]
	s_nop 0
	v_pk_fma_f32 v[32:33], v[38:39], v[12:13], v[32:33]
	s_waitcnt lgkmcnt(4)
	v_pk_fma_f32 v[32:33], v[40:41], v[14:15], v[32:33]
	s_nop 0
	v_pk_fma_f32 v[32:33], v[42:43], v[16:17], v[32:33]
	s_waitcnt lgkmcnt(3)
	v_pk_fma_f32 v[32:33], v[242:243], v[48:49], v[32:33]
	s_nop 0
	v_pk_fma_f32 v[32:33], v[244:245], 0, v[32:33] op_sel_hi:[1,0,1]
	s_nop 0
	v_add_f32_e32 v32, v32, v33
	s_nop 1
	v_add_f32_dpp v32, v32, v32 quad_perm:[1,0,3,2] row_mask:0xf bank_mask:0xf bound_ctrl:1
	s_nop 1
	v_add_f32_dpp v32, v32, v32 quad_perm:[2,3,0,1] row_mask:0xf bank_mask:0xf bound_ctrl:1
	v_sub_f32_e32 v32, v162, v32
	v_cndmask_b32_e64 v32, v48, v32, s[90:91]
	v_mov_b32_e32 v33, v131
	ds_read_b128 v[38:41], v56 offset:13328
	ds_read_b128 v[242:245], v56 offset:13344
	ds_read_b128 v[246:249], v56 offset:13360
	s_waitcnt lgkmcnt(5)
	v_pk_fma_f32 v[42:43], v[230:231], v[10:11], 0 op_sel_hi:[1,1,0]
	s_mov_b32 s40, 0xe000
	v_pk_fma_f32 v[42:43], v[232:233], v[12:13], v[42:43]
	v_add_co_u32_e32 v46, vcc, s40, v8
	s_waitcnt lgkmcnt(4)
	v_pk_fma_f32 v[42:43], v[234:235], v[14:15], v[42:43]
	v_addc_co_u32_e32 v47, vcc, 0, v9, vcc
	v_pk_fma_f32 v[42:43], v[236:237], v[16:17], v[42:43]
	s_waitcnt lgkmcnt(3)
	v_pk_fma_f32 v[42:43], v[238:239], v[32:33], v[42:43]
	s_nop 0
	v_pk_fma_f32 v[42:43], v[240:241], 0, v[42:43] op_sel_hi:[1,0,1]
	s_nop 0
	v_add_f32_e32 v33, v42, v43
	ds_read_b64 v[42:43], v185
	ds_read_b64 v[44:45], v186
	v_add_f32_dpp v33, v33, v33 quad_perm:[1,0,3,2] row_mask:0xf bank_mask:0xf bound_ctrl:1
	s_waitcnt lgkmcnt(0)
	global_store_dwordx4 v[46:47], v[42:45], off offset:2048
	v_add_f32_dpp v33, v33, v33 quad_perm:[2,3,0,1] row_mask:0xf bank_mask:0xf bound_ctrl:1
	v_sub_f32_e32 v33, v163, v33
	v_cndmask_b32_e64 v32, v32, v33, s[92:93]
	v_mov_b32_e32 v33, v131
	ds_read_b128 v[46:49], v56 offset:13584
	ds_read_b128 v[230:233], v56 offset:13600
	ds_read_b128 v[234:237], v56 offset:13616
	v_pk_fma_f32 v[34:35], v[38:39], v[10:11], 0 op_sel_hi:[1,1,0]
	s_nop 0
	v_pk_fma_f32 v[34:35], v[40:41], v[12:13], v[34:35]
	s_nop 0
	v_pk_fma_f32 v[34:35], v[242:243], v[14:15], v[34:35]
	s_nop 0
	v_pk_fma_f32 v[34:35], v[244:245], v[16:17], v[34:35]
	s_nop 0
	v_pk_fma_f32 v[34:35], v[246:247], v[32:33], v[34:35]
	s_nop 0
	v_pk_fma_f32 v[34:35], v[248:249], 0, v[34:35] op_sel_hi:[1,0,1]
	s_nop 0
	v_add_f32_e32 v33, v34, v35
	s_nop 1
	v_add_f32_dpp v33, v33, v33 quad_perm:[1,0,3,2] row_mask:0xf bank_mask:0xf bound_ctrl:1
	s_nop 1
	v_add_f32_dpp v33, v33, v33 quad_perm:[2,3,0,1] row_mask:0xf bank_mask:0xf bound_ctrl:1
	v_sub_f32_e32 v33, v173, v33
	v_cndmask_b32_e64 v33, 0, v33, s[86:87]
	ds_read_b128 v[38:41], v56 offset:13840
	ds_read_b128 v[238:241], v56 offset:13856
	ds_read_b128 v[242:245], v56 offset:13872
	s_waitcnt lgkmcnt(5)
	v_pk_fma_f32 v[42:43], v[46:47], v[10:11], 0 op_sel_hi:[1,1,0]
	s_nop 0
	v_pk_fma_f32 v[42:43], v[48:49], v[12:13], v[42:43]
	s_waitcnt lgkmcnt(4)
	v_pk_fma_f32 v[42:43], v[230:231], v[14:15], v[42:43]
	s_nop 0
	v_pk_fma_f32 v[42:43], v[232:233], v[16:17], v[42:43]
	s_waitcnt lgkmcnt(3)
	v_pk_fma_f32 v[42:43], v[234:235], v[32:33], v[42:43]
	s_nop 0
	v_pk_fma_f32 v[42:43], v[236:237], 0, v[42:43] op_sel_hi:[1,0,1]
	s_nop 0
	v_add_f32_e32 v42, v42, v43
	s_nop 1
	v_add_f32_dpp v42, v42, v42 quad_perm:[1,0,3,2] row_mask:0xf bank_mask:0xf bound_ctrl:1
	s_nop 1
	v_add_f32_dpp v42, v42, v42 quad_perm:[2,3,0,1] row_mask:0xf bank_mask:0xf bound_ctrl:1
	v_sub_f32_e32 v42, v174, v42
	v_cndmask_b32_e64 v33, v33, v42, s[88:89]
	ds_read_b128 v[46:49], v56 offset:14096
	ds_read_b128 v[230:233], v56 offset:14112
	ds_read_b128 v[234:237], v56 offset:14128
	s_waitcnt lgkmcnt(5)
	v_pk_fma_f32 v[34:35], v[38:39], v[10:11], 0 op_sel_hi:[1,1,0]
	s_nop 0
	v_pk_fma_f32 v[34:35], v[40:41], v[12:13], v[34:35]
	s_waitcnt lgkmcnt(4)
	v_pk_fma_f32 v[34:35], v[238:239], v[14:15], v[34:35]
	s_nop 0
	v_pk_fma_f32 v[34:35], v[240:241], v[16:17], v[34:35]
	s_waitcnt lgkmcnt(3)
	v_pk_fma_f32 v[34:35], v[242:243], v[32:33], v[34:35]
	s_nop 0
	v_pk_fma_f32 v[34:35], v[244:245], 0, v[34:35] op_sel_hi:[1,0,1]
	s_nop 0
	v_add_f32_e32 v34, v34, v35
	s_nop 1
	v_add_f32_dpp v34, v34, v34 quad_perm:[1,0,3,2] row_mask:0xf bank_mask:0xf bound_ctrl:1
	s_nop 1
	v_add_f32_dpp v34, v34, v34 quad_perm:[2,3,0,1] row_mask:0xf bank_mask:0xf bound_ctrl:1
	v_sub_f32_e32 v34, v175, v34
	v_cndmask_b32_e64 v33, v33, v34, s[90:91]
	ds_read_b128 v[38:41], v56 offset:14352
	ds_read_b128 v[238:241], v56 offset:14368
	ds_read_b128 v[242:245], v56 offset:14384
	s_waitcnt lgkmcnt(5)
	v_pk_fma_f32 v[42:43], v[46:47], v[10:11], 0 op_sel_hi:[1,1,0]
	s_nop 0
	v_pk_fma_f32 v[42:43], v[48:49], v[12:13], v[42:43]
	s_waitcnt lgkmcnt(4)
	v_pk_fma_f32 v[42:43], v[230:231], v[14:15], v[42:43]
	s_nop 0
	v_pk_fma_f32 v[42:43], v[232:233], v[16:17], v[42:43]
	s_waitcnt lgkmcnt(3)
; #define SOLVE_LD(i_) do { _Pragma("unroll") for (int a4 = 0; a4 < ((i_) + 15) / 16; ++a4) lq[(i_) % 3][a4] = *(const LAS f32x4*)(LP + (i_) * 64 + 4 * a4); } while (0)
; __device__ __forceinline__ void gdn_prep_phase(LAS unsigned char* lds, const GdnPrepArgs& A, int bid, int G, const unsigned char* zero_page) {
;     ...
;         for (int i = 0; i < 64; ++i) {
;             if (i + 2 < 48) SOLVE_LD(i + 2);
;             else if (i + 1 >= 48 && i + 1 < 64) SOLVE_LD(i + 1);
;             float p0 = 0.f, p1 = 0.f;
; #pragma unroll
;             for (int a4 = 0; a4 < (i + 15) / 16; ++a4) { const f32x4 lv = lq[i % 3][a4];
;                 p0 = __builtin_fmaf(lv.x, t[4 * a4], p0); p1 = __builtin_fmaf(lv.y, t[4 * a4 + 1], p1); p0 = __builtin_fmaf(lv.z, t[4 * a4 + 2], p0); p1 = __builtin_fmaf(lv.w, t[4 * a4 + 3], p1); }
;             float p = quad_sum(p0 + p1);
;             const float ti = (i == j ? 1.f : 0.f) - p;
;             if (q == (i & 3)) t[i >> 2] = ti;
;             if ((i & 7) == 3 && !(pflg & 64)) {
;                 constexpr int kk = 0; const int k8 = i >> 3, b = w + 8 * (k8 & 1); v4u f; int off; (void)kk;
;                 if (k8 < 2)      { f = frag16_rm(lds + L_KN, QS_, b >> 2, b & 3, lane); off = B_KA + b * 1024; }
;                 else if (k8 < 4) { f = frag16_rm(lds + L_QN, QS_, b >> 2, b & 3, lane); off = B_QA + b * 1024; }
;                 else if (k8 < 6) { f = frag16_tr(lds + L_KN, QS_, b >> 1, b & 1, lane); off = B_KT + b * 1024; }
;                 else             { f = frag16_rm(lds + (k8 == 6 ? L_AF : L_AB), AS_, w >> 1, w & 1, lane); off = (k8 == 6 ? B_AF : B_AB) + w * 1024; }
;                 *(v4u*)(blob + off + lane * 16) = f; }
;             __builtin_amdgcn_sched_barrier(0);
;         }
	v_pk_fma_f32 v[42:43], v[234:235], v[32:33], v[42:43]
	s_nop 0
	v_pk_fma_f32 v[42:43], v[236:237], 0, v[42:43] op_sel_hi:[1,0,1]
	s_nop 0
	v_add_f32_e32 v42, v42, v43
	s_nop 1
	v_add_f32_dpp v42, v42, v42 quad_perm:[1,0,3,2] row_mask:0xf bank_mask:0xf bound_ctrl:1
	s_nop 1
	v_add_f32_dpp v42, v42, v42 quad_perm:[2,3,0,1] row_mask:0xf bank_mask:0xf bound_ctrl:1
	v_sub_f32_e32 v42, v176, v42
	v_cndmask_b32_e64 v33, v33, v42, s[92:93]
	ds_read_b128 v[46:49], v56 offset:14608
	ds_read_b128 v[230:233], v56 offset:14624
	ds_read_b128 v[234:237], v56 offset:14640
	s_waitcnt lgkmcnt(5)
	v_pk_fma_f32 v[34:35], v[38:39], v[10:11], 0 op_sel_hi:[1,1,0]
	s_nop 0
	v_pk_fma_f32 v[34:35], v[40:41], v[12:13], v[34:35]
	s_waitcnt lgkmcnt(4)
	v_pk_fma_f32 v[34:35], v[238:239], v[14:15], v[34:35]
	s_nop 0
	v_pk_fma_f32 v[34:35], v[240:241], v[16:17], v[34:35]
	s_waitcnt lgkmcnt(3)
	v_pk_fma_f32 v[34:35], v[242:243], v[32:33], v[34:35]
	s_nop 0
	v_pk_fma_f32 v[34:35], v[244:245], 0, v[34:35] op_sel_hi:[1,0,1]
	s_nop 0
	v_add_f32_e32 v34, v34, v35
	s_nop 1
	v_add_f32_dpp v34, v34, v34 quad_perm:[1,0,3,2] row_mask:0xf bank_mask:0xf bound_ctrl:1
	s_nop 1
	v_add_f32_dpp v34, v34, v34 quad_perm:[2,3,0,1] row_mask:0xf bank_mask:0xf bound_ctrl:1
	v_sub_f32_e32 v34, v177, v34
	v_cndmask_b32_e64 v246, 0, v34, s[86:87]
	ds_read_b128 v[38:41], v56 offset:14864
	ds_read_b128 v[238:241], v56 offset:14880
	ds_read_b128 v[242:245], v56 offset:14896
	v_mov_b32_e32 v247, v131
	s_waitcnt lgkmcnt(5)
	v_pk_fma_f32 v[42:43], v[46:47], v[10:11], 0 op_sel_hi:[1,1,0]
	s_nop 0
	v_pk_fma_f32 v[42:43], v[48:49], v[12:13], v[42:43]
	s_waitcnt lgkmcnt(4)
	v_pk_fma_f32 v[42:43], v[230:231], v[14:15], v[42:43]
	s_nop 0
	v_pk_fma_f32 v[42:43], v[232:233], v[16:17], v[42:43]
	s_waitcnt lgkmcnt(3)
	v_pk_fma_f32 v[42:43], v[234:235], v[32:33], v[42:43]
	s_nop 0
	v_pk_fma_f32 v[42:43], v[236:237], v[246:247], v[42:43]
	s_nop 0
	v_add_f32_e32 v42, v42, v43
	s_nop 1
	v_add_f32_dpp v42, v42, v42 quad_perm:[1,0,3,2] row_mask:0xf bank_mask:0xf bound_ctrl:1
	s_nop 1
	v_add_f32_dpp v42, v42, v42 quad_perm:[2,3,0,1] row_mask:0xf bank_mask:0xf bound_ctrl:1
	v_sub_f32_e32 v42, v178, v42
	v_cndmask_b32_e64 v246, v246, v42, s[88:89]
	ds_read_b128 v[46:49], v56 offset:15120
	ds_read_b128 v[230:233], v56 offset:15136
	ds_read_b128 v[234:237], v56 offset:15152
	s_waitcnt lgkmcnt(5)
	v_pk_fma_f32 v[34:35], v[38:39], v[10:11], 0 op_sel_hi:[1,1,0]
	s_nop 0
	v_pk_fma_f32 v[34:35], v[40:41], v[12:13], v[34:35]
	s_waitcnt lgkmcnt(4)
	v_pk_fma_f32 v[34:35], v[238:239], v[14:15], v[34:35]
	s_nop 0
	v_pk_fma_f32 v[34:35], v[240:241], v[16:17], v[34:35]
	s_waitcnt lgkmcnt(3)
	v_pk_fma_f32 v[34:35], v[242:243], v[32:33], v[34:35]
	s_nop 0
	v_pk_fma_f32 v[34:35], v[244:245], v[246:247], v[34:35]
	s_nop 0
	v_add_f32_e32 v34, v34, v35
	s_nop 1
	v_add_f32_dpp v34, v34, v34 quad_perm:[1,0,3,2] row_mask:0xf bank_mask:0xf bound_ctrl:1
	s_nop 1
	v_add_f32_dpp v34, v34, v34 quad_perm:[2,3,0,1] row_mask:0xf bank_mask:0xf bound_ctrl:1
	v_sub_f32_e32 v34, v179, v34
	v_cndmask_b32_e64 v34, v246, v34, s[90:91]
	ds_read_b128 v[238:241], v56 offset:15376
	ds_read_b128 v[242:245], v56 offset:15392
	ds_read_b128 v[246:249], v56 offset:15408
	v_mov_b32_e32 v35, v131
	s_waitcnt lgkmcnt(5)
	v_pk_fma_f32 v[40:41], v[46:47], v[10:11], 0 op_sel_hi:[1,1,0]
	s_mov_b32 s40, 0x12000
	v_pk_fma_f32 v[40:41], v[48:49], v[12:13], v[40:41]
	v_add_co_u32_e32 v8, vcc, s40, v8
	s_waitcnt lgkmcnt(4)
	v_pk_fma_f32 v[40:41], v[230:231], v[14:15], v[40:41]
	v_addc_co_u32_e32 v9, vcc, 0, v9, vcc
	v_pk_fma_f32 v[40:41], v[232:233], v[16:17], v[40:41]
	s_waitcnt lgkmcnt(3)
	v_pk_fma_f32 v[40:41], v[234:235], v[32:33], v[40:41]
	s_nop 0
	v_pk_fma_f32 v[40:41], v[236:237], v[34:35], v[40:41]
	s_nop 0
	v_add_f32_e32 v35, v40, v41
	ds_read_b64 v[40:41], v187
	ds_read_b64 v[42:43], v188
	v_add_f32_dpp v35, v35, v35 quad_perm:[1,0,3,2] row_mask:0xf bank_mask:0xf bound_ctrl:1
	s_waitcnt lgkmcnt(0)
	global_store_dwordx4 v[8:9], v[40:43], off offset:2048
	v_add_f32_dpp v35, v35, v35 quad_perm:[2,3,0,1] row_mask:0xf bank_mask:0xf bound_ctrl:1
	v_sub_f32_e32 v35, v180, v35
	v_cndmask_b32_e64 v34, v34, v35, s[92:93]
	ds_read_b128 v[44:47], v56 offset:15632
	ds_read_b128 v[230:233], v56 offset:15648
	ds_read_b128 v[234:237], v56 offset:15664
	v_mov_b32_e32 v35, v131
	v_pk_fma_f32 v[8:9], v[238:239], v[10:11], 0 op_sel_hi:[1,1,0]
	s_nop 0
	v_pk_fma_f32 v[8:9], v[240:241], v[12:13], v[8:9]
	s_nop 0
	v_pk_fma_f32 v[8:9], v[242:243], v[14:15], v[8:9]
	s_nop 0
	v_pk_fma_f32 v[8:9], v[244:245], v[16:17], v[8:9]
	s_nop 0
	v_pk_fma_f32 v[8:9], v[246:247], v[32:33], v[8:9]
	s_nop 0
	v_pk_fma_f32 v[8:9], v[248:249], v[34:35], v[8:9]
	s_nop 0
	v_add_f32_e32 v8, v8, v9
	s_nop 1
	v_add_f32_dpp v8, v8, v8 quad_perm:[1,0,3,2] row_mask:0xf bank_mask:0xf bound_ctrl:1
	s_nop 1
	v_add_f32_dpp v8, v8, v8 quad_perm:[2,3,0,1] row_mask:0xf bank_mask:0xf bound_ctrl:1
	v_sub_f32_e32 v8, v181, v8
	v_cndmask_b32_e64 v35, 0, v8, s[86:87]
	ds_read_b128 v[238:241], v56 offset:15888
	ds_read_b128 v[242:245], v56 offset:15904
	ds_read_b128 v[246:249], v56 offset:15920
	s_waitcnt lgkmcnt(5)
	v_pk_fma_f32 v[8:9], v[44:45], v[10:11], 0 op_sel_hi:[1,1,0]
	s_nop 0
	v_pk_fma_f32 v[8:9], v[46:47], v[12:13], v[8:9]
	s_waitcnt lgkmcnt(4)
	v_pk_fma_f32 v[8:9], v[230:231], v[14:15], v[8:9]
	s_nop 0
	v_pk_fma_f32 v[8:9], v[232:233], v[16:17], v[8:9]
	s_waitcnt lgkmcnt(3)
; #define SOLVE_LD(i_) do { _Pragma("unroll") for (int a4 = 0; a4 < ((i_) + 15) / 16; ++a4) lq[(i_) % 3][a4] = *(const LAS f32x4*)(LP + (i_) * 64 + 4 * a4); } while (0)
; __device__ __forceinline__ void gdn_prep_phase(LAS unsigned char* lds, const GdnPrepArgs& A, int bid, int G, const unsigned char* zero_page) {
;     ...
;         for (int i = 0; i < 64; ++i) {
;             if (i + 2 < 48) SOLVE_LD(i + 2);
;             else if (i + 1 >= 48 && i + 1 < 64) SOLVE_LD(i + 1);
;             float p0 = 0.f, p1 = 0.f;
; #pragma unroll
;             for (int a4 = 0; a4 < (i + 15) / 16; ++a4) { const f32x4 lv = lq[i % 3][a4];
;                 p0 = __builtin_fmaf(lv.x, t[4 * a4], p0); p1 = __builtin_fmaf(lv.y, t[4 * a4 + 1], p1); p0 = __builtin_fmaf(lv.z, t[4 * a4 + 2], p0); p1 = __builtin_fmaf(lv.w, t[4 * a4 + 3], p1); }
;             float p = quad_sum(p0 + p1);
;             const float ti = (i == j ? 1.f : 0.f) - p;
;             if (q == (i & 3)) t[i >> 2] = ti;
;             if ((i & 7) == 3 && !(pflg & 64)) {
;                 constexpr int kk = 0; const int k8 = i >> 3, b = w + 8 * (k8 & 1); v4u f; int off; (void)kk;
;                 if (k8 < 2)      { f = frag16_rm(lds + L_KN, QS_, b >> 2, b & 3, lane); off = B_KA + b * 1024; }
;                 else if (k8 < 4) { f = frag16_rm(lds + L_QN, QS_, b >> 2, b & 3, lane); off = B_QA + b * 1024; }
;                 else if (k8 < 6) { f = frag16_tr(lds + L_KN, QS_, b >> 1, b & 1, lane); off = B_KT + b * 1024; }
;                 else             { f = frag16_rm(lds + (k8 == 6 ? L_AF : L_AB), AS_, w >> 1, w & 1, lane); off = (k8 == 6 ? B_AF : B_AB) + w * 1024; }
;                 *(v4u*)(blob + off + lane * 16) = f; }
;             __builtin_amdgcn_sched_barrier(0);
;         }
	v_pk_fma_f32 v[8:9], v[234:235], v[32:33], v[8:9]
	s_nop 0
	v_pk_fma_f32 v[8:9], v[236:237], v[34:35], v[8:9]
	s_nop 0
	v_add_f32_e32 v8, v8, v9
	s_nop 1
	v_add_f32_dpp v8, v8, v8 quad_perm:[1,0,3,2] row_mask:0xf bank_mask:0xf bound_ctrl:1
	s_nop 1
	v_add_f32_dpp v8, v8, v8 quad_perm:[2,3,0,1] row_mask:0xf bank_mask:0xf bound_ctrl:1
	v_sub_f32_e32 v8, v182, v8
	v_cndmask_b32_e64 v35, v35, v8, s[88:89]
	ds_read_b128 v[44:47], v56 offset:16144
	ds_read_b128 v[230:233], v56 offset:16160
	ds_read_b128 v[234:237], v56 offset:16176
	s_waitcnt lgkmcnt(5)
	v_pk_fma_f32 v[8:9], v[238:239], v[10:11], 0 op_sel_hi:[1,1,0]
	s_nop 0
	v_pk_fma_f32 v[8:9], v[240:241], v[12:13], v[8:9]
	s_waitcnt lgkmcnt(4)
	v_pk_fma_f32 v[8:9], v[242:243], v[14:15], v[8:9]
	s_nop 0
	v_pk_fma_f32 v[8:9], v[244:245], v[16:17], v[8:9]
	s_waitcnt lgkmcnt(3)
	v_pk_fma_f32 v[8:9], v[246:247], v[32:33], v[8:9]
	s_nop 0
	v_pk_fma_f32 v[8:9], v[248:249], v[34:35], v[8:9]
	s_nop 0
	v_add_f32_e32 v8, v8, v9
	s_nop 1
	v_add_f32_dpp v8, v8, v8 quad_perm:[1,0,3,2] row_mask:0xf bank_mask:0xf bound_ctrl:1
	s_nop 1
	v_add_f32_dpp v8, v8, v8 quad_perm:[2,3,0,1] row_mask:0xf bank_mask:0xf bound_ctrl:1
	v_sub_f32_e32 v8, v183, v8
	v_cndmask_b32_e64 v35, v35, v8, s[90:91]
	s_nop 0
	s_waitcnt lgkmcnt(2)
	v_pk_fma_f32 v[8:9], v[44:45], v[10:11], 0 op_sel_hi:[1,1,0]
	s_nop 0
	v_pk_fma_f32 v[8:9], v[46:47], v[12:13], v[8:9]
	s_waitcnt lgkmcnt(1)
	v_pk_fma_f32 v[8:9], v[230:231], v[14:15], v[8:9]
	s_nop 0
	v_pk_fma_f32 v[8:9], v[232:233], v[16:17], v[8:9]
	s_waitcnt lgkmcnt(0)
	v_pk_fma_f32 v[8:9], v[234:235], v[32:33], v[8:9]
	s_nop 0
	v_pk_fma_f32 v[8:9], v[236:237], v[34:35], v[8:9]
	s_nop 0
	v_add_f32_e32 v2, v8, v9
	s_nop 1
	v_add_f32_dpp v2, v2, v2 quad_perm:[1,0,3,2] row_mask:0xf bank_mask:0xf bound_ctrl:1
	s_nop 1
	v_add_f32_dpp v2, v2, v2 quad_perm:[2,3,0,1] row_mask:0xf bank_mask:0xf bound_ctrl:1
	v_sub_f32_e32 v2, v184, v2
	v_cndmask_b32_e64 v2, v35, v2, s[92:93]
	s_branch .Ls4join
.Ls4v2:
	v_lshl_add_u64 v[6:7], s[40:41], 0, v[22:23]
	s_nop 0
	s_nop 0
	s_nop 1
	s_nop 1
	s_nop 0
	s_nop 1
	s_nop 1
	v_readlane_b32 s2, v255, 48
	v_add_u32_e32 v9, v63, v108
	ds_read2_b64 v[10:13], v9 offset1:4
	v_readlane_b32 s3, v255, 49
	s_nop 0
	v_lshl_add_u64 v[8:9], v[6:7], 0, s[2:3]
	s_waitcnt lgkmcnt(0)
	global_store_dwordx4 v[8:9], v[10:13], off
	s_nop 0
	s_nop 1
	s_nop 1
	s_nop 0
	s_nop 1
	s_nop 1
	s_nop 0
	s_nop 1
	s_nop 1
	s_nop 0
	s_nop 1
	s_nop 1
	s_nop 0
	s_nop 1
	s_nop 1
	v_mov_b32_e32 v5, v131
	s_nop 1
	s_nop 1
	v_mov_b32_e32 v5, v131
	s_nop 1
	s_nop 1
	v_mov_b32_e32 v5, v131
	v_add_u32_e32 v14, v63, v117
	ds_read2_b64 v[14:17], v14 offset1:4
	v_lshl_add_u64 v[32:33], v[6:7], 0, s[38:39]
	s_waitcnt lgkmcnt(0)
	global_store_dwordx4 v[32:33], v[14:17], off
	v_mov_b32_e32 v5, v131
	s_nop 1
	s_nop 1
	s_nop 0
	s_nop 1
	s_nop 1
	s_nop 0
	s_nop 1
	s_nop 1
	s_nop 0
	s_nop 1
	s_nop 1
	s_nop 0
	s_nop 1
	s_nop 1
	v_mov_b32_e32 v231, v131
	s_nop 0
	s_nop 0
	s_nop 1
	s_nop 1
	s_nop 0
	s_nop 0
	s_nop 1
	s_nop 1
	v_mov_b32_e32 v11, v131
	s_movk_i32 s40, 0x4000
	s_nop 0
	v_add_co_u32_e32 v12, vcc, s40, v8
	s_nop 0
	v_addc_co_u32_e32 v13, vcc, 0, v9, vcc
	s_nop 0
	v_add_u32_e32 v11, v62, v108
	v_add_u32_e32 v11, 0xc800, v11
	ds_read2_b64 v[34:37], v11 offset0:128 offset1:132
	s_waitcnt lgkmcnt(0)
	global_store_dwordx4 v[12:13], v[34:37], off
	v_mov_b32_e32 v11, v131
	s_nop 0
	s_nop 0
	s_nop 1
	s_nop 1
	s_nop 0
	s_nop 0
	s_nop 0
	s_nop 1
	s_nop 1
	s_nop 0
	s_nop 0
	s_nop 1
	s_nop 1
	s_nop 0
	s_nop 0
	s_nop 1
	s_nop 1
	s_nop 0
	s_nop 0
	s_nop 1
	s_nop 1
	v_mov_b32_e32 v17, v131
	s_nop 0
	s_nop 0
	s_nop 1
	s_nop 1
	v_mov_b32_e32 v17, v131
	s_nop 0
	s_nop 0
	s_nop 1
	s_nop 1
	v_mov_b32_e32 v13, v131
	v_add_co_u32_e32 v230, vcc, s40, v32
	s_nop 0
	v_addc_co_u32_e32 v231, vcc, 0, v33, vcc
	s_nop 1
	s_nop 1
	v_add_u32_e32 v13, v62, v117
	v_add_u32_e32 v13, 0xc800, v13
	ds_read2_b64 v[42:45], v13 offset0:128 offset1:132
	s_waitcnt lgkmcnt(0)
	global_store_dwordx4 v[230:231], v[42:45], off
	v_mov_b32_e32 v13, v131
	s_nop 0
	s_nop 0
	s_nop 1
	s_nop 1
	s_nop 0
	s_nop 0
	s_nop 0
	s_nop 1
	s_nop 1
	s_nop 0
	s_nop 0
	s_nop 1
	s_nop 1
	ds_read_b128 v[234:237], v56 offset:8480
	s_nop 0
	s_nop 0
	s_nop 1
	s_nop 1
	v_mov_b32_e32 v130, 0
	v_mov_b32_e32 v3, 0
	v_mov_b32_e32 v2, 0
	v_mov_b32_e32 v4, 0
	v_mov_b32_e32 v5, 0
	v_mov_b32_e32 v10, 0
	v_mov_b32_e32 v11, 0
	v_mov_b32_e32 v16, 0
	v_mov_b32_e32 v12, 0
	v_mov_b32_e32 v13, 0
	ds_read_b128 v[238:241], v56 offset:8736
	s_nop 0
	s_nop 0
	v_mov_b32_e32 v14, 0
	s_nop 1
	v_add_f32_dpp v14, v14, v14 quad_perm:[1,0,3,2] row_mask:0xf bank_mask:0xf bound_ctrl:1
	s_nop 1
	v_add_f32_dpp v14, v14, v14 quad_perm:[2,3,0,1] row_mask:0xf bank_mask:0xf bound_ctrl:1
	v_sub_f32_e32 v14, v144, v14
	v_cndmask_b32_e64 v246, 0, v14, s[86:87]
	v_mov_b32_e32 v247, v131
	ds_read_b128 v[242:245], v56 offset:8992
	s_nop 0
	s_waitcnt lgkmcnt(2)
	v_pk_fma_f32 v[42:43], v[234:235], v[246:247], 0 op_sel_hi:[1,1,0]
	s_nop 0
	v_pk_fma_f32 v[42:43], v[236:237], 0, v[42:43] op_sel_hi:[1,0,1]
	s_nop 0
	v_add_f32_e32 v42, v42, v43
	s_nop 1
	v_add_f32_dpp v42, v42, v42 quad_perm:[1,0,3,2] row_mask:0xf bank_mask:0xf bound_ctrl:1
	s_nop 1
	v_add_f32_dpp v42, v42, v42 quad_perm:[2,3,0,1] row_mask:0xf bank_mask:0xf bound_ctrl:1
	v_sub_f32_e32 v42, v145, v42
	v_cndmask_b32_e64 v246, v246, v42, s[88:89]
	ds_read_b128 v[234:237], v56 offset:9248
	s_nop 0
	s_waitcnt lgkmcnt(2)
; #define SOLVE_LD(i_) do { _Pragma("unroll") for (int a4 = 0; a4 < ((i_) + 15) / 16; ++a4) lq[(i_) % 3][a4] = *(const LAS f32x4*)(LP + (i_) * 64 + 4 * a4); } while (0)
; __device__ __forceinline__ void gdn_prep_phase(LAS unsigned char* lds, const GdnPrepArgs& A, int bid, int G, const unsigned char* zero_page) {
;     ...
;         for (int i = 0; i < 64; ++i) {
;             if (i + 2 < 48) SOLVE_LD(i + 2);
;             else if (i + 1 >= 48 && i + 1 < 64) SOLVE_LD(i + 1);
;             float p0 = 0.f, p1 = 0.f;
; #pragma unroll
;             for (int a4 = 0; a4 < (i + 15) / 16; ++a4) { const f32x4 lv = lq[i % 3][a4];
;                 p0 = __builtin_fmaf(lv.x, t[4 * a4], p0); p1 = __builtin_fmaf(lv.y, t[4 * a4 + 1], p1); p0 = __builtin_fmaf(lv.z, t[4 * a4 + 2], p0); p1 = __builtin_fmaf(lv.w, t[4 * a4 + 3], p1); }
;             float p = quad_sum(p0 + p1);
;             const float ti = (i == j ? 1.f : 0.f) - p;
;             if (q == (i & 3)) t[i >> 2] = ti;
;             if ((i & 7) == 3 && !(pflg & 64)) {
;                 constexpr int kk = 0; const int k8 = i >> 3, b = w + 8 * (k8 & 1); v4u f; int off; (void)kk;
;                 if (k8 < 2)      { f = frag16_rm(lds + L_KN, QS_, b >> 2, b & 3, lane); off = B_KA + b * 1024; }
;                 else if (k8 < 4) { f = frag16_rm(lds + L_QN, QS_, b >> 2, b & 3, lane); off = B_QA + b * 1024; }
;                 else if (k8 < 6) { f = frag16_tr(lds + L_KN, QS_, b >> 1, b & 1, lane); off = B_KT + b * 1024; }
;                 else             { f = frag16_rm(lds + (k8 == 6 ? L_AF : L_AB), AS_, w >> 1, w & 1, lane); off = (k8 == 6 ? B_AF : B_AB) + w * 1024; }
;                 *(v4u*)(blob + off + lane * 16) = f; }
;             __builtin_amdgcn_sched_barrier(0);
;         }
	v_pk_fma_f32 v[34:35], v[238:239], v[246:247], 0 op_sel_hi:[1,1,0]
	s_nop 0
	v_pk_fma_f32 v[34:35], v[240:241], 0, v[34:35] op_sel_hi:[1,0,1]
	s_nop 0
	v_add_f32_e32 v34, v34, v35
	s_nop 1
	v_add_f32_dpp v34, v34, v34 quad_perm:[1,0,3,2] row_mask:0xf bank_mask:0xf bound_ctrl:1
	s_nop 1
	v_add_f32_dpp v34, v34, v34 quad_perm:[2,3,0,1] row_mask:0xf bank_mask:0xf bound_ctrl:1
	v_sub_f32_e32 v34, v146, v34
	v_cndmask_b32_e64 v238, v246, v34, s[90:91]
	v_mov_b32_e32 v239, v131
	s_mov_b32 s40, 0x8000
	s_waitcnt lgkmcnt(1)
	v_pk_fma_f32 v[14:15], v[242:243], v[238:239], 0 op_sel_hi:[1,1,0]
	s_nop 0
	v_pk_fma_f32 v[14:15], v[244:245], 0, v[14:15] op_sel_hi:[1,0,1]
	s_nop 0
	v_add_f32_e32 v14, v14, v15
	v_add_u32_e32 v15, s71, v61
	ds_read_u16 v16, v15 offset:816
	ds_read_u16 v17, v15 offset:4352
	ds_read_u16 v239, v15 offset:4624
	ds_read_u16 v240, v15 offset:4896
	ds_read_u16 v241, v15 offset:5168
	ds_read_b128 v[38:41], v56 offset:9504
	ds_read_u16 v242, v15
	ds_read_u16 v243, v15 offset:272
	ds_read_u16 v15, v15 offset:544
	v_add_f32_dpp v14, v14, v14 quad_perm:[1,0,3,2] row_mask:0xf bank_mask:0xf bound_ctrl:1
	s_waitcnt lgkmcnt(4)
	v_perm_b32 v241, v241, v240, s33
	v_perm_b32 v240, v239, v17, s33
	v_add_f32_dpp v14, v14, v14 quad_perm:[2,3,0,1] row_mask:0xf bank_mask:0xf bound_ctrl:1
	v_sub_f32_e32 v14, v147, v14
	s_waitcnt lgkmcnt(0)
	v_perm_b32 v239, v16, v15, s33
	v_add_co_u32_e32 v16, vcc, s40, v8
	v_cndmask_b32_e64 v14, v238, v14, s[92:93]
	v_perm_b32 v238, v243, v242, s33
	v_addc_co_u32_e32 v17, vcc, 0, v9, vcc
	global_store_dwordx4 v[16:17], v[238:241], off offset:2048
	v_mov_b32_e32 v15, v131
	ds_read_b128 v[246:249], v56 offset:9760
	s_nop 0
	s_nop 0
	v_pk_fma_f32 v[16:17], v[234:235], v[14:15], 0 op_sel_hi:[1,1,0]
	s_nop 0
	v_pk_fma_f32 v[16:17], v[236:237], 0, v[16:17] op_sel_hi:[1,0,1]
	s_nop 0
	v_add_f32_e32 v15, v16, v17
	s_nop 1
	v_add_f32_dpp v15, v15, v15 quad_perm:[1,0,3,2] row_mask:0xf bank_mask:0xf bound_ctrl:1
	s_nop 1
	v_add_f32_dpp v15, v15, v15 quad_perm:[2,3,0,1] row_mask:0xf bank_mask:0xf bound_ctrl:1
	v_sub_f32_e32 v15, v148, v15
	v_cndmask_b32_e64 v15, 0, v15, s[86:87]
	ds_read_b128 v[234:237], v56 offset:10016
	s_nop 0
	s_nop 0
	s_nop 0
	v_pk_fma_f32 v[16:17], v[38:39], v[14:15], 0 op_sel_hi:[1,1,0]
	s_nop 0
	v_pk_fma_f32 v[16:17], v[40:41], 0, v[16:17] op_sel_hi:[1,0,1]
	s_nop 0
	v_add_f32_e32 v16, v16, v17
	s_nop 1
	v_add_f32_dpp v16, v16, v16 quad_perm:[1,0,3,2] row_mask:0xf bank_mask:0xf bound_ctrl:1
	s_nop 1
	v_add_f32_dpp v16, v16, v16 quad_perm:[2,3,0,1] row_mask:0xf bank_mask:0xf bound_ctrl:1
	v_sub_f32_e32 v16, v149, v16
	v_cndmask_b32_e64 v15, v15, v16, s[88:89]
	ds_read_b128 v[46:49], v56 offset:10272
	s_nop 0
	s_waitcnt lgkmcnt(2)
	v_pk_fma_f32 v[16:17], v[246:247], v[14:15], 0 op_sel_hi:[1,1,0]
	s_nop 0
	v_pk_fma_f32 v[16:17], v[248:249], 0, v[16:17] op_sel_hi:[1,0,1]
	s_nop 0
	v_add_f32_e32 v16, v16, v17
	s_nop 1
	v_add_f32_dpp v16, v16, v16 quad_perm:[1,0,3,2] row_mask:0xf bank_mask:0xf bound_ctrl:1
	s_nop 1
	v_add_f32_dpp v16, v16, v16 quad_perm:[2,3,0,1] row_mask:0xf bank_mask:0xf bound_ctrl:1
	v_sub_f32_e32 v16, v150, v16
	v_cndmask_b32_e64 v15, v15, v16, s[90:91]
	ds_read_b128 v[246:249], v56 offset:10528
	s_nop 0
	s_waitcnt lgkmcnt(2)
	v_pk_fma_f32 v[16:17], v[234:235], v[14:15], 0 op_sel_hi:[1,1,0]
	s_nop 0
	v_pk_fma_f32 v[16:17], v[236:237], 0, v[16:17] op_sel_hi:[1,0,1]
	s_nop 0
	v_add_f32_e32 v16, v16, v17
	s_nop 1
	v_add_f32_dpp v16, v16, v16 quad_perm:[1,0,3,2] row_mask:0xf bank_mask:0xf bound_ctrl:1
	s_nop 1
	v_add_f32_dpp v16, v16, v16 quad_perm:[2,3,0,1] row_mask:0xf bank_mask:0xf bound_ctrl:1
	v_sub_f32_e32 v16, v151, v16
	v_cndmask_b32_e64 v15, v15, v16, s[92:93]
	ds_read_b128 v[234:237], v56 offset:10784
	s_nop 0
	s_waitcnt lgkmcnt(2)
	v_pk_fma_f32 v[16:17], v[46:47], v[14:15], 0 op_sel_hi:[1,1,0]
	s_nop 0
	v_pk_fma_f32 v[16:17], v[48:49], 0, v[16:17] op_sel_hi:[1,0,1]
	s_nop 0
	v_add_f32_e32 v16, v16, v17
	s_nop 1
	v_add_f32_dpp v16, v16, v16 quad_perm:[1,0,3,2] row_mask:0xf bank_mask:0xf bound_ctrl:1
	s_nop 1
	v_add_f32_dpp v16, v16, v16 quad_perm:[2,3,0,1] row_mask:0xf bank_mask:0xf bound_ctrl:1
	v_sub_f32_e32 v16, v152, v16
	v_cndmask_b32_e64 v16, 0, v16, s[86:87]
	v_mov_b32_e32 v17, v131
	ds_read_b128 v[46:49], v56 offset:11040
	s_nop 0
	s_waitcnt lgkmcnt(2)
	v_pk_fma_f32 v[238:239], v[246:247], v[14:15], 0 op_sel_hi:[1,1,0]
	s_nop 0
	v_pk_fma_f32 v[238:239], v[248:249], v[16:17], v[238:239]
	s_nop 0
	v_add_f32_e32 v17, v238, v239
	s_nop 1
	v_add_f32_dpp v17, v17, v17 quad_perm:[1,0,3,2] row_mask:0xf bank_mask:0xf bound_ctrl:1
	s_nop 1
	v_add_f32_dpp v17, v17, v17 quad_perm:[2,3,0,1] row_mask:0xf bank_mask:0xf bound_ctrl:1
	v_sub_f32_e32 v17, v153, v17
	v_cndmask_b32_e64 v16, v16, v17, s[88:89]
	v_mov_b32_e32 v17, v131
	ds_read_b128 v[246:249], v56 offset:11296
	s_nop 0
	s_waitcnt lgkmcnt(2)
	v_pk_fma_f32 v[42:43], v[234:235], v[14:15], 0 op_sel_hi:[1,1,0]
	s_nop 0
	v_pk_fma_f32 v[42:43], v[236:237], v[16:17], v[42:43]
	s_nop 0
	v_add_f32_e32 v17, v42, v43
	s_nop 1
	v_add_f32_dpp v17, v17, v17 quad_perm:[1,0,3,2] row_mask:0xf bank_mask:0xf bound_ctrl:1
	s_nop 1
	v_add_f32_dpp v17, v17, v17 quad_perm:[2,3,0,1] row_mask:0xf bank_mask:0xf bound_ctrl:1
	v_sub_f32_e32 v17, v154, v17
	v_cndmask_b32_e64 v16, v16, v17, s[90:91]
	v_mov_b32_e32 v17, v131
	v_add_u32_e32 v38, s72, v61
	v_add_co_u32_e32 v32, vcc, s40, v32
	s_waitcnt lgkmcnt(1)
; #define SOLVE_LD(i_) do { _Pragma("unroll") for (int a4 = 0; a4 < ((i_) + 15) / 16; ++a4) lq[(i_) % 3][a4] = *(const LAS f32x4*)(LP + (i_) * 64 + 4 * a4); } while (0)
; __device__ __forceinline__ void gdn_prep_phase(LAS unsigned char* lds, const GdnPrepArgs& A, int bid, int G, const unsigned char* zero_page) {
;     ...
;         for (int i = 0; i < 64; ++i) {
;             if (i + 2 < 48) SOLVE_LD(i + 2);
;             else if (i + 1 >= 48 && i + 1 < 64) SOLVE_LD(i + 1);
;             float p0 = 0.f, p1 = 0.f;
; #pragma unroll
;             for (int a4 = 0; a4 < (i + 15) / 16; ++a4) { const f32x4 lv = lq[i % 3][a4];
;                 p0 = __builtin_fmaf(lv.x, t[4 * a4], p0); p1 = __builtin_fmaf(lv.y, t[4 * a4 + 1], p1); p0 = __builtin_fmaf(lv.z, t[4 * a4 + 2], p0); p1 = __builtin_fmaf(lv.w, t[4 * a4 + 3], p1); }
;             float p = quad_sum(p0 + p1);
;             const float ti = (i == j ? 1.f : 0.f) - p;
;             if (q == (i & 3)) t[i >> 2] = ti;
;             if ((i & 7) == 3 && !(pflg & 64)) {
;                 constexpr int kk = 0; const int k8 = i >> 3, b = w + 8 * (k8 & 1); v4u f; int off; (void)kk;
;                 if (k8 < 2)      { f = frag16_rm(lds + L_KN, QS_, b >> 2, b & 3, lane); off = B_KA + b * 1024; }
;                 else if (k8 < 4) { f = frag16_rm(lds + L_QN, QS_, b >> 2, b & 3, lane); off = B_QA + b * 1024; }
;                 else if (k8 < 6) { f = frag16_tr(lds + L_KN, QS_, b >> 1, b & 1, lane); off = B_KT + b * 1024; }
;                 else             { f = frag16_rm(lds + (k8 == 6 ? L_AF : L_AB), AS_, w >> 1, w & 1, lane); off = (k8 == 6 ? B_AF : B_AB) + w * 1024; }
;                 *(v4u*)(blob + off + lane * 16) = f; }
;             __builtin_amdgcn_sched_barrier(0);
;         }
	v_pk_fma_f32 v[34:35], v[46:47], v[14:15], 0 op_sel_hi:[1,1,0]
	v_addc_co_u32_e32 v33, vcc, 0, v33, vcc
	v_pk_fma_f32 v[34:35], v[48:49], v[16:17], v[34:35]
	s_nop 0
	v_add_f32_e32 v17, v34, v35
	ds_read_u16 v39, v38 offset:816
	ds_read_u16 v40, v38 offset:4352
	ds_read_u16 v46, v38 offset:4624
	ds_read_u16 v41, v38 offset:4896
	ds_read_u16 v47, v38 offset:5168
	ds_read_b128 v[34:37], v56 offset:11552
	ds_read_u16 v48, v38
	ds_read_u16 v49, v38 offset:272
	ds_read_u16 v38, v38 offset:544
	v_add_f32_dpp v17, v17, v17 quad_perm:[1,0,3,2] row_mask:0xf bank_mask:0xf bound_ctrl:1
	s_waitcnt lgkmcnt(4)
	v_perm_b32 v41, v47, v41, s33
	v_perm_b32 v40, v46, v40, s33
	v_add_f32_dpp v17, v17, v17 quad_perm:[2,3,0,1] row_mask:0xf bank_mask:0xf bound_ctrl:1
	v_sub_f32_e32 v17, v155, v17
	v_cndmask_b32_e64 v16, v16, v17, s[92:93]
	s_waitcnt lgkmcnt(0)
	v_perm_b32 v39, v39, v38, s33
	v_perm_b32 v38, v49, v48, s33
	global_store_dwordx4 v[32:33], v[38:41], off offset:2048
	v_mov_b32_e32 v17, v131
	ds_read_b128 v[234:237], v56 offset:11808
	s_nop 0
	s_nop 0
	v_pk_fma_f32 v[32:33], v[246:247], v[14:15], 0 op_sel_hi:[1,1,0]
	s_nop 0
	v_pk_fma_f32 v[32:33], v[248:249], v[16:17], v[32:33]
	s_nop 0
	v_add_f32_e32 v17, v32, v33
	s_nop 1
	v_add_f32_dpp v17, v17, v17 quad_perm:[1,0,3,2] row_mask:0xf bank_mask:0xf bound_ctrl:1
	s_nop 1
	v_add_f32_dpp v17, v17, v17 quad_perm:[2,3,0,1] row_mask:0xf bank_mask:0xf bound_ctrl:1
	v_sub_f32_e32 v17, v156, v17
	v_cndmask_b32_e64 v17, 0, v17, s[86:87]
	ds_read_b128 v[246:249], v56 offset:12064
	s_nop 0
	s_nop 0
	s_nop 0
	v_pk_fma_f32 v[32:33], v[34:35], v[14:15], 0 op_sel_hi:[1,1,0]
	s_nop 0
	v_pk_fma_f32 v[32:33], v[36:37], v[16:17], v[32:33]
	s_nop 0
	v_add_f32_e32 v32, v32, v33
	s_nop 1
	v_add_f32_dpp v32, v32, v32 quad_perm:[1,0,3,2] row_mask:0xf bank_mask:0xf bound_ctrl:1
	s_nop 1
	v_add_f32_dpp v32, v32, v32 quad_perm:[2,3,0,1] row_mask:0xf bank_mask:0xf bound_ctrl:1
	v_sub_f32_e32 v32, v157, v32
	v_cndmask_b32_e64 v17, v17, v32, s[88:89]
	s_nop 0
	s_nop 0
	s_waitcnt lgkmcnt(1)
	v_pk_fma_f32 v[32:33], v[234:235], v[14:15], 0 op_sel_hi:[1,1,0]
	s_nop 0
	v_pk_fma_f32 v[32:33], v[236:237], v[16:17], v[32:33]
	s_nop 0
	v_add_f32_e32 v32, v32, v33
	s_nop 1
	v_add_f32_dpp v32, v32, v32 quad_perm:[1,0,3,2] row_mask:0xf bank_mask:0xf bound_ctrl:1
	s_nop 1
	v_add_f32_dpp v32, v32, v32 quad_perm:[2,3,0,1] row_mask:0xf bank_mask:0xf bound_ctrl:1
	v_sub_f32_e32 v32, v158, v32
	v_cndmask_b32_e64 v17, v17, v32, s[90:91]
	ds_read_b128 v[40:43], v56 offset:12320
	s_nop 0
	s_waitcnt lgkmcnt(1)
	v_pk_fma_f32 v[44:45], v[246:247], v[14:15], 0 op_sel_hi:[1,1,0]
	s_nop 0
	v_pk_fma_f32 v[44:45], v[248:249], v[16:17], v[44:45]
	s_nop 0
	v_add_f32_e32 v44, v44, v45
	s_nop 1
	v_add_f32_dpp v44, v44, v44 quad_perm:[1,0,3,2] row_mask:0xf bank_mask:0xf bound_ctrl:1
	s_nop 1
	v_add_f32_dpp v44, v44, v44 quad_perm:[2,3,0,1] row_mask:0xf bank_mask:0xf bound_ctrl:1
	v_sub_f32_e32 v44, v159, v44
	v_cndmask_b32_e64 v17, v17, v44, s[92:93]
	ds_read_b128 v[234:237], v56 offset:12576
	ds_read_b128 v[238:241], v56 offset:12592
	s_nop 0
	s_waitcnt lgkmcnt(2)
	v_pk_fma_f32 v[32:33], v[40:41], v[14:15], 0 op_sel_hi:[1,1,0]
	s_nop 0
	v_pk_fma_f32 v[32:33], v[42:43], v[16:17], v[32:33]
	s_nop 0
	v_add_f32_e32 v32, v32, v33
	s_nop 1
	v_add_f32_dpp v32, v32, v32 quad_perm:[1,0,3,2] row_mask:0xf bank_mask:0xf bound_ctrl:1
	s_nop 1
	v_add_f32_dpp v32, v32, v32 quad_perm:[2,3,0,1] row_mask:0xf bank_mask:0xf bound_ctrl:1
	v_sub_f32_e32 v32, v160, v32
	v_cndmask_b32_e64 v48, 0, v32, s[86:87]
	ds_read_b128 v[40:43], v56 offset:12832
	ds_read_b128 v[242:245], v56 offset:12848
	v_mov_b32_e32 v49, v131
	s_nop 0
	s_waitcnt lgkmcnt(3)
	v_pk_fma_f32 v[44:45], v[234:235], v[14:15], 0 op_sel_hi:[1,1,0]
	s_nop 0
	v_pk_fma_f32 v[44:45], v[236:237], v[16:17], v[44:45]
	s_waitcnt lgkmcnt(2)
	v_pk_fma_f32 v[44:45], v[238:239], v[48:49], v[44:45]
	s_nop 0
	v_pk_fma_f32 v[44:45], v[240:241], 0, v[44:45] op_sel_hi:[1,0,1]
	s_nop 0
	v_add_f32_e32 v44, v44, v45
	s_nop 1
	v_add_f32_dpp v44, v44, v44 quad_perm:[1,0,3,2] row_mask:0xf bank_mask:0xf bound_ctrl:1
	s_nop 1
	v_add_f32_dpp v44, v44, v44 quad_perm:[2,3,0,1] row_mask:0xf bank_mask:0xf bound_ctrl:1
	v_sub_f32_e32 v44, v161, v44
	v_cndmask_b32_e64 v48, v48, v44, s[88:89]
	ds_read_b128 v[234:237], v56 offset:13088
	ds_read_b128 v[238:241], v56 offset:13104
	s_nop 0
	s_waitcnt lgkmcnt(3)
	v_pk_fma_f32 v[32:33], v[40:41], v[14:15], 0 op_sel_hi:[1,1,0]
	s_nop 0
	v_pk_fma_f32 v[32:33], v[42:43], v[16:17], v[32:33]
	s_waitcnt lgkmcnt(2)
	v_pk_fma_f32 v[32:33], v[242:243], v[48:49], v[32:33]
	s_nop 0
	v_pk_fma_f32 v[32:33], v[244:245], 0, v[32:33] op_sel_hi:[1,0,1]
	s_nop 0
	v_add_f32_e32 v32, v32, v33
	s_nop 1
	v_add_f32_dpp v32, v32, v32 quad_perm:[1,0,3,2] row_mask:0xf bank_mask:0xf bound_ctrl:1
	s_nop 1
	v_add_f32_dpp v32, v32, v32 quad_perm:[2,3,0,1] row_mask:0xf bank_mask:0xf bound_ctrl:1
	v_sub_f32_e32 v32, v162, v32
	v_cndmask_b32_e64 v32, v48, v32, s[90:91]
	v_mov_b32_e32 v33, v131
	ds_read_b128 v[242:245], v56 offset:13344
	ds_read_b128 v[246:249], v56 offset:13360
	s_mov_b32 s40, 0xe000
	v_add_co_u32_e32 v46, vcc, s40, v8
	s_waitcnt lgkmcnt(3)
	v_pk_fma_f32 v[42:43], v[234:235], v[14:15], 0 op_sel_hi:[1,1,0]
	v_addc_co_u32_e32 v47, vcc, 0, v9, vcc
	v_pk_fma_f32 v[42:43], v[236:237], v[16:17], v[42:43]
	s_waitcnt lgkmcnt(2)
	v_pk_fma_f32 v[42:43], v[238:239], v[32:33], v[42:43]
	s_nop 0
	v_pk_fma_f32 v[42:43], v[240:241], 0, v[42:43] op_sel_hi:[1,0,1]
	s_nop 0
	v_add_f32_e32 v33, v42, v43
	ds_read_b64 v[42:43], v185
	ds_read_b64 v[44:45], v186
	v_add_f32_dpp v33, v33, v33 quad_perm:[1,0,3,2] row_mask:0xf bank_mask:0xf bound_ctrl:1
	s_waitcnt lgkmcnt(0)
; #define SOLVE_LD(i_) do { _Pragma("unroll") for (int a4 = 0; a4 < ((i_) + 15) / 16; ++a4) lq[(i_) % 3][a4] = *(const LAS f32x4*)(LP + (i_) * 64 + 4 * a4); } while (0)
; __device__ __forceinline__ void gdn_prep_phase(LAS unsigned char* lds, const GdnPrepArgs& A, int bid, int G, const unsigned char* zero_page) {
;     ...
;         for (int i = 0; i < 64; ++i) {
;             if (i + 2 < 48) SOLVE_LD(i + 2);
;             else if (i + 1 >= 48 && i + 1 < 64) SOLVE_LD(i + 1);
;             float p0 = 0.f, p1 = 0.f;
; #pragma unroll
;             for (int a4 = 0; a4 < (i + 15) / 16; ++a4) { const f32x4 lv = lq[i % 3][a4];
;                 p0 = __builtin_fmaf(lv.x, t[4 * a4], p0); p1 = __builtin_fmaf(lv.y, t[4 * a4 + 1], p1); p0 = __builtin_fmaf(lv.z, t[4 * a4 + 2], p0); p1 = __builtin_fmaf(lv.w, t[4 * a4 + 3], p1); }
;             float p = quad_sum(p0 + p1);
;             const float ti = (i == j ? 1.f : 0.f) - p;
;             if (q == (i & 3)) t[i >> 2] = ti;
;             if ((i & 7) == 3 && !(pflg & 64)) {
;                 constexpr int kk = 0; const int k8 = i >> 3, b = w + 8 * (k8 & 1); v4u f; int off; (void)kk;
;                 if (k8 < 2)      { f = frag16_rm(lds + L_KN, QS_, b >> 2, b & 3, lane); off = B_KA + b * 1024; }
;                 else if (k8 < 4) { f = frag16_rm(lds + L_QN, QS_, b >> 2, b & 3, lane); off = B_QA + b * 1024; }
;                 else if (k8 < 6) { f = frag16_tr(lds + L_KN, QS_, b >> 1, b & 1, lane); off = B_KT + b * 1024; }
;                 else             { f = frag16_rm(lds + (k8 == 6 ? L_AF : L_AB), AS_, w >> 1, w & 1, lane); off = (k8 == 6 ? B_AF : B_AB) + w * 1024; }
;                 *(v4u*)(blob + off + lane * 16) = f; }
;             __builtin_amdgcn_sched_barrier(0);
;         }
	global_store_dwordx4 v[46:47], v[42:45], off offset:2048
	v_add_f32_dpp v33, v33, v33 quad_perm:[2,3,0,1] row_mask:0xf bank_mask:0xf bound_ctrl:1
	v_sub_f32_e32 v33, v163, v33
	v_cndmask_b32_e64 v32, v32, v33, s[92:93]
	v_mov_b32_e32 v33, v131
	ds_read_b128 v[230:233], v56 offset:13600
	ds_read_b128 v[234:237], v56 offset:13616
	s_nop 0
	s_nop 0
	v_pk_fma_f32 v[34:35], v[242:243], v[14:15], 0 op_sel_hi:[1,1,0]
	s_nop 0
	v_pk_fma_f32 v[34:35], v[244:245], v[16:17], v[34:35]
	s_nop 0
	v_pk_fma_f32 v[34:35], v[246:247], v[32:33], v[34:35]
	s_nop 0
	v_pk_fma_f32 v[34:35], v[248:249], 0, v[34:35] op_sel_hi:[1,0,1]
	s_nop 0
	v_add_f32_e32 v33, v34, v35
	s_nop 1
	v_add_f32_dpp v33, v33, v33 quad_perm:[1,0,3,2] row_mask:0xf bank_mask:0xf bound_ctrl:1
	s_nop 1
	v_add_f32_dpp v33, v33, v33 quad_perm:[2,3,0,1] row_mask:0xf bank_mask:0xf bound_ctrl:1
	v_sub_f32_e32 v33, v173, v33
	v_cndmask_b32_e64 v33, 0, v33, s[86:87]
	ds_read_b128 v[238:241], v56 offset:13856
	ds_read_b128 v[242:245], v56 offset:13872
	s_nop 0
	s_waitcnt lgkmcnt(3)
	v_pk_fma_f32 v[42:43], v[230:231], v[14:15], 0 op_sel_hi:[1,1,0]
	s_nop 0
	v_pk_fma_f32 v[42:43], v[232:233], v[16:17], v[42:43]
	s_waitcnt lgkmcnt(2)
	v_pk_fma_f32 v[42:43], v[234:235], v[32:33], v[42:43]
	s_nop 0
	v_pk_fma_f32 v[42:43], v[236:237], 0, v[42:43] op_sel_hi:[1,0,1]
	s_nop 0
	v_add_f32_e32 v42, v42, v43
	s_nop 1
	v_add_f32_dpp v42, v42, v42 quad_perm:[1,0,3,2] row_mask:0xf bank_mask:0xf bound_ctrl:1
	s_nop 1
	v_add_f32_dpp v42, v42, v42 quad_perm:[2,3,0,1] row_mask:0xf bank_mask:0xf bound_ctrl:1
	v_sub_f32_e32 v42, v174, v42
	v_cndmask_b32_e64 v33, v33, v42, s[88:89]
	ds_read_b128 v[230:233], v56 offset:14112
	ds_read_b128 v[234:237], v56 offset:14128
	s_nop 0
	s_waitcnt lgkmcnt(3)
	v_pk_fma_f32 v[34:35], v[238:239], v[14:15], 0 op_sel_hi:[1,1,0]
	s_nop 0
	v_pk_fma_f32 v[34:35], v[240:241], v[16:17], v[34:35]
	s_waitcnt lgkmcnt(2)
	v_pk_fma_f32 v[34:35], v[242:243], v[32:33], v[34:35]
	s_nop 0
	v_pk_fma_f32 v[34:35], v[244:245], 0, v[34:35] op_sel_hi:[1,0,1]
	s_nop 0
	v_add_f32_e32 v34, v34, v35
	s_nop 1
	v_add_f32_dpp v34, v34, v34 quad_perm:[1,0,3,2] row_mask:0xf bank_mask:0xf bound_ctrl:1
	s_nop 1
	v_add_f32_dpp v34, v34, v34 quad_perm:[2,3,0,1] row_mask:0xf bank_mask:0xf bound_ctrl:1
	v_sub_f32_e32 v34, v175, v34
	v_cndmask_b32_e64 v33, v33, v34, s[90:91]
	ds_read_b128 v[238:241], v56 offset:14368
	ds_read_b128 v[242:245], v56 offset:14384
	s_nop 0
	s_waitcnt lgkmcnt(3)
	v_pk_fma_f32 v[42:43], v[230:231], v[14:15], 0 op_sel_hi:[1,1,0]
	s_nop 0
	v_pk_fma_f32 v[42:43], v[232:233], v[16:17], v[42:43]
	s_waitcnt lgkmcnt(2)
	v_pk_fma_f32 v[42:43], v[234:235], v[32:33], v[42:43]
	s_nop 0
	v_pk_fma_f32 v[42:43], v[236:237], 0, v[42:43] op_sel_hi:[1,0,1]
	s_nop 0
	v_add_f32_e32 v42, v42, v43
	s_nop 1
	v_add_f32_dpp v42, v42, v42 quad_perm:[1,0,3,2] row_mask:0xf bank_mask:0xf bound_ctrl:1
	s_nop 1
	v_add_f32_dpp v42, v42, v42 quad_perm:[2,3,0,1] row_mask:0xf bank_mask:0xf bound_ctrl:1
	v_sub_f32_e32 v42, v176, v42
	v_cndmask_b32_e64 v33, v33, v42, s[92:93]
	ds_read_b128 v[230:233], v56 offset:14624
	ds_read_b128 v[234:237], v56 offset:14640
	s_nop 0
	s_waitcnt lgkmcnt(3)
	v_pk_fma_f32 v[34:35], v[238:239], v[14:15], 0 op_sel_hi:[1,1,0]
	s_nop 0
	v_pk_fma_f32 v[34:35], v[240:241], v[16:17], v[34:35]
	s_waitcnt lgkmcnt(2)
	v_pk_fma_f32 v[34:35], v[242:243], v[32:33], v[34:35]
	s_nop 0
	v_pk_fma_f32 v[34:35], v[244:245], 0, v[34:35] op_sel_hi:[1,0,1]
	s_nop 0
	v_add_f32_e32 v34, v34, v35
	s_nop 1
	v_add_f32_dpp v34, v34, v34 quad_perm:[1,0,3,2] row_mask:0xf bank_mask:0xf bound_ctrl:1
	s_nop 1
	v_add_f32_dpp v34, v34, v34 quad_perm:[2,3,0,1] row_mask:0xf bank_mask:0xf bound_ctrl:1
	v_sub_f32_e32 v34, v177, v34
	v_cndmask_b32_e64 v246, 0, v34, s[86:87]
	ds_read_b128 v[238:241], v56 offset:14880
	ds_read_b128 v[242:245], v56 offset:14896
	v_mov_b32_e32 v247, v131
	s_nop 0
	s_waitcnt lgkmcnt(3)
	v_pk_fma_f32 v[42:43], v[230:231], v[14:15], 0 op_sel_hi:[1,1,0]
	s_nop 0
	v_pk_fma_f32 v[42:43], v[232:233], v[16:17], v[42:43]
	s_waitcnt lgkmcnt(2)
	v_pk_fma_f32 v[42:43], v[234:235], v[32:33], v[42:43]
	s_nop 0
	v_pk_fma_f32 v[42:43], v[236:237], v[246:247], v[42:43]
	s_nop 0
	v_add_f32_e32 v42, v42, v43
	s_nop 1
	v_add_f32_dpp v42, v42, v42 quad_perm:[1,0,3,2] row_mask:0xf bank_mask:0xf bound_ctrl:1
	s_nop 1
	v_add_f32_dpp v42, v42, v42 quad_perm:[2,3,0,1] row_mask:0xf bank_mask:0xf bound_ctrl:1
	v_sub_f32_e32 v42, v178, v42
	v_cndmask_b32_e64 v246, v246, v42, s[88:89]
	ds_read_b128 v[230:233], v56 offset:15136
	ds_read_b128 v[234:237], v56 offset:15152
	s_nop 0
	s_waitcnt lgkmcnt(3)
	v_pk_fma_f32 v[34:35], v[238:239], v[14:15], 0 op_sel_hi:[1,1,0]
	s_nop 0
	v_pk_fma_f32 v[34:35], v[240:241], v[16:17], v[34:35]
	s_waitcnt lgkmcnt(2)
	v_pk_fma_f32 v[34:35], v[242:243], v[32:33], v[34:35]
	s_nop 0
	v_pk_fma_f32 v[34:35], v[244:245], v[246:247], v[34:35]
	s_nop 0
	v_add_f32_e32 v34, v34, v35
	s_nop 1
	v_add_f32_dpp v34, v34, v34 quad_perm:[1,0,3,2] row_mask:0xf bank_mask:0xf bound_ctrl:1
	s_nop 1
	v_add_f32_dpp v34, v34, v34 quad_perm:[2,3,0,1] row_mask:0xf bank_mask:0xf bound_ctrl:1
	v_sub_f32_e32 v34, v179, v34
	v_cndmask_b32_e64 v34, v246, v34, s[90:91]
	ds_read_b128 v[242:245], v56 offset:15392
	ds_read_b128 v[246:249], v56 offset:15408
	v_mov_b32_e32 v35, v131
	s_mov_b32 s40, 0x12000
	v_add_co_u32_e32 v8, vcc, s40, v8
	s_waitcnt lgkmcnt(3)
	v_pk_fma_f32 v[40:41], v[230:231], v[14:15], 0 op_sel_hi:[1,1,0]
	v_addc_co_u32_e32 v9, vcc, 0, v9, vcc
	v_pk_fma_f32 v[40:41], v[232:233], v[16:17], v[40:41]
	s_waitcnt lgkmcnt(2)
; #define SOLVE_LD(i_) do { _Pragma("unroll") for (int a4 = 0; a4 < ((i_) + 15) / 16; ++a4) lq[(i_) % 3][a4] = *(const LAS f32x4*)(LP + (i_) * 64 + 4 * a4); } while (0)
; __device__ __forceinline__ void gdn_prep_phase(LAS unsigned char* lds, const GdnPrepArgs& A, int bid, int G, const unsigned char* zero_page) {
;     ...
;         for (int i = 0; i < 64; ++i) {
;             if (i + 2 < 48) SOLVE_LD(i + 2);
;             else if (i + 1 >= 48 && i + 1 < 64) SOLVE_LD(i + 1);
;             float p0 = 0.f, p1 = 0.f;
; #pragma unroll
;             for (int a4 = 0; a4 < (i + 15) / 16; ++a4) { const f32x4 lv = lq[i % 3][a4];
;                 p0 = __builtin_fmaf(lv.x, t[4 * a4], p0); p1 = __builtin_fmaf(lv.y, t[4 * a4 + 1], p1); p0 = __builtin_fmaf(lv.z, t[4 * a4 + 2], p0); p1 = __builtin_fmaf(lv.w, t[4 * a4 + 3], p1); }
;             float p = quad_sum(p0 + p1);
;             const float ti = (i == j ? 1.f : 0.f) - p;
;             if (q == (i & 3)) t[i >> 2] = ti;
;             if ((i & 7) == 3 && !(pflg & 64)) {
;                 constexpr int kk = 0; const int k8 = i >> 3, b = w + 8 * (k8 & 1); v4u f; int off; (void)kk;
;                 if (k8 < 2)      { f = frag16_rm(lds + L_KN, QS_, b >> 2, b & 3, lane); off = B_KA + b * 1024; }
;                 else if (k8 < 4) { f = frag16_rm(lds + L_QN, QS_, b >> 2, b & 3, lane); off = B_QA + b * 1024; }
;                 else if (k8 < 6) { f = frag16_tr(lds + L_KN, QS_, b >> 1, b & 1, lane); off = B_KT + b * 1024; }
;                 else             { f = frag16_rm(lds + (k8 == 6 ? L_AF : L_AB), AS_, w >> 1, w & 1, lane); off = (k8 == 6 ? B_AF : B_AB) + w * 1024; }
;                 *(v4u*)(blob + off + lane * 16) = f; }
;             __builtin_amdgcn_sched_barrier(0);
;         }
	v_pk_fma_f32 v[40:41], v[234:235], v[32:33], v[40:41]
	s_nop 0
	v_pk_fma_f32 v[40:41], v[236:237], v[34:35], v[40:41]
	s_nop 0
	v_add_f32_e32 v35, v40, v41
	ds_read_b64 v[40:41], v187
	ds_read_b64 v[42:43], v188
	v_add_f32_dpp v35, v35, v35 quad_perm:[1,0,3,2] row_mask:0xf bank_mask:0xf bound_ctrl:1
	s_waitcnt lgkmcnt(0)
	global_store_dwordx4 v[8:9], v[40:43], off offset:2048
	v_add_f32_dpp v35, v35, v35 quad_perm:[2,3,0,1] row_mask:0xf bank_mask:0xf bound_ctrl:1
	v_sub_f32_e32 v35, v180, v35
	v_cndmask_b32_e64 v34, v34, v35, s[92:93]
	ds_read_b128 v[230:233], v56 offset:15648
	ds_read_b128 v[234:237], v56 offset:15664
	v_mov_b32_e32 v35, v131
	s_nop 0
	s_nop 0
	v_pk_fma_f32 v[8:9], v[242:243], v[14:15], 0 op_sel_hi:[1,1,0]
	s_nop 0
	v_pk_fma_f32 v[8:9], v[244:245], v[16:17], v[8:9]
	s_nop 0
	v_pk_fma_f32 v[8:9], v[246:247], v[32:33], v[8:9]
	s_nop 0
	v_pk_fma_f32 v[8:9], v[248:249], v[34:35], v[8:9]
	s_nop 0
	v_add_f32_e32 v8, v8, v9
	s_nop 1
	v_add_f32_dpp v8, v8, v8 quad_perm:[1,0,3,2] row_mask:0xf bank_mask:0xf bound_ctrl:1
	s_nop 1
	v_add_f32_dpp v8, v8, v8 quad_perm:[2,3,0,1] row_mask:0xf bank_mask:0xf bound_ctrl:1
	v_sub_f32_e32 v8, v181, v8
	v_cndmask_b32_e64 v35, 0, v8, s[86:87]
	ds_read_b128 v[242:245], v56 offset:15904
	ds_read_b128 v[246:249], v56 offset:15920
	s_nop 0
	s_waitcnt lgkmcnt(3)
	v_pk_fma_f32 v[8:9], v[230:231], v[14:15], 0 op_sel_hi:[1,1,0]
	s_nop 0
	v_pk_fma_f32 v[8:9], v[232:233], v[16:17], v[8:9]
	s_waitcnt lgkmcnt(2)
	v_pk_fma_f32 v[8:9], v[234:235], v[32:33], v[8:9]
	s_nop 0
	v_pk_fma_f32 v[8:9], v[236:237], v[34:35], v[8:9]
	s_nop 0
	v_add_f32_e32 v8, v8, v9
	s_nop 1
	v_add_f32_dpp v8, v8, v8 quad_perm:[1,0,3,2] row_mask:0xf bank_mask:0xf bound_ctrl:1
	s_nop 1
	v_add_f32_dpp v8, v8, v8 quad_perm:[2,3,0,1] row_mask:0xf bank_mask:0xf bound_ctrl:1
	v_sub_f32_e32 v8, v182, v8
	v_cndmask_b32_e64 v35, v35, v8, s[88:89]
	ds_read_b128 v[230:233], v56 offset:16160
	ds_read_b128 v[234:237], v56 offset:16176
	s_nop 0
	s_waitcnt lgkmcnt(3)
	v_pk_fma_f32 v[8:9], v[242:243], v[14:15], 0 op_sel_hi:[1,1,0]
	s_nop 0
	v_pk_fma_f32 v[8:9], v[244:245], v[16:17], v[8:9]
	s_waitcnt lgkmcnt(2)
	v_pk_fma_f32 v[8:9], v[246:247], v[32:33], v[8:9]
	s_nop 0
	v_pk_fma_f32 v[8:9], v[248:249], v[34:35], v[8:9]
	s_nop 0
	v_add_f32_e32 v8, v8, v9
	s_nop 1
	v_add_f32_dpp v8, v8, v8 quad_perm:[1,0,3,2] row_mask:0xf bank_mask:0xf bound_ctrl:1
	s_nop 1
	v_add_f32_dpp v8, v8, v8 quad_perm:[2,3,0,1] row_mask:0xf bank_mask:0xf bound_ctrl:1
	v_sub_f32_e32 v8, v183, v8
	v_cndmask_b32_e64 v35, v35, v8, s[90:91]
	s_nop 0
	s_nop 0
	s_waitcnt lgkmcnt(1)
	v_pk_fma_f32 v[8:9], v[230:231], v[14:15], 0 op_sel_hi:[1,1,0]
	s_nop 0
	v_pk_fma_f32 v[8:9], v[232:233], v[16:17], v[8:9]
	s_waitcnt lgkmcnt(0)
	v_pk_fma_f32 v[8:9], v[234:235], v[32:33], v[8:9]
	s_nop 0
	v_pk_fma_f32 v[8:9], v[236:237], v[34:35], v[8:9]
	s_nop 0
	v_add_f32_e32 v2, v8, v9
	s_nop 1
	v_add_f32_dpp v2, v2, v2 quad_perm:[1,0,3,2] row_mask:0xf bank_mask:0xf bound_ctrl:1
	s_nop 1
	v_add_f32_dpp v2, v2, v2 quad_perm:[2,3,0,1] row_mask:0xf bank_mask:0xf bound_ctrl:1
	v_sub_f32_e32 v2, v184, v2
	v_cndmask_b32_e64 v2, v35, v2, s[92:93]
	s_branch .Ls4join
.Ls4v3:
	v_lshl_add_u64 v[6:7], s[40:41], 0, v[22:23]
	s_nop 0
	s_nop 0
	s_nop 1
	s_nop 1
	s_nop 0
	s_nop 1
	s_nop 1
	v_readlane_b32 s2, v255, 48
	v_add_u32_e32 v9, v63, v108
	ds_read2_b64 v[10:13], v9 offset1:4
	v_readlane_b32 s3, v255, 49
	s_nop 0
	v_lshl_add_u64 v[8:9], v[6:7], 0, s[2:3]
	s_waitcnt lgkmcnt(0)
	global_store_dwordx4 v[8:9], v[10:13], off
	s_nop 0
	s_nop 1
	s_nop 1
	s_nop 0
	s_nop 1
	s_nop 1
	s_nop 0
	s_nop 1
	s_nop 1
	s_nop 0
	s_nop 1
	s_nop 1
	s_nop 0
	s_nop 1
	s_nop 1
	v_mov_b32_e32 v5, v131
	s_nop 1
	s_nop 1
	v_mov_b32_e32 v5, v131
	s_nop 1
	s_nop 1
	v_mov_b32_e32 v5, v131
	v_add_u32_e32 v14, v63, v117
	ds_read2_b64 v[14:17], v14 offset1:4
	v_lshl_add_u64 v[32:33], v[6:7], 0, s[38:39]
	s_waitcnt lgkmcnt(0)
	global_store_dwordx4 v[32:33], v[14:17], off
	v_mov_b32_e32 v5, v131
	s_nop 1
	s_nop 1
	s_nop 0
	s_nop 1
	s_nop 1
	s_nop 0
	s_nop 1
	s_nop 1
	s_nop 0
	s_nop 1
	s_nop 1
	s_nop 0
	s_nop 1
	s_nop 1
	v_mov_b32_e32 v231, v131
	s_nop 0
	s_nop 0
	s_nop 1
	s_nop 1
	s_nop 0
	s_nop 0
	s_nop 1
	s_nop 1
	v_mov_b32_e32 v11, v131
	s_movk_i32 s40, 0x4000
	s_nop 0
	v_add_co_u32_e32 v12, vcc, s40, v8
	s_nop 0
	v_addc_co_u32_e32 v13, vcc, 0, v9, vcc
	s_nop 0
	v_add_u32_e32 v11, v62, v108
	v_add_u32_e32 v11, 0xc800, v11
	ds_read2_b64 v[34:37], v11 offset0:128 offset1:132
	s_waitcnt lgkmcnt(0)
	global_store_dwordx4 v[12:13], v[34:37], off
	v_mov_b32_e32 v11, v131
	s_nop 0
	s_nop 0
	s_nop 1
	s_nop 1
	s_nop 0
	s_nop 0
	s_nop 0
	s_nop 1
	s_nop 1
	s_nop 0
	s_nop 0
	s_nop 1
	s_nop 1
	s_nop 0
	s_nop 0
	s_nop 1
	s_nop 1
	s_nop 0
	s_nop 0
	s_nop 1
	s_nop 1
	v_mov_b32_e32 v17, v131
	s_nop 0
	s_nop 0
	s_nop 1
	s_nop 1
	v_mov_b32_e32 v17, v131
	s_nop 0
	s_nop 0
	s_nop 1
	s_nop 1
	v_mov_b32_e32 v13, v131
	v_add_co_u32_e32 v230, vcc, s40, v32
	s_nop 0
	v_addc_co_u32_e32 v231, vcc, 0, v33, vcc
	s_nop 1
	s_nop 1
	v_add_u32_e32 v13, v62, v117
	v_add_u32_e32 v13, 0xc800, v13
	ds_read2_b64 v[42:45], v13 offset0:128 offset1:132
	s_waitcnt lgkmcnt(0)
	global_store_dwordx4 v[230:231], v[42:45], off
	v_mov_b32_e32 v13, v131
	s_nop 0
	s_nop 0
	s_nop 1
	s_nop 1
	s_nop 0
	s_nop 0
	s_nop 0
	s_nop 1
	s_nop 1
	s_nop 0
	s_nop 0
	s_nop 1
	s_nop 1
	s_nop 0
	s_nop 0
	s_nop 1
	s_nop 1
	s_nop 0
	s_nop 0
	s_nop 1
	s_nop 1
	v_mov_b32_e32 v247, v131
	s_nop 0
	s_nop 0
	s_nop 0
	s_nop 1
	s_nop 1
	s_nop 0
	s_nop 0
	s_nop 0
	s_nop 1
	s_nop 1
	v_mov_b32_e32 v239, v131
	s_mov_b32 s40, 0x8000
	s_nop 0
	s_nop 0
	v_add_u32_e32 v15, s71, v61
	ds_read_u16 v16, v15 offset:816
	ds_read_u16 v17, v15 offset:4352
	ds_read_u16 v239, v15 offset:4624
	ds_read_u16 v240, v15 offset:4896
	ds_read_u16 v241, v15 offset:5168
	ds_read_u16 v242, v15
	ds_read_u16 v243, v15 offset:272
	ds_read_u16 v15, v15 offset:544
	s_waitcnt lgkmcnt(3)
; #define SOLVE_LD(i_) do { _Pragma("unroll") for (int a4 = 0; a4 < ((i_) + 15) / 16; ++a4) lq[(i_) % 3][a4] = *(const LAS f32x4*)(LP + (i_) * 64 + 4 * a4); } while (0)
; __device__ __forceinline__ void gdn_prep_phase(LAS unsigned char* lds, const GdnPrepArgs& A, int bid, int G, const unsigned char* zero_page) {
;     ...
;         for (int i = 0; i < 64; ++i) {
;             if (i + 2 < 48) SOLVE_LD(i + 2);
;             else if (i + 1 >= 48 && i + 1 < 64) SOLVE_LD(i + 1);
;             float p0 = 0.f, p1 = 0.f;
; #pragma unroll
;             for (int a4 = 0; a4 < (i + 15) / 16; ++a4) { const f32x4 lv = lq[i % 3][a4];
;                 p0 = __builtin_fmaf(lv.x, t[4 * a4], p0); p1 = __builtin_fmaf(lv.y, t[4 * a4 + 1], p1); p0 = __builtin_fmaf(lv.z, t[4 * a4 + 2], p0); p1 = __builtin_fmaf(lv.w, t[4 * a4 + 3], p1); }
;             float p = quad_sum(p0 + p1);
;             const float ti = (i == j ? 1.f : 0.f) - p;
;             if (q == (i & 3)) t[i >> 2] = ti;
;             if ((i & 7) == 3 && !(pflg & 64)) {
;                 constexpr int kk = 0; const int k8 = i >> 3, b = w + 8 * (k8 & 1); v4u f; int off; (void)kk;
;                 if (k8 < 2)      { f = frag16_rm(lds + L_KN, QS_, b >> 2, b & 3, lane); off = B_KA + b * 1024; }
;                 else if (k8 < 4) { f = frag16_rm(lds + L_QN, QS_, b >> 2, b & 3, lane); off = B_QA + b * 1024; }
;                 else if (k8 < 6) { f = frag16_tr(lds + L_KN, QS_, b >> 1, b & 1, lane); off = B_KT + b * 1024; }
;                 else             { f = frag16_rm(lds + (k8 == 6 ? L_AF : L_AB), AS_, w >> 1, w & 1, lane); off = (k8 == 6 ? B_AF : B_AB) + w * 1024; }
;                 *(v4u*)(blob + off + lane * 16) = f; }
;             __builtin_amdgcn_sched_barrier(0);
;         }
	v_perm_b32 v241, v241, v240, s33
	v_perm_b32 v240, v239, v17, s33
	s_waitcnt lgkmcnt(0)
	v_perm_b32 v239, v16, v15, s33
	v_add_co_u32_e32 v16, vcc, s40, v8
	v_perm_b32 v238, v243, v242, s33
	v_addc_co_u32_e32 v17, vcc, 0, v9, vcc
	global_store_dwordx4 v[16:17], v[238:241], off offset:2048
	v_mov_b32_e32 v15, v131
	s_nop 0
	s_nop 0
	s_nop 0
	s_nop 0
	s_nop 1
	s_nop 1
	s_nop 0
	s_nop 0
	s_nop 0
	s_nop 0
	s_nop 0
	s_nop 1
	s_nop 1
	s_nop 0
	s_nop 0
	s_nop 0
	s_nop 1
	s_nop 1
	s_nop 0
	s_nop 0
	s_nop 0
	s_nop 1
	s_nop 1
	s_nop 0
	s_nop 0
	s_nop 0
	s_nop 1
	s_nop 1
	v_mov_b32_e32 v17, v131
	s_nop 0
	s_nop 0
	s_nop 0
	s_nop 1
	s_nop 1
	v_mov_b32_e32 v17, v131
	s_nop 0
	s_nop 0
	s_nop 0
	s_nop 1
	s_nop 1
	v_mov_b32_e32 v17, v131
	v_add_u32_e32 v38, s72, v61
	v_add_co_u32_e32 v32, vcc, s40, v32
	v_addc_co_u32_e32 v33, vcc, 0, v33, vcc
	s_nop 0
	ds_read_u16 v39, v38 offset:816
	ds_read_u16 v40, v38 offset:4352
	ds_read_u16 v46, v38 offset:4624
	ds_read_u16 v41, v38 offset:4896
	ds_read_u16 v47, v38 offset:5168
	ds_read_u16 v48, v38
	ds_read_u16 v49, v38 offset:272
	ds_read_u16 v38, v38 offset:544
	s_waitcnt lgkmcnt(3)
	v_perm_b32 v41, v47, v41, s33
	v_perm_b32 v40, v46, v40, s33
	s_waitcnt lgkmcnt(0)
	v_perm_b32 v39, v39, v38, s33
	v_perm_b32 v38, v49, v48, s33
	global_store_dwordx4 v[32:33], v[38:41], off offset:2048
	v_mov_b32_e32 v17, v131
	s_nop 0
	s_nop 0
	s_nop 0
	s_nop 0
	s_nop 1
	s_nop 1
	s_nop 0
	s_nop 0
	s_nop 0
	s_nop 0
	s_nop 0
	s_nop 1
	s_nop 1
	s_nop 0
	s_nop 0
	s_nop 0
	s_nop 0
	s_nop 1
	s_nop 1
	s_nop 0
	s_nop 0
	s_nop 0
	s_nop 1
	s_nop 1
	v_mov_b32_e32 v130, 0
	v_mov_b32_e32 v3, 0
	v_mov_b32_e32 v2, 0
	v_mov_b32_e32 v4, 0
	v_mov_b32_e32 v5, 0
	v_mov_b32_e32 v10, 0
	v_mov_b32_e32 v11, 0
	v_mov_b32_e32 v12, 0
	v_mov_b32_e32 v13, 0
	v_mov_b32_e32 v14, 0
	v_mov_b32_e32 v15, 0
	v_mov_b32_e32 v16, 0
	v_mov_b32_e32 v17, 0
	ds_read_b128 v[238:241], v56 offset:12592
	s_nop 0
	s_nop 0
	s_nop 0
	v_mov_b32_e32 v32, 0
	s_nop 1
	v_add_f32_dpp v32, v32, v32 quad_perm:[1,0,3,2] row_mask:0xf bank_mask:0xf bound_ctrl:1
	s_nop 1
	v_add_f32_dpp v32, v32, v32 quad_perm:[2,3,0,1] row_mask:0xf bank_mask:0xf bound_ctrl:1
	v_sub_f32_e32 v32, v160, v32
	v_cndmask_b32_e64 v48, 0, v32, s[86:87]
	ds_read_b128 v[242:245], v56 offset:12848
	v_mov_b32_e32 v49, v131
	s_nop 0
	s_nop 0
	s_waitcnt lgkmcnt(1)
	v_pk_fma_f32 v[44:45], v[238:239], v[48:49], 0 op_sel_hi:[1,1,0]
	s_nop 0
	v_pk_fma_f32 v[44:45], v[240:241], 0, v[44:45] op_sel_hi:[1,0,1]
	s_nop 0
	v_add_f32_e32 v44, v44, v45
	s_nop 1
	v_add_f32_dpp v44, v44, v44 quad_perm:[1,0,3,2] row_mask:0xf bank_mask:0xf bound_ctrl:1
	s_nop 1
	v_add_f32_dpp v44, v44, v44 quad_perm:[2,3,0,1] row_mask:0xf bank_mask:0xf bound_ctrl:1
	v_sub_f32_e32 v44, v161, v44
	v_cndmask_b32_e64 v48, v48, v44, s[88:89]
	ds_read_b128 v[238:241], v56 offset:13104
	s_nop 0
	s_nop 0
	s_waitcnt lgkmcnt(1)
	v_pk_fma_f32 v[32:33], v[242:243], v[48:49], 0 op_sel_hi:[1,1,0]
	s_nop 0
	v_pk_fma_f32 v[32:33], v[244:245], 0, v[32:33] op_sel_hi:[1,0,1]
	s_nop 0
	v_add_f32_e32 v32, v32, v33
	s_nop 1
	v_add_f32_dpp v32, v32, v32 quad_perm:[1,0,3,2] row_mask:0xf bank_mask:0xf bound_ctrl:1
	s_nop 1
	v_add_f32_dpp v32, v32, v32 quad_perm:[2,3,0,1] row_mask:0xf bank_mask:0xf bound_ctrl:1
	v_sub_f32_e32 v32, v162, v32
	v_cndmask_b32_e64 v32, v48, v32, s[90:91]
	v_mov_b32_e32 v33, v131
	ds_read_b128 v[246:249], v56 offset:13360
	s_mov_b32 s40, 0xe000
	v_add_co_u32_e32 v46, vcc, s40, v8
	v_addc_co_u32_e32 v47, vcc, 0, v9, vcc
	s_waitcnt lgkmcnt(1)
	v_pk_fma_f32 v[42:43], v[238:239], v[32:33], 0 op_sel_hi:[1,1,0]
	s_nop 0
	v_pk_fma_f32 v[42:43], v[240:241], 0, v[42:43] op_sel_hi:[1,0,1]
	s_nop 0
	v_add_f32_e32 v33, v42, v43
	ds_read_b64 v[42:43], v185
	ds_read_b64 v[44:45], v186
	v_add_f32_dpp v33, v33, v33 quad_perm:[1,0,3,2] row_mask:0xf bank_mask:0xf bound_ctrl:1
	s_waitcnt lgkmcnt(0)
	global_store_dwordx4 v[46:47], v[42:45], off offset:2048
	v_add_f32_dpp v33, v33, v33 quad_perm:[2,3,0,1] row_mask:0xf bank_mask:0xf bound_ctrl:1
	v_sub_f32_e32 v33, v163, v33
	v_cndmask_b32_e64 v32, v32, v33, s[92:93]
	v_mov_b32_e32 v33, v131
	ds_read_b128 v[234:237], v56 offset:13616
	s_nop 0
	s_nop 0
	s_nop 0
	s_nop 0
	v_pk_fma_f32 v[34:35], v[246:247], v[32:33], 0 op_sel_hi:[1,1,0]
	s_nop 0
	v_pk_fma_f32 v[34:35], v[248:249], 0, v[34:35] op_sel_hi:[1,0,1]
	s_nop 0
	v_add_f32_e32 v33, v34, v35
	s_nop 1
	v_add_f32_dpp v33, v33, v33 quad_perm:[1,0,3,2] row_mask:0xf bank_mask:0xf bound_ctrl:1
	s_nop 1
	v_add_f32_dpp v33, v33, v33 quad_perm:[2,3,0,1] row_mask:0xf bank_mask:0xf bound_ctrl:1
	v_sub_f32_e32 v33, v173, v33
	v_cndmask_b32_e64 v33, 0, v33, s[86:87]
	ds_read_b128 v[242:245], v56 offset:13872
	s_nop 0
	s_nop 0
	s_waitcnt lgkmcnt(1)
	v_pk_fma_f32 v[42:43], v[234:235], v[32:33], 0 op_sel_hi:[1,1,0]
	s_nop 0
	v_pk_fma_f32 v[42:43], v[236:237], 0, v[42:43] op_sel_hi:[1,0,1]
	s_nop 0
	v_add_f32_e32 v42, v42, v43
	s_nop 1
	v_add_f32_dpp v42, v42, v42 quad_perm:[1,0,3,2] row_mask:0xf bank_mask:0xf bound_ctrl:1
	s_nop 1
	v_add_f32_dpp v42, v42, v42 quad_perm:[2,3,0,1] row_mask:0xf bank_mask:0xf bound_ctrl:1
	v_sub_f32_e32 v42, v174, v42
	v_cndmask_b32_e64 v33, v33, v42, s[88:89]
	ds_read_b128 v[234:237], v56 offset:14128
	s_nop 0
	s_nop 0
	s_waitcnt lgkmcnt(1)
	v_pk_fma_f32 v[34:35], v[242:243], v[32:33], 0 op_sel_hi:[1,1,0]
	s_nop 0
	v_pk_fma_f32 v[34:35], v[244:245], 0, v[34:35] op_sel_hi:[1,0,1]
	s_nop 0
	v_add_f32_e32 v34, v34, v35
	s_nop 1
	v_add_f32_dpp v34, v34, v34 quad_perm:[1,0,3,2] row_mask:0xf bank_mask:0xf bound_ctrl:1
	s_nop 1
	v_add_f32_dpp v34, v34, v34 quad_perm:[2,3,0,1] row_mask:0xf bank_mask:0xf bound_ctrl:1
	v_sub_f32_e32 v34, v175, v34
	v_cndmask_b32_e64 v33, v33, v34, s[90:91]
	ds_read_b128 v[242:245], v56 offset:14384
	s_nop 0
	s_nop 0
	s_waitcnt lgkmcnt(1)
; #define LAS __attribute__((address_space(3)))
; __device__ __forceinline__ unsigned pkbf(float a, float b) { bf16x2_t v = __builtin_convertvector((f32x2_t){a, b}, bf16x2_t); return __builtin_bit_cast(unsigned, v); }
; __device__ __forceinline__ void gdn_prep_phase(LAS unsigned char* lds, const GdnPrepArgs& A, int bid, int G, const unsigned char* zero_page) {
;     ...
;         for (int i = 0; i < 64; ++i) {
;             if (i + 2 < 48) SOLVE_LD(i + 2);
;             else if (i + 1 >= 48 && i + 1 < 64) SOLVE_LD(i + 1);
;             float p0 = 0.f, p1 = 0.f;
; #pragma unroll
;             for (int a4 = 0; a4 < (i + 15) / 16; ++a4) { const f32x4 lv = lq[i % 3][a4];
;                 p0 = __builtin_fmaf(lv.x, t[4 * a4], p0); p1 = __builtin_fmaf(lv.y, t[4 * a4 + 1], p1); p0 = __builtin_fmaf(lv.z, t[4 * a4 + 2], p0); p1 = __builtin_fmaf(lv.w, t[4 * a4 + 3], p1); }
;             float p = quad_sum(p0 + p1);
;             const float ti = (i == j ? 1.f : 0.f) - p;
;             if (q == (i & 3)) t[i >> 2] = ti;
;             if ((i & 7) == 3 && !(pflg & 64)) {
;                 constexpr int kk = 0; const int k8 = i >> 3, b = w + 8 * (k8 & 1); v4u f; int off; (void)kk;
;                 if (k8 < 2)      { f = frag16_rm(lds + L_KN, QS_, b >> 2, b & 3, lane); off = B_KA + b * 1024; }
;                 else if (k8 < 4) { f = frag16_rm(lds + L_QN, QS_, b >> 2, b & 3, lane); off = B_QA + b * 1024; }
;                 else if (k8 < 6) { f = frag16_tr(lds + L_KN, QS_, b >> 1, b & 1, lane); off = B_KT + b * 1024; }
;                 else             { f = frag16_rm(lds + (k8 == 6 ? L_AF : L_AB), AS_, w >> 1, w & 1, lane); off = (k8 == 6 ? B_AF : B_AB) + w * 1024; }
;                 *(v4u*)(blob + off + lane * 16) = f; }
;             __builtin_amdgcn_sched_barrier(0);
;         }
;     ...
;         const LAS float* sc = (const LAS float*)(lds + L_SC);
;         if (dir == 0) { const float bj = sc[128 + j];
; #pragma unroll
;             for (int a = 0; a < 16; ++a) *(LAS unsigned short*)(lds + L_TBF + (4 * a + q) * AS_ + j * 2) = (unsigned short)(pkbf(t[a] * bj, 0.f) & 0xffffu);
;         } else { const int jo = 63 - j; const float bj = sc[192 + jo];
; #pragma unroll
;             for (int a = 0; a < 16; ++a) *(LAS unsigned short*)(lds + L_TBB + (63 - (4 * a + q)) * AS_ + jo * 2) = (unsigned short)(pkbf(t[a] * bj, 0.f) & 0xffffu);
;         }
	v_pk_fma_f32 v[42:43], v[234:235], v[32:33], 0 op_sel_hi:[1,1,0]
	s_nop 0
	v_pk_fma_f32 v[42:43], v[236:237], 0, v[42:43] op_sel_hi:[1,0,1]
	s_nop 0
	v_add_f32_e32 v42, v42, v43
	s_nop 1
	v_add_f32_dpp v42, v42, v42 quad_perm:[1,0,3,2] row_mask:0xf bank_mask:0xf bound_ctrl:1
	s_nop 1
	v_add_f32_dpp v42, v42, v42 quad_perm:[2,3,0,1] row_mask:0xf bank_mask:0xf bound_ctrl:1
	v_sub_f32_e32 v42, v176, v42
	v_cndmask_b32_e64 v33, v33, v42, s[92:93]
	ds_read_b128 v[234:237], v56 offset:14640
	s_nop 0
	s_nop 0
	s_waitcnt lgkmcnt(1)
	v_pk_fma_f32 v[34:35], v[242:243], v[32:33], 0 op_sel_hi:[1,1,0]
	s_nop 0
	v_pk_fma_f32 v[34:35], v[244:245], 0, v[34:35] op_sel_hi:[1,0,1]
	s_nop 0
	v_add_f32_e32 v34, v34, v35
	s_nop 1
	v_add_f32_dpp v34, v34, v34 quad_perm:[1,0,3,2] row_mask:0xf bank_mask:0xf bound_ctrl:1
	s_nop 1
	v_add_f32_dpp v34, v34, v34 quad_perm:[2,3,0,1] row_mask:0xf bank_mask:0xf bound_ctrl:1
	v_sub_f32_e32 v34, v177, v34
	v_cndmask_b32_e64 v246, 0, v34, s[86:87]
	ds_read_b128 v[242:245], v56 offset:14896
	v_mov_b32_e32 v247, v131
	s_nop 0
	s_nop 0
	s_waitcnt lgkmcnt(1)
	v_pk_fma_f32 v[42:43], v[234:235], v[32:33], 0 op_sel_hi:[1,1,0]
	s_nop 0
	v_pk_fma_f32 v[42:43], v[236:237], v[246:247], v[42:43]
	s_nop 0
	v_add_f32_e32 v42, v42, v43
	s_nop 1
	v_add_f32_dpp v42, v42, v42 quad_perm:[1,0,3,2] row_mask:0xf bank_mask:0xf bound_ctrl:1
	s_nop 1
	v_add_f32_dpp v42, v42, v42 quad_perm:[2,3,0,1] row_mask:0xf bank_mask:0xf bound_ctrl:1
	v_sub_f32_e32 v42, v178, v42
	v_cndmask_b32_e64 v246, v246, v42, s[88:89]
	ds_read_b128 v[234:237], v56 offset:15152
	s_nop 0
	s_nop 0
	s_waitcnt lgkmcnt(1)
	v_pk_fma_f32 v[34:35], v[242:243], v[32:33], 0 op_sel_hi:[1,1,0]
	s_nop 0
	v_pk_fma_f32 v[34:35], v[244:245], v[246:247], v[34:35]
	s_nop 0
	v_add_f32_e32 v34, v34, v35
	s_nop 1
	v_add_f32_dpp v34, v34, v34 quad_perm:[1,0,3,2] row_mask:0xf bank_mask:0xf bound_ctrl:1
	s_nop 1
	v_add_f32_dpp v34, v34, v34 quad_perm:[2,3,0,1] row_mask:0xf bank_mask:0xf bound_ctrl:1
	v_sub_f32_e32 v34, v179, v34
	v_cndmask_b32_e64 v34, v246, v34, s[90:91]
	ds_read_b128 v[246:249], v56 offset:15408
	v_mov_b32_e32 v35, v131
	s_mov_b32 s40, 0x12000
	v_add_co_u32_e32 v8, vcc, s40, v8
	v_addc_co_u32_e32 v9, vcc, 0, v9, vcc
	s_waitcnt lgkmcnt(1)
	v_pk_fma_f32 v[40:41], v[234:235], v[32:33], 0 op_sel_hi:[1,1,0]
	s_nop 0
	v_pk_fma_f32 v[40:41], v[236:237], v[34:35], v[40:41]
	s_nop 0
	v_add_f32_e32 v35, v40, v41
	ds_read_b64 v[40:41], v187
	ds_read_b64 v[42:43], v188
	v_add_f32_dpp v35, v35, v35 quad_perm:[1,0,3,2] row_mask:0xf bank_mask:0xf bound_ctrl:1
	s_waitcnt lgkmcnt(0)
	global_store_dwordx4 v[8:9], v[40:43], off offset:2048
	v_add_f32_dpp v35, v35, v35 quad_perm:[2,3,0,1] row_mask:0xf bank_mask:0xf bound_ctrl:1
	v_sub_f32_e32 v35, v180, v35
	v_cndmask_b32_e64 v34, v34, v35, s[92:93]
	ds_read_b128 v[234:237], v56 offset:15664
	v_mov_b32_e32 v35, v131
	s_nop 0
	s_nop 0
	s_nop 0
	s_nop 0
	v_pk_fma_f32 v[8:9], v[246:247], v[32:33], 0 op_sel_hi:[1,1,0]
	s_nop 0
	v_pk_fma_f32 v[8:9], v[248:249], v[34:35], v[8:9]
	s_nop 0
	v_add_f32_e32 v8, v8, v9
	s_nop 1
	v_add_f32_dpp v8, v8, v8 quad_perm:[1,0,3,2] row_mask:0xf bank_mask:0xf bound_ctrl:1
	s_nop 1
	v_add_f32_dpp v8, v8, v8 quad_perm:[2,3,0,1] row_mask:0xf bank_mask:0xf bound_ctrl:1
	v_sub_f32_e32 v8, v181, v8
	v_cndmask_b32_e64 v35, 0, v8, s[86:87]
	ds_read_b128 v[246:249], v56 offset:15920
	s_nop 0
	s_nop 0
	s_waitcnt lgkmcnt(1)
	v_pk_fma_f32 v[8:9], v[234:235], v[32:33], 0 op_sel_hi:[1,1,0]
	s_nop 0
	v_pk_fma_f32 v[8:9], v[236:237], v[34:35], v[8:9]
	s_nop 0
	v_add_f32_e32 v8, v8, v9
	s_nop 1
	v_add_f32_dpp v8, v8, v8 quad_perm:[1,0,3,2] row_mask:0xf bank_mask:0xf bound_ctrl:1
	s_nop 1
	v_add_f32_dpp v8, v8, v8 quad_perm:[2,3,0,1] row_mask:0xf bank_mask:0xf bound_ctrl:1
	v_sub_f32_e32 v8, v182, v8
	v_cndmask_b32_e64 v35, v35, v8, s[88:89]
	ds_read_b128 v[234:237], v56 offset:16176
	s_nop 0
	s_nop 0
	s_waitcnt lgkmcnt(1)
	v_pk_fma_f32 v[8:9], v[246:247], v[32:33], 0 op_sel_hi:[1,1,0]
	s_nop 0
	v_pk_fma_f32 v[8:9], v[248:249], v[34:35], v[8:9]
	s_nop 0
	v_add_f32_e32 v8, v8, v9
	s_nop 1
	v_add_f32_dpp v8, v8, v8 quad_perm:[1,0,3,2] row_mask:0xf bank_mask:0xf bound_ctrl:1
	s_nop 1
	v_add_f32_dpp v8, v8, v8 quad_perm:[2,3,0,1] row_mask:0xf bank_mask:0xf bound_ctrl:1
	v_sub_f32_e32 v8, v183, v8
	v_cndmask_b32_e64 v35, v35, v8, s[90:91]
	s_nop 0
	s_nop 0
	s_nop 0
	s_waitcnt lgkmcnt(0)
	v_pk_fma_f32 v[8:9], v[234:235], v[32:33], 0 op_sel_hi:[1,1,0]
	s_nop 0
	v_pk_fma_f32 v[8:9], v[236:237], v[34:35], v[8:9]
	s_nop 0
	v_add_f32_e32 v2, v8, v9
	s_nop 1
	v_add_f32_dpp v2, v2, v2 quad_perm:[1,0,3,2] row_mask:0xf bank_mask:0xf bound_ctrl:1
	s_nop 1
	v_add_f32_dpp v2, v2, v2 quad_perm:[2,3,0,1] row_mask:0xf bank_mask:0xf bound_ctrl:1
	v_sub_f32_e32 v2, v184, v2
	v_cndmask_b32_e64 v2, v35, v2, s[92:93]
.Ls4join:
	s_mov_b64 s[40:41], -1
	s_and_b64 vcc, exec, s[4:5]
	s_cbranch_vccz .LBB0_339
	ds_read_b32 v8, v64
	s_mov_b64 s[40:41], 0
	s_waitcnt lgkmcnt(0)
	v_mul_f32_e32 v9, v130, v8
	v_cvt_pk_bf16_f32 v9, v9, s0
	ds_write_b16 v208, v9
	v_mul_f32_e32 v9, v3, v8
	v_cvt_pk_bf16_f32 v9, v9, s0
	ds_write_b16 v209, v9
	v_mul_f32_e32 v9, v4, v8
	v_cvt_pk_bf16_f32 v9, v9, s0
	ds_write_b16 v210, v9
	v_mul_f32_e32 v9, v5, v8
	v_cvt_pk_bf16_f32 v9, v9, s0
	ds_write_b16 v211, v9
	v_mul_f32_e32 v9, v10, v8
	v_cvt_pk_bf16_f32 v9, v9, s0
	ds_write_b16 v212, v9
	v_mul_f32_e32 v9, v11, v8
	v_cvt_pk_bf16_f32 v9, v9, s0
	ds_write_b16 v213, v9
	v_mul_f32_e32 v9, v12, v8
	v_cvt_pk_bf16_f32 v9, v9, s0
	ds_write_b16 v214, v9
	v_mul_f32_e32 v9, v13, v8
	v_cvt_pk_bf16_f32 v9, v9, s0
	ds_write_b16 v215, v9
	v_mul_f32_e32 v9, v14, v8
	v_cvt_pk_bf16_f32 v9, v9, s0
	ds_write_b16 v216, v9
	v_mul_f32_e32 v9, v15, v8
	v_cvt_pk_bf16_f32 v9, v9, s0
	ds_write_b16 v217, v9
	v_mul_f32_e32 v9, v16, v8
	v_cvt_pk_bf16_f32 v9, v9, s0
	ds_write_b16 v218, v9
	v_mul_f32_e32 v9, v17, v8
	v_cvt_pk_bf16_f32 v9, v9, s0
	ds_write_b16 v219, v9
	v_mul_f32_e32 v9, v32, v8
	v_cvt_pk_bf16_f32 v9, v9, s0
	ds_write_b16 v220, v9
	v_mul_f32_e32 v9, v33, v8
	v_cvt_pk_bf16_f32 v9, v9, s0
	ds_write_b16 v221, v9
	v_mul_f32_e32 v9, v34, v8
	v_mul_f32_e32 v8, v2, v8
	v_cvt_pk_bf16_f32 v9, v9, s0
	v_cvt_pk_bf16_f32 v8, v8, s0
	ds_write_b16 v222, v9
	ds_write_b16 v223, v8
